# qkpost: LDS shuffles replaced by DPP; the 16 second-round quads spread over wave 0 of 16 CUs
# speedup vs baseline: 1.0338x; 1.0093x over previous
; __device__ __forceinline__ void phase_qkpost(Frame& F, const Params& p, int j) {
;     ...
;     for (int quad = gw; quad < MVALID / 4; quad += NGW) {
;         const int row0 = quad * 4;
;         int b, pos0, kind;
;         if (row0 < MMAIN) { b = row0 >> 12; pos0 = (row0 & 4095) + 16; kind = 0; }
;         else if (row0 < ROW_META) { b = row0 - ROW_SAMPLE; pos0 = PASTLEN; kind = 1; }
;         else { b = (row0 - ROW_META) >> 4; pos0 = (row0 - ROW_META) & 15; kind = 0; }
.LBB0_824:
	s_cmpk_lg_i32 s39, 0x800
	s_cbranch_scc1 .Lqk_orig
	s_cmpk_gt_i32 s38, 0x7ff
	s_cbranch_scc1 .LBB0_1240
	s_and_b32 vcc_lo, s38, 7
	s_cmp_lg_u32 vcc_lo, 0
	s_cbranch_scc1 .LBB0_1240
	s_lshr_b32 vcc_lo, s38, 3
	s_cmpk_gt_u32 vcc_lo, 15
	s_cbranch_scc1 .LBB0_1240
	s_add_i32 s38, vcc_lo, 0x800
	s_lshl_b32 s10, s38, 2
	s_branch .LBB0_825

; __device__ __forceinline__ void phase_qkpost(Frame& F, const Params& p, int j) {
;     ...
;         for (int r = 0; r < 4; ++r) { const u32x2* src = (const u32x2*)((const bf16_t*)F.QKV + (size_t)(row0 + r) * NQKV) + lane;
; #pragma unroll
;             for (int c = 0; c < 10; ++c) xr[r][c] = src[64 * c]; }
;         __builtin_amdgcn_sched_barrier(0);
; #pragma unroll
;         for (int r = 0; r < 4; ++r) {
;             const int row = row0 + r, pos = kind ? PASTLEN : pos0 + r;
;             f32x4 x[10];
; #pragma unroll
;             for (int c = 0; c < 10; ++c) x[c] = (f32x4){__uint_as_float(xr[r][c].x << 16), __uint_as_float(xr[r][c].x & 0xffff0000u), __uint_as_float(xr[r][c].y << 16), __uint_as_float(xr[r][c].y & 0xffff0000u)};
;             f32x4 cs, sn;
; #pragma unroll
;             for (int e = 0; e < 4; ++e) { const float ang = (float)pos * inv[e]; const double tr = (double)ang * 0.15915494309189535; const float rv = (float)(tr - __builtin_rint(tr));
;                 cs[e] = __builtin_amdgcn_cosf(rv); sn[e] = __builtin_amdgcn_sinf(rv); }
; #pragma unroll
;             for (int c = 0; c < 9; ++c) {
;                 f32x4 v = x[c];
;                 float ss = (v.x * v.x + v.y * v.y) + (v.z * v.z + v.w * v.w);
;                 ss += __shfl_xor(ss, 1); ss += __shfl_xor(ss, 2); ss += __shfl_xor(ss, 4); ss += __shfl_xor(ss, 8);
;                 v = v * (1.0f / sqrtf(ss * (1.0f / 64.0f) + EPS)) * (c < 8 ? qg : kg);
;                 f32x4 pr; pr.x = __shfl_xor(v.x, 2); pr.y = __shfl_xor(v.y, 2); pr.z = __shfl_xor(v.z, 2); pr.w = __shfl_xor(v.w, 2);
;                 if (li < 2) v = v * cs - pr * sn; else if (li < 4) v = v * cs + pr * sn;
.LBB0_833:
	v_mad_i64_i32 v[10:11], s[6:7], s10, v217, v[40:41]
	global_load_dwordx2 v[14:15], v[10:11], off
	global_load_dwordx2 v[114:115], v[10:11], off offset:512
	global_load_dwordx2 v[110:111], v[10:11], off offset:1024
	global_load_dwordx2 v[108:109], v[10:11], off offset:1536
	global_load_dwordx2 v[106:107], v[10:11], off offset:2048
	global_load_dwordx2 v[104:105], v[10:11], off offset:2560
	global_load_dwordx2 v[22:23], v[10:11], off offset:3072
	global_load_dwordx2 v[20:21], v[10:11], off offset:3584
	v_add_co_u32_e32 v10, vcc, 0x1000, v10
	s_add_i32 s24, s10, 1
	s_nop 0
	v_addc_co_u32_e32 v11, vcc, 0, v11, vcc
	v_mad_i64_i32 v[12:13], s[6:7], s24, v217, v[40:41]
	global_load_dwordx2 v[18:19], v[10:11], off
	global_load_dwordx2 v[100:101], v[10:11], off offset:512
	global_load_dwordx2 v[98:99], v[12:13], off
	global_load_dwordx2 v[96:97], v[12:13], off offset:512
	global_load_dwordx2 v[94:95], v[12:13], off offset:1024
	global_load_dwordx2 v[92:93], v[12:13], off offset:1536
	global_load_dwordx2 v[90:91], v[12:13], off offset:2048
	global_load_dwordx2 v[88:89], v[12:13], off offset:2560
	v_add_co_u32_e32 v10, vcc, s43, v12
	s_add_i32 s22, s10, 2
	s_nop 0
	v_addc_co_u32_e32 v11, vcc, 0, v13, vcc
	global_load_dwordx2 v[86:87], v[12:13], off offset:3072
	global_load_dwordx2 v[26:27], v[12:13], off offset:3584
	global_load_dwordx2 v[24:25], v[10:11], off
	global_load_dwordx2 v[84:85], v[10:11], off offset:512
	v_mad_i64_i32 v[10:11], s[6:7], s22, v217, v[40:41]
	global_load_dwordx2 v[82:83], v[10:11], off
	global_load_dwordx2 v[80:81], v[10:11], off offset:512
	global_load_dwordx2 v[78:79], v[10:11], off offset:1024
	global_load_dwordx2 v[76:77], v[10:11], off offset:1536
	global_load_dwordx2 v[74:75], v[10:11], off offset:2048
	global_load_dwordx2 v[72:73], v[10:11], off offset:2560
	global_load_dwordx2 v[70:71], v[10:11], off offset:3072
	global_load_dwordx2 v[30:31], v[10:11], off offset:3584
	v_add_co_u32_e32 v10, vcc, s43, v10
	s_add_i32 s16, s10, 3
	s_nop 0
	v_addc_co_u32_e32 v11, vcc, 0, v11, vcc
	v_mad_i64_i32 v[12:13], s[6:7], s16, v217, v[40:41]
	global_load_dwordx2 v[28:29], v[10:11], off
	global_load_dwordx2 v[66:67], v[10:11], off offset:512
	global_load_dwordx2 v[62:63], v[12:13], off
	global_load_dwordx2 v[60:61], v[12:13], off offset:512
	global_load_dwordx2 v[58:59], v[12:13], off offset:1024
	global_load_dwordx2 v[56:57], v[12:13], off offset:1536
	global_load_dwordx2 v[54:55], v[12:13], off offset:2048
	global_load_dwordx2 v[52:53], v[12:13], off offset:2560
	v_add_co_u32_e32 v10, vcc, s43, v12
	s_nop 1
	v_addc_co_u32_e32 v11, vcc, 0, v13, vcc
	s_waitcnt lgkmcnt(0)
	global_load_dwordx2 v[50:51], v[12:13], off offset:3072
	global_load_dwordx2 v[34:35], v[12:13], off offset:3584
	global_load_dwordx2 v[32:33], v[10:11], off
	global_load_dwordx2 v[48:49], v[10:11], off offset:512
	v_cvt_f32_u32_e32 v10, s82
	v_cndmask_b32_e64 v69, v218, v10, s[12:13]
	v_mul_f32_e32 v10, v39, v69
	v_cvt_f64_f32_e32 v[10:11], v10
	v_mul_f64 v[12:13], v[10:11], s[66:67]
	v_rndne_f64_e32 v[12:13], v[12:13]
	v_fma_f64 v[10:11], v[10:11], s[66:67], -v[12:13]
	v_cvt_f32_f64_e32 v10, v[10:11]
	v_mul_f32_e32 v11, v120, v69
	v_cvt_f64_f32_e32 v[16:17], v11
	v_mul_f64 v[64:65], v[16:17], s[66:67]
	v_rndne_f64_e32 v[64:65], v[64:65]
	v_fma_f64 v[16:17], v[16:17], s[66:67], -v[64:65]
	v_cvt_f32_f64_e32 v11, v[16:17]
	v_mul_f32_e32 v16, v121, v69
	v_cvt_f64_f32_e32 v[16:17], v16
	v_mul_f64 v[64:65], v[16:17], s[66:67]
	v_rndne_f64_e32 v[64:65], v[64:65]
	v_fma_f64 v[16:17], v[16:17], s[66:67], -v[64:65]
	v_cvt_f32_f64_e32 v16, v[16:17]
	v_cos_f32_e32 v64, v16
	v_sin_f32_e32 v68, v16
	v_mul_f32_e32 v16, v122, v69
	v_cvt_f64_f32_e32 v[16:17], v16
	v_mul_f64 v[102:103], v[16:17], s[66:67]
	v_rndne_f64_e32 v[102:103], v[102:103]
	v_fma_f64 v[16:17], v[16:17], s[66:67], -v[102:103]
	v_cvt_f32_f64_e32 v16, v[16:17]
	v_cos_f32_e32 v65, v16
	v_sin_f32_e32 v69, v16
	s_waitcnt vmcnt(39)
	v_lshlrev_b32_e32 v17, 16, v15
	v_lshlrev_b32_e32 v16, 16, v14
	v_and_b32_e32 v15, 0xffff0000, v15
	v_and_b32_e32 v14, 0xffff0000, v14
	v_pk_mul_f32 v[102:103], v[14:15], v[14:15]
	v_cos_f32_e32 v12, v10
	v_pk_fma_f32 v[102:103], v[16:17], v[16:17], v[102:103]
	v_sin_f32_e32 v10, v10
	v_add_f32_e32 v102, v102, v103
	s_nop 1
	v_mov_b32_dpp v103, v102 quad_perm:[1,0,3,2] row_mask:0xf bank_mask:0xf
	v_cos_f32_e32 v13, v11
	v_sin_f32_e32 v11, v11
	s_waitcnt lgkmcnt(0)
	v_add_f32_e32 v102, v102, v103
	s_nop 1
	v_mov_b32_dpp v103, v102 quad_perm:[2,3,0,1] row_mask:0xf bank_mask:0xf
	s_waitcnt lgkmcnt(0)
	v_add_f32_e32 v102, v102, v103
	s_nop 1
	v_mov_b32_dpp v103, v102 row_half_mirror row_mask:0xf bank_mask:0xf
	s_waitcnt lgkmcnt(0)
	v_add_f32_e32 v102, v102, v103
	s_nop 1
	v_mov_b32_dpp v103, v102 row_mirror row_mask:0xf bank_mask:0xf
	s_waitcnt lgkmcnt(0)
	v_add_f32_e32 v102, v102, v103
	v_fmamk_f32 v102, v102, 0x3c800000, v204
	v_cmp_gt_f32_e32 vcc, s33, v102
	v_mul_f32_e32 v103, 0x4f800000, v102
	s_nop 0
	v_cndmask_b32_e32 v102, v102, v103, vcc
	v_sqrt_f32_e32 v103, v102
	s_nop 0
	v_add_u32_e32 v112, -1, v103
	v_fma_f32 v113, -v112, v103, v102
	v_cmp_ge_f32_e64 s[6:7], 0, v113
	v_add_u32_e32 v113, 1, v103
	s_nop 0
	v_cndmask_b32_e64 v112, v103, v112, s[6:7]
	v_fma_f32 v103, -v113, v103, v102
	v_cmp_lt_f32_e64 s[6:7], 0, v103
	s_nop 1
	v_cndmask_b32_e64 v103, v112, v113, s[6:7]
	v_mul_f32_e32 v112, 0x37800000, v103
	v_cndmask_b32_e32 v103, v103, v112, vcc
	v_cmp_class_f32_e32 vcc, v102, v205
	s_nop 1
	v_cndmask_b32_e32 v102, v103, v102, vcc
	v_div_scale_f32 v103, s[6:7], v102, v102, 1.0
	v_rcp_f32_e32 v112, v103
	s_nop 0
	v_fma_f32 v113, -v103, v112, 1.0
	v_fmac_f32_e32 v112, v113, v112
	v_div_scale_f32 v113, vcc, 1.0, v102, 1.0
	v_mul_f32_e32 v116, v113, v112
	v_fma_f32 v117, -v103, v116, v113
	v_fmac_f32_e32 v116, v117, v112
	v_fma_f32 v103, -v103, v116, v113
	v_div_fmas_f32 v103, v103, v112, v116
	v_div_fixup_f32 v102, v103, v102, 1.0
	v_mov_b32_e32 v112, v16
	v_mov_b32_e32 v113, v14
	v_mov_b32_e32 v14, v17
	v_pk_mul_f32 v[116:117], v[102:103], v[112:113] op_sel_hi:[0,1]
	v_pk_mul_f32 v[14:15], v[102:103], v[14:15] op_sel_hi:[0,1]
	v_pk_mul_f32 v[112:113], v[8:9], v[14:15]
	v_pk_mul_f32 v[102:103], v[6:7], v[116:117]
	s_nop 1
	v_mov_b32_dpp v14, v102 quad_perm:[2,3,0,1] row_mask:0xf bank_mask:0xf
	v_mov_b32_dpp v15, v103 quad_perm:[2,3,0,1] row_mask:0xf bank_mask:0xf
	v_mov_b32_dpp v116, v112 quad_perm:[2,3,0,1] row_mask:0xf bank_mask:0xf
	v_mov_b32_dpp v117, v113 quad_perm:[2,3,0,1] row_mask:0xf bank_mask:0xf
	s_and_saveexec_b64 s[6:7], s[2:3]
	s_xor_b64 s[6:7], exec, s[6:7]
	s_cbranch_execz .LBB0_837
	s_and_saveexec_b64 s[8:9], s[4:5]
	s_cbranch_execz .LBB0_836
	v_pk_mul_f32 v[16:17], v[64:65], v[112:113]
	v_pk_mul_f32 v[102:103], v[12:13], v[102:103]
	s_waitcnt lgkmcnt(0)
	v_pk_fma_f32 v[112:113], v[68:69], v[116:117], v[16:17]
	v_pk_fma_f32 v[102:103], v[10:11], v[14:15], v[102:103]

; __device__ __forceinline__ void phase_qkpost(Frame& F, const Params& p, int j) {
;     ...
;             for (int c = 0; c < 9; ++c) {
;                 f32x4 v = x[c];
;                 float ss = (v.x * v.x + v.y * v.y) + (v.z * v.z + v.w * v.w);
;                 ss += __shfl_xor(ss, 1); ss += __shfl_xor(ss, 2); ss += __shfl_xor(ss, 4); ss += __shfl_xor(ss, 8);
;                 v = v * (1.0f / sqrtf(ss * (1.0f / 64.0f) + EPS)) * (c < 8 ? qg : kg);
;                 f32x4 pr; pr.x = __shfl_xor(v.x, 2); pr.y = __shfl_xor(v.y, 2); pr.z = __shfl_xor(v.z, 2); pr.w = __shfl_xor(v.w, 2);
;                 if (li < 2) v = v * cs - pr * sn; else if (li < 4) v = v * cs + pr * sn;
.LBB0_843:
	s_waitcnt vmcnt(38)
	v_and_b32_e32 v17, 0xffff0000, v115
	v_and_b32_e32 v16, 0xffff0000, v114
	v_lshlrev_b32_e32 v15, 16, v115
	v_lshlrev_b32_e32 v14, 16, v114
	v_pk_mul_f32 v[114:115], v[16:17], v[16:17]
	s_nop 0
	v_pk_fma_f32 v[114:115], v[14:15], v[14:15], v[114:115]
	s_nop 0
	v_add_f32_e32 v114, v114, v115
	s_waitcnt lgkmcnt(0)
	s_nop 1
	v_add_f32_dpp v114, v114, v114 quad_perm:[1,0,3,2] row_mask:0xf bank_mask:0xf
	s_nop 1
	v_add_f32_dpp v114, v114, v114 quad_perm:[2,3,0,1] row_mask:0xf bank_mask:0xf
	s_nop 1
	v_add_f32_dpp v114, v114, v114 row_half_mirror row_mask:0xf bank_mask:0xf
	s_nop 1
	v_add_f32_dpp v114, v114, v114 row_mirror row_mask:0xf bank_mask:0xf
	v_fmamk_f32 v114, v114, 0x3c800000, v204
	v_mul_f32_e32 v115, 0x4f800000, v114
	v_cmp_gt_f32_e32 vcc, s33, v114
	s_nop 1
	v_cndmask_b32_e32 v116, v114, v115, vcc
	v_sqrt_f32_e32 v117, v116
	v_mov_b32_e32 v114, v14
	v_mov_b32_e32 v115, v16
	v_add_u32_e32 v14, -1, v117
	v_add_u32_e32 v16, 1, v117
	v_fma_f32 v118, -v14, v117, v116
	v_fma_f32 v119, -v16, v117, v116
	v_cmp_ge_f32_e64 s[6:7], 0, v118
	s_nop 1
	v_cndmask_b32_e64 v14, v117, v14, s[6:7]
	v_cmp_lt_f32_e64 s[6:7], 0, v119
	s_nop 1
	v_cndmask_b32_e64 v14, v14, v16, s[6:7]
	v_mul_f32_e32 v16, 0x37800000, v14
	v_cndmask_b32_e32 v14, v14, v16, vcc
	v_cmp_class_f32_e32 vcc, v116, v205
	v_mov_b32_e32 v16, v15
	s_nop 0
	v_cndmask_b32_e32 v14, v14, v116, vcc
	v_div_scale_f32 v116, s[6:7], v14, v14, 1.0
	v_rcp_f32_e32 v117, v116
	v_div_scale_f32 v15, vcc, 1.0, v14, 1.0
	v_fma_f32 v118, -v116, v117, 1.0
	v_fmac_f32_e32 v117, v118, v117
	v_mul_f32_e32 v118, v15, v117
	v_fma_f32 v119, -v116, v118, v15
	v_fmac_f32_e32 v118, v119, v117
	v_fma_f32 v15, -v116, v118, v15
	v_div_fmas_f32 v15, v15, v117, v118
	v_div_fixup_f32 v14, v15, v14, 1.0
	v_pk_mul_f32 v[114:115], v[14:15], v[114:115] op_sel_hi:[0,1]
	v_pk_mul_f32 v[14:15], v[14:15], v[16:17] op_sel_hi:[0,1]
	v_pk_mul_f32 v[116:117], v[8:9], v[14:15]
	v_pk_mul_f32 v[114:115], v[6:7], v[114:115]
	s_nop 1
	v_mov_b32_dpp v14, v114 quad_perm:[2,3,0,1] row_mask:0xf bank_mask:0xf
	v_mov_b32_dpp v15, v115 quad_perm:[2,3,0,1] row_mask:0xf bank_mask:0xf
	v_mov_b32_dpp v118, v116 quad_perm:[2,3,0,1] row_mask:0xf bank_mask:0xf
	v_mov_b32_dpp v119, v117 quad_perm:[2,3,0,1] row_mask:0xf bank_mask:0xf
	s_and_saveexec_b64 s[6:7], s[2:3]
	s_xor_b64 s[6:7], exec, s[6:7]
	s_cbranch_execz .LBB0_847
	s_and_saveexec_b64 s[8:9], s[4:5]
	s_cbranch_execz .LBB0_846
	v_pk_mul_f32 v[16:17], v[64:65], v[116:117]
	v_pk_mul_f32 v[114:115], v[12:13], v[114:115]
	s_waitcnt lgkmcnt(0)
	v_pk_fma_f32 v[116:117], v[68:69], v[118:119], v[16:17]
	v_pk_fma_f32 v[114:115], v[10:11], v[14:15], v[114:115]

; __device__ __forceinline__ void phase_qkpost(Frame& F, const Params& p, int j) {
;     ...
;             for (int c = 0; c < 9; ++c) {
;                 f32x4 v = x[c];
;                 float ss = (v.x * v.x + v.y * v.y) + (v.z * v.z + v.w * v.w);
;                 ss += __shfl_xor(ss, 1); ss += __shfl_xor(ss, 2); ss += __shfl_xor(ss, 4); ss += __shfl_xor(ss, 8);
;                 v = v * (1.0f / sqrtf(ss * (1.0f / 64.0f) + EPS)) * (c < 8 ? qg : kg);
;                 f32x4 pr; pr.x = __shfl_xor(v.x, 2); pr.y = __shfl_xor(v.y, 2); pr.z = __shfl_xor(v.z, 2); pr.w = __shfl_xor(v.w, 2);
;                 if (li < 2) v = v * cs - pr * sn; else if (li < 4) v = v * cs + pr * sn;
.LBB0_853:
	s_waitcnt vmcnt(37)
	v_and_b32_e32 v17, 0xffff0000, v111
	v_and_b32_e32 v16, 0xffff0000, v110
	v_lshlrev_b32_e32 v15, 16, v111
	v_lshlrev_b32_e32 v14, 16, v110
	v_pk_mul_f32 v[110:111], v[16:17], v[16:17]
	s_nop 0
	v_pk_fma_f32 v[110:111], v[14:15], v[14:15], v[110:111]
	s_nop 0
	v_add_f32_e32 v110, v110, v111
	s_waitcnt lgkmcnt(0)
	s_nop 1
	v_add_f32_dpp v110, v110, v110 quad_perm:[1,0,3,2] row_mask:0xf bank_mask:0xf
	s_nop 1
	v_add_f32_dpp v110, v110, v110 quad_perm:[2,3,0,1] row_mask:0xf bank_mask:0xf
	s_nop 1
	v_add_f32_dpp v110, v110, v110 row_half_mirror row_mask:0xf bank_mask:0xf
	s_nop 1
	v_add_f32_dpp v110, v110, v110 row_mirror row_mask:0xf bank_mask:0xf
	v_fmamk_f32 v110, v110, 0x3c800000, v204
	v_mul_f32_e32 v111, 0x4f800000, v110
	v_cmp_gt_f32_e32 vcc, s33, v110
	s_nop 1
	v_cndmask_b32_e32 v114, v110, v111, vcc
	v_sqrt_f32_e32 v115, v114
	v_mov_b32_e32 v110, v14
	v_mov_b32_e32 v111, v16
	v_add_u32_e32 v14, -1, v115
	v_add_u32_e32 v16, 1, v115
	v_fma_f32 v116, -v14, v115, v114
	v_fma_f32 v117, -v16, v115, v114
	v_cmp_ge_f32_e64 s[8:9], 0, v116
	s_nop 1
	v_cndmask_b32_e64 v14, v115, v14, s[8:9]
	v_cmp_lt_f32_e64 s[8:9], 0, v117
	s_nop 1
	v_cndmask_b32_e64 v14, v14, v16, s[8:9]
	v_mul_f32_e32 v16, 0x37800000, v14
	v_cndmask_b32_e32 v14, v14, v16, vcc
	v_cmp_class_f32_e32 vcc, v114, v205
	v_mov_b32_e32 v16, v15
	s_nop 0
	v_cndmask_b32_e32 v14, v14, v114, vcc
	v_div_scale_f32 v114, s[8:9], v14, v14, 1.0
	v_rcp_f32_e32 v115, v114
	v_div_scale_f32 v15, vcc, 1.0, v14, 1.0
	v_fma_f32 v116, -v114, v115, 1.0
	v_fmac_f32_e32 v115, v116, v115
	v_mul_f32_e32 v116, v15, v115
	v_fma_f32 v117, -v114, v116, v15
	v_fmac_f32_e32 v116, v117, v115
	v_fma_f32 v15, -v114, v116, v15
	v_div_fmas_f32 v15, v15, v115, v116
	v_div_fixup_f32 v14, v15, v14, 1.0
	v_pk_mul_f32 v[110:111], v[14:15], v[110:111] op_sel_hi:[0,1]
	v_pk_mul_f32 v[14:15], v[14:15], v[16:17] op_sel_hi:[0,1]
	v_pk_mul_f32 v[114:115], v[8:9], v[14:15]
	v_pk_mul_f32 v[110:111], v[6:7], v[110:111]
	s_nop 1
	v_mov_b32_dpp v14, v110 quad_perm:[2,3,0,1] row_mask:0xf bank_mask:0xf
	v_mov_b32_dpp v15, v111 quad_perm:[2,3,0,1] row_mask:0xf bank_mask:0xf
	v_mov_b32_dpp v116, v114 quad_perm:[2,3,0,1] row_mask:0xf bank_mask:0xf
	v_mov_b32_dpp v117, v115 quad_perm:[2,3,0,1] row_mask:0xf bank_mask:0xf
	s_and_saveexec_b64 s[8:9], s[2:3]
	s_xor_b64 s[8:9], exec, s[8:9]
	s_cbranch_execz .LBB0_857
	s_and_saveexec_b64 s[20:21], s[4:5]
	s_cbranch_execz .LBB0_856
	v_pk_mul_f32 v[16:17], v[64:65], v[114:115]
	v_pk_mul_f32 v[110:111], v[12:13], v[110:111]
	s_waitcnt lgkmcnt(0)
	v_pk_fma_f32 v[114:115], v[68:69], v[116:117], v[16:17]
	v_pk_fma_f32 v[110:111], v[10:11], v[14:15], v[110:111]

; __device__ __forceinline__ void phase_qkpost(Frame& F, const Params& p, int j) {
;     ...
;             for (int c = 0; c < 9; ++c) {
;                 f32x4 v = x[c];
;                 float ss = (v.x * v.x + v.y * v.y) + (v.z * v.z + v.w * v.w);
;                 ss += __shfl_xor(ss, 1); ss += __shfl_xor(ss, 2); ss += __shfl_xor(ss, 4); ss += __shfl_xor(ss, 8);
;                 v = v * (1.0f / sqrtf(ss * (1.0f / 64.0f) + EPS)) * (c < 8 ? qg : kg);
;                 f32x4 pr; pr.x = __shfl_xor(v.x, 2); pr.y = __shfl_xor(v.y, 2); pr.z = __shfl_xor(v.z, 2); pr.w = __shfl_xor(v.w, 2);
;                 if (li < 2) v = v * cs - pr * sn; else if (li < 4) v = v * cs + pr * sn;
.LBB0_863:
	s_waitcnt vmcnt(36)
	v_and_b32_e32 v17, 0xffff0000, v109
	v_and_b32_e32 v16, 0xffff0000, v108
	v_lshlrev_b32_e32 v15, 16, v109
	v_lshlrev_b32_e32 v14, 16, v108
	v_pk_mul_f32 v[108:109], v[16:17], v[16:17]
	s_nop 0
	v_pk_fma_f32 v[108:109], v[14:15], v[14:15], v[108:109]
	s_nop 0
	v_add_f32_e32 v108, v108, v109
	s_waitcnt lgkmcnt(0)
	s_nop 1
	v_add_f32_dpp v108, v108, v108 quad_perm:[1,0,3,2] row_mask:0xf bank_mask:0xf
	s_nop 1
	v_add_f32_dpp v108, v108, v108 quad_perm:[2,3,0,1] row_mask:0xf bank_mask:0xf
	s_nop 1
	v_add_f32_dpp v108, v108, v108 row_half_mirror row_mask:0xf bank_mask:0xf
	s_nop 1
	v_add_f32_dpp v108, v108, v108 row_mirror row_mask:0xf bank_mask:0xf
	v_fmamk_f32 v108, v108, 0x3c800000, v204
	v_mul_f32_e32 v109, 0x4f800000, v108
	v_cmp_gt_f32_e32 vcc, s33, v108
	s_nop 1
	v_cndmask_b32_e32 v110, v108, v109, vcc
	v_sqrt_f32_e32 v111, v110
	v_mov_b32_e32 v108, v14
	v_mov_b32_e32 v109, v16
	v_add_u32_e32 v14, -1, v111
	v_add_u32_e32 v16, 1, v111
	v_fma_f32 v114, -v14, v111, v110
	v_fma_f32 v115, -v16, v111, v110
	v_cmp_ge_f32_e64 s[8:9], 0, v114
	s_nop 1
	v_cndmask_b32_e64 v14, v111, v14, s[8:9]
	v_cmp_lt_f32_e64 s[8:9], 0, v115
	s_nop 1
	v_cndmask_b32_e64 v14, v14, v16, s[8:9]
	v_mul_f32_e32 v16, 0x37800000, v14
	v_cndmask_b32_e32 v14, v14, v16, vcc
	v_cmp_class_f32_e32 vcc, v110, v205
	v_mov_b32_e32 v16, v15
	s_nop 0
	v_cndmask_b32_e32 v14, v14, v110, vcc
	v_div_scale_f32 v110, s[8:9], v14, v14, 1.0
	v_rcp_f32_e32 v111, v110
	v_div_scale_f32 v15, vcc, 1.0, v14, 1.0
	v_fma_f32 v114, -v110, v111, 1.0
	v_fmac_f32_e32 v111, v114, v111
	v_mul_f32_e32 v114, v15, v111
	v_fma_f32 v115, -v110, v114, v15
	v_fmac_f32_e32 v114, v115, v111
	v_fma_f32 v15, -v110, v114, v15
	v_div_fmas_f32 v15, v15, v111, v114
	v_div_fixup_f32 v14, v15, v14, 1.0
	v_pk_mul_f32 v[108:109], v[14:15], v[108:109] op_sel_hi:[0,1]
	v_pk_mul_f32 v[14:15], v[14:15], v[16:17] op_sel_hi:[0,1]
	v_pk_mul_f32 v[110:111], v[8:9], v[14:15]
	v_pk_mul_f32 v[108:109], v[6:7], v[108:109]
	s_nop 1
	v_mov_b32_dpp v14, v108 quad_perm:[2,3,0,1] row_mask:0xf bank_mask:0xf
	v_mov_b32_dpp v15, v109 quad_perm:[2,3,0,1] row_mask:0xf bank_mask:0xf
	v_mov_b32_dpp v114, v110 quad_perm:[2,3,0,1] row_mask:0xf bank_mask:0xf
	v_mov_b32_dpp v115, v111 quad_perm:[2,3,0,1] row_mask:0xf bank_mask:0xf
	s_and_saveexec_b64 s[8:9], s[2:3]
	s_xor_b64 s[8:9], exec, s[8:9]
	s_cbranch_execz .LBB0_867
	s_and_saveexec_b64 s[20:21], s[4:5]
	s_cbranch_execz .LBB0_866
	v_pk_mul_f32 v[16:17], v[64:65], v[110:111]
	v_pk_mul_f32 v[108:109], v[12:13], v[108:109]
	s_waitcnt lgkmcnt(0)
	v_pk_fma_f32 v[110:111], v[68:69], v[114:115], v[16:17]
	v_pk_fma_f32 v[108:109], v[10:11], v[14:15], v[108:109]

; __device__ __forceinline__ void phase_qkpost(Frame& F, const Params& p, int j) {
;     ...
;             for (int c = 0; c < 9; ++c) {
;                 f32x4 v = x[c];
;                 float ss = (v.x * v.x + v.y * v.y) + (v.z * v.z + v.w * v.w);
;                 ss += __shfl_xor(ss, 1); ss += __shfl_xor(ss, 2); ss += __shfl_xor(ss, 4); ss += __shfl_xor(ss, 8);
;                 v = v * (1.0f / sqrtf(ss * (1.0f / 64.0f) + EPS)) * (c < 8 ? qg : kg);
;                 f32x4 pr; pr.x = __shfl_xor(v.x, 2); pr.y = __shfl_xor(v.y, 2); pr.z = __shfl_xor(v.z, 2); pr.w = __shfl_xor(v.w, 2);
;                 if (li < 2) v = v * cs - pr * sn; else if (li < 4) v = v * cs + pr * sn;
.LBB0_873:
	s_waitcnt vmcnt(35)
	v_and_b32_e32 v17, 0xffff0000, v107
	v_and_b32_e32 v16, 0xffff0000, v106
	v_lshlrev_b32_e32 v15, 16, v107
	v_lshlrev_b32_e32 v14, 16, v106
	v_pk_mul_f32 v[106:107], v[16:17], v[16:17]
	s_nop 0
	v_pk_fma_f32 v[106:107], v[14:15], v[14:15], v[106:107]
	s_nop 0
	v_add_f32_e32 v106, v106, v107
	s_waitcnt lgkmcnt(0)
	s_nop 1
	v_add_f32_dpp v106, v106, v106 quad_perm:[1,0,3,2] row_mask:0xf bank_mask:0xf
	s_nop 1
	v_add_f32_dpp v106, v106, v106 quad_perm:[2,3,0,1] row_mask:0xf bank_mask:0xf
	s_nop 1
	v_add_f32_dpp v106, v106, v106 row_half_mirror row_mask:0xf bank_mask:0xf
	s_nop 1
	v_add_f32_dpp v106, v106, v106 row_mirror row_mask:0xf bank_mask:0xf
	v_fmamk_f32 v106, v106, 0x3c800000, v204
	v_mul_f32_e32 v107, 0x4f800000, v106
	v_cmp_gt_f32_e32 vcc, s33, v106
	s_nop 1
	v_cndmask_b32_e32 v108, v106, v107, vcc
	v_sqrt_f32_e32 v109, v108
	v_mov_b32_e32 v106, v14
	v_mov_b32_e32 v107, v16
	v_add_u32_e32 v14, -1, v109
	v_add_u32_e32 v16, 1, v109
	v_fma_f32 v110, -v14, v109, v108
	v_fma_f32 v111, -v16, v109, v108
	v_cmp_ge_f32_e64 s[8:9], 0, v110
	s_nop 1
	v_cndmask_b32_e64 v14, v109, v14, s[8:9]
	v_cmp_lt_f32_e64 s[8:9], 0, v111
	s_nop 1
	v_cndmask_b32_e64 v14, v14, v16, s[8:9]
	v_mul_f32_e32 v16, 0x37800000, v14
	v_cndmask_b32_e32 v14, v14, v16, vcc
	v_cmp_class_f32_e32 vcc, v108, v205
	v_mov_b32_e32 v16, v15
	s_nop 0
	v_cndmask_b32_e32 v14, v14, v108, vcc
	v_div_scale_f32 v108, s[8:9], v14, v14, 1.0
	v_rcp_f32_e32 v109, v108
	v_div_scale_f32 v15, vcc, 1.0, v14, 1.0
	v_fma_f32 v110, -v108, v109, 1.0
	v_fmac_f32_e32 v109, v110, v109
	v_mul_f32_e32 v110, v15, v109
	v_fma_f32 v111, -v108, v110, v15
	v_fmac_f32_e32 v110, v111, v109
	v_fma_f32 v15, -v108, v110, v15
	v_div_fmas_f32 v15, v15, v109, v110
	v_div_fixup_f32 v14, v15, v14, 1.0
	v_pk_mul_f32 v[106:107], v[14:15], v[106:107] op_sel_hi:[0,1]
	v_pk_mul_f32 v[14:15], v[14:15], v[16:17] op_sel_hi:[0,1]
	v_pk_mul_f32 v[108:109], v[8:9], v[14:15]
	v_pk_mul_f32 v[106:107], v[6:7], v[106:107]
	s_nop 1
	v_mov_b32_dpp v14, v106 quad_perm:[2,3,0,1] row_mask:0xf bank_mask:0xf
	v_mov_b32_dpp v15, v107 quad_perm:[2,3,0,1] row_mask:0xf bank_mask:0xf
	v_mov_b32_dpp v110, v108 quad_perm:[2,3,0,1] row_mask:0xf bank_mask:0xf
	v_mov_b32_dpp v111, v109 quad_perm:[2,3,0,1] row_mask:0xf bank_mask:0xf
	s_and_saveexec_b64 s[8:9], s[2:3]
	s_xor_b64 s[8:9], exec, s[8:9]
	s_cbranch_execz .LBB0_877
	s_and_saveexec_b64 s[20:21], s[4:5]
	s_cbranch_execz .LBB0_876
	v_pk_mul_f32 v[16:17], v[64:65], v[108:109]
	v_pk_mul_f32 v[106:107], v[12:13], v[106:107]
	s_waitcnt lgkmcnt(0)
	v_pk_fma_f32 v[108:109], v[68:69], v[110:111], v[16:17]
	v_pk_fma_f32 v[106:107], v[10:11], v[14:15], v[106:107]

; __device__ __forceinline__ void phase_qkpost(Frame& F, const Params& p, int j) {
;     ...
;             for (int c = 0; c < 9; ++c) {
;                 f32x4 v = x[c];
;                 float ss = (v.x * v.x + v.y * v.y) + (v.z * v.z + v.w * v.w);
;                 ss += __shfl_xor(ss, 1); ss += __shfl_xor(ss, 2); ss += __shfl_xor(ss, 4); ss += __shfl_xor(ss, 8);
;                 v = v * (1.0f / sqrtf(ss * (1.0f / 64.0f) + EPS)) * (c < 8 ? qg : kg);
;                 f32x4 pr; pr.x = __shfl_xor(v.x, 2); pr.y = __shfl_xor(v.y, 2); pr.z = __shfl_xor(v.z, 2); pr.w = __shfl_xor(v.w, 2);
;                 if (li < 2) v = v * cs - pr * sn; else if (li < 4) v = v * cs + pr * sn;
.LBB0_883:
	s_waitcnt vmcnt(34)
	v_and_b32_e32 v17, 0xffff0000, v105
	v_and_b32_e32 v16, 0xffff0000, v104
	v_lshlrev_b32_e32 v15, 16, v105
	v_lshlrev_b32_e32 v14, 16, v104
	v_pk_mul_f32 v[104:105], v[16:17], v[16:17]
	s_nop 0
	v_pk_fma_f32 v[104:105], v[14:15], v[14:15], v[104:105]
	s_nop 0
	v_add_f32_e32 v104, v104, v105
	s_waitcnt lgkmcnt(0)
	s_nop 1
	v_add_f32_dpp v104, v104, v104 quad_perm:[1,0,3,2] row_mask:0xf bank_mask:0xf
	s_nop 1
	v_add_f32_dpp v104, v104, v104 quad_perm:[2,3,0,1] row_mask:0xf bank_mask:0xf
	s_nop 1
	v_add_f32_dpp v104, v104, v104 row_half_mirror row_mask:0xf bank_mask:0xf
	s_nop 1
	v_add_f32_dpp v104, v104, v104 row_mirror row_mask:0xf bank_mask:0xf
	v_fmamk_f32 v104, v104, 0x3c800000, v204
	v_mul_f32_e32 v105, 0x4f800000, v104
	v_cmp_gt_f32_e32 vcc, s33, v104
	s_nop 1
	v_cndmask_b32_e32 v106, v104, v105, vcc
	v_sqrt_f32_e32 v107, v106
	v_mov_b32_e32 v104, v14
	v_mov_b32_e32 v105, v16
	v_add_u32_e32 v14, -1, v107
	v_add_u32_e32 v16, 1, v107
	v_fma_f32 v108, -v14, v107, v106
	v_fma_f32 v109, -v16, v107, v106
	v_cmp_ge_f32_e64 s[8:9], 0, v108
	s_nop 1
	v_cndmask_b32_e64 v14, v107, v14, s[8:9]
	v_cmp_lt_f32_e64 s[8:9], 0, v109
	s_nop 1
	v_cndmask_b32_e64 v14, v14, v16, s[8:9]
	v_mul_f32_e32 v16, 0x37800000, v14
	v_cndmask_b32_e32 v14, v14, v16, vcc
	v_cmp_class_f32_e32 vcc, v106, v205
	v_mov_b32_e32 v16, v15
	s_nop 0
	v_cndmask_b32_e32 v14, v14, v106, vcc
	v_div_scale_f32 v106, s[8:9], v14, v14, 1.0
	v_rcp_f32_e32 v107, v106
	v_div_scale_f32 v15, vcc, 1.0, v14, 1.0
	v_fma_f32 v108, -v106, v107, 1.0
	v_fmac_f32_e32 v107, v108, v107
	v_mul_f32_e32 v108, v15, v107
	v_fma_f32 v109, -v106, v108, v15
	v_fmac_f32_e32 v108, v109, v107
	v_fma_f32 v15, -v106, v108, v15
	v_div_fmas_f32 v15, v15, v107, v108
	v_div_fixup_f32 v14, v15, v14, 1.0
	v_pk_mul_f32 v[104:105], v[14:15], v[104:105] op_sel_hi:[0,1]
	v_pk_mul_f32 v[14:15], v[14:15], v[16:17] op_sel_hi:[0,1]
	v_pk_mul_f32 v[106:107], v[8:9], v[14:15]
	v_pk_mul_f32 v[104:105], v[6:7], v[104:105]
	s_nop 1
	v_mov_b32_dpp v14, v104 quad_perm:[2,3,0,1] row_mask:0xf bank_mask:0xf
	v_mov_b32_dpp v15, v105 quad_perm:[2,3,0,1] row_mask:0xf bank_mask:0xf
	v_mov_b32_dpp v108, v106 quad_perm:[2,3,0,1] row_mask:0xf bank_mask:0xf
	v_mov_b32_dpp v109, v107 quad_perm:[2,3,0,1] row_mask:0xf bank_mask:0xf
	s_and_saveexec_b64 s[8:9], s[2:3]
	s_xor_b64 s[8:9], exec, s[8:9]
	s_cbranch_execz .LBB0_887
	s_and_saveexec_b64 s[20:21], s[4:5]
	s_cbranch_execz .LBB0_886
	v_pk_mul_f32 v[16:17], v[64:65], v[106:107]
	v_pk_mul_f32 v[104:105], v[12:13], v[104:105]
	s_waitcnt lgkmcnt(0)
	v_pk_fma_f32 v[106:107], v[68:69], v[108:109], v[16:17]
	v_pk_fma_f32 v[104:105], v[10:11], v[14:15], v[104:105]

; __device__ __forceinline__ void phase_qkpost(Frame& F, const Params& p, int j) {
;     ...
;             for (int c = 0; c < 9; ++c) {
;                 f32x4 v = x[c];
;                 float ss = (v.x * v.x + v.y * v.y) + (v.z * v.z + v.w * v.w);
;                 ss += __shfl_xor(ss, 1); ss += __shfl_xor(ss, 2); ss += __shfl_xor(ss, 4); ss += __shfl_xor(ss, 8);
;                 v = v * (1.0f / sqrtf(ss * (1.0f / 64.0f) + EPS)) * (c < 8 ? qg : kg);
;                 f32x4 pr; pr.x = __shfl_xor(v.x, 2); pr.y = __shfl_xor(v.y, 2); pr.z = __shfl_xor(v.z, 2); pr.w = __shfl_xor(v.w, 2);
;                 if (li < 2) v = v * cs - pr * sn; else if (li < 4) v = v * cs + pr * sn;
.LBB0_893:
	s_waitcnt vmcnt(33)
	v_and_b32_e32 v17, 0xffff0000, v23
	v_and_b32_e32 v16, 0xffff0000, v22
	v_lshlrev_b32_e32 v15, 16, v23
	v_lshlrev_b32_e32 v14, 16, v22
	v_pk_mul_f32 v[22:23], v[16:17], v[16:17]
	s_nop 0
	v_pk_fma_f32 v[22:23], v[14:15], v[14:15], v[22:23]
	s_nop 0
	v_add_f32_e32 v22, v22, v23
	s_waitcnt lgkmcnt(0)
	s_nop 1
	v_add_f32_dpp v22, v22, v22 quad_perm:[1,0,3,2] row_mask:0xf bank_mask:0xf
	s_nop 1
	v_add_f32_dpp v22, v22, v22 quad_perm:[2,3,0,1] row_mask:0xf bank_mask:0xf
	s_nop 1
	v_add_f32_dpp v22, v22, v22 row_half_mirror row_mask:0xf bank_mask:0xf
	s_nop 1
	v_add_f32_dpp v22, v22, v22 row_mirror row_mask:0xf bank_mask:0xf
	v_fmamk_f32 v22, v22, 0x3c800000, v204
	v_mul_f32_e32 v23, 0x4f800000, v22
	v_cmp_gt_f32_e32 vcc, s33, v22
	s_nop 1
	v_cndmask_b32_e32 v104, v22, v23, vcc
	v_sqrt_f32_e32 v105, v104
	v_mov_b32_e32 v22, v14
	v_mov_b32_e32 v23, v16
	v_add_u32_e32 v14, -1, v105
	v_add_u32_e32 v16, 1, v105
	v_fma_f32 v106, -v14, v105, v104
	v_fma_f32 v107, -v16, v105, v104
	v_cmp_ge_f32_e64 s[8:9], 0, v106
	s_nop 1
	v_cndmask_b32_e64 v14, v105, v14, s[8:9]
	v_cmp_lt_f32_e64 s[8:9], 0, v107
	s_nop 1
	v_cndmask_b32_e64 v14, v14, v16, s[8:9]
	v_mul_f32_e32 v16, 0x37800000, v14
	v_cndmask_b32_e32 v14, v14, v16, vcc
	v_cmp_class_f32_e32 vcc, v104, v205
	v_mov_b32_e32 v16, v15
	s_nop 0
	v_cndmask_b32_e32 v14, v14, v104, vcc
	v_div_scale_f32 v104, s[8:9], v14, v14, 1.0
	v_rcp_f32_e32 v105, v104
	v_div_scale_f32 v15, vcc, 1.0, v14, 1.0
	v_fma_f32 v106, -v104, v105, 1.0
	v_fmac_f32_e32 v105, v106, v105
	v_mul_f32_e32 v106, v15, v105
	v_fma_f32 v107, -v104, v106, v15
	v_fmac_f32_e32 v106, v107, v105
	v_fma_f32 v15, -v104, v106, v15
	v_div_fmas_f32 v15, v15, v105, v106
	v_div_fixup_f32 v14, v15, v14, 1.0
	v_pk_mul_f32 v[22:23], v[14:15], v[22:23] op_sel_hi:[0,1]
	v_pk_mul_f32 v[14:15], v[14:15], v[16:17] op_sel_hi:[0,1]
	v_pk_mul_f32 v[104:105], v[8:9], v[14:15]
	v_pk_mul_f32 v[22:23], v[6:7], v[22:23]
	s_nop 1
	v_mov_b32_dpp v14, v22 quad_perm:[2,3,0,1] row_mask:0xf bank_mask:0xf
	v_mov_b32_dpp v15, v23 quad_perm:[2,3,0,1] row_mask:0xf bank_mask:0xf
	v_mov_b32_dpp v106, v104 quad_perm:[2,3,0,1] row_mask:0xf bank_mask:0xf
	v_mov_b32_dpp v107, v105 quad_perm:[2,3,0,1] row_mask:0xf bank_mask:0xf
	s_and_saveexec_b64 s[8:9], s[2:3]
	s_xor_b64 s[8:9], exec, s[8:9]
	s_cbranch_execz .LBB0_897
	s_and_saveexec_b64 s[20:21], s[4:5]
	s_cbranch_execz .LBB0_896
	v_pk_mul_f32 v[16:17], v[64:65], v[104:105]
	v_pk_mul_f32 v[22:23], v[12:13], v[22:23]
	s_waitcnt lgkmcnt(0)
	v_pk_fma_f32 v[104:105], v[68:69], v[106:107], v[16:17]
	v_pk_fma_f32 v[22:23], v[10:11], v[14:15], v[22:23]

; __device__ __forceinline__ void phase_qkpost(Frame& F, const Params& p, int j) {
;     ...
;             for (int c = 0; c < 9; ++c) {
;                 f32x4 v = x[c];
;                 float ss = (v.x * v.x + v.y * v.y) + (v.z * v.z + v.w * v.w);
;                 ss += __shfl_xor(ss, 1); ss += __shfl_xor(ss, 2); ss += __shfl_xor(ss, 4); ss += __shfl_xor(ss, 8);
;                 v = v * (1.0f / sqrtf(ss * (1.0f / 64.0f) + EPS)) * (c < 8 ? qg : kg);
;                 f32x4 pr; pr.x = __shfl_xor(v.x, 2); pr.y = __shfl_xor(v.y, 2); pr.z = __shfl_xor(v.z, 2); pr.w = __shfl_xor(v.w, 2);
;                 if (li < 2) v = v * cs - pr * sn; else if (li < 4) v = v * cs + pr * sn;
.LBB0_903:
	s_waitcnt vmcnt(32)
	v_and_b32_e32 v17, 0xffff0000, v21
	v_and_b32_e32 v16, 0xffff0000, v20
	v_lshlrev_b32_e32 v15, 16, v21
	v_lshlrev_b32_e32 v14, 16, v20
	v_pk_mul_f32 v[20:21], v[16:17], v[16:17]
	s_nop 0
	v_pk_fma_f32 v[20:21], v[14:15], v[14:15], v[20:21]
	s_nop 0
	v_add_f32_e32 v20, v20, v21
	s_waitcnt lgkmcnt(0)
	s_nop 1
	v_add_f32_dpp v20, v20, v20 quad_perm:[1,0,3,2] row_mask:0xf bank_mask:0xf
	s_nop 1
	v_add_f32_dpp v20, v20, v20 quad_perm:[2,3,0,1] row_mask:0xf bank_mask:0xf
	s_nop 1
	v_add_f32_dpp v20, v20, v20 row_half_mirror row_mask:0xf bank_mask:0xf
	s_nop 1
	v_add_f32_dpp v20, v20, v20 row_mirror row_mask:0xf bank_mask:0xf
	v_fmamk_f32 v20, v20, 0x3c800000, v204
	v_mul_f32_e32 v21, 0x4f800000, v20
	v_cmp_gt_f32_e32 vcc, s33, v20
	s_nop 1
	v_cndmask_b32_e32 v22, v20, v21, vcc
	v_sqrt_f32_e32 v23, v22
	v_mov_b32_e32 v20, v14
	v_mov_b32_e32 v21, v16
	v_add_u32_e32 v14, -1, v23
	v_add_u32_e32 v16, 1, v23
	v_fma_f32 v104, -v14, v23, v22
	v_fma_f32 v105, -v16, v23, v22
	v_cmp_ge_f32_e64 s[8:9], 0, v104
	s_nop 1
	v_cndmask_b32_e64 v14, v23, v14, s[8:9]
	v_cmp_lt_f32_e64 s[8:9], 0, v105
	s_nop 1
	v_cndmask_b32_e64 v14, v14, v16, s[8:9]
	v_mul_f32_e32 v16, 0x37800000, v14
	v_cndmask_b32_e32 v14, v14, v16, vcc
	v_cmp_class_f32_e32 vcc, v22, v205
	v_mov_b32_e32 v16, v15
	s_nop 0
	v_cndmask_b32_e32 v14, v14, v22, vcc
	v_div_scale_f32 v22, s[8:9], v14, v14, 1.0
	v_rcp_f32_e32 v23, v22
	v_div_scale_f32 v15, vcc, 1.0, v14, 1.0
	v_fma_f32 v104, -v22, v23, 1.0
	v_fmac_f32_e32 v23, v104, v23
	v_mul_f32_e32 v104, v15, v23
	v_fma_f32 v105, -v22, v104, v15
	v_fmac_f32_e32 v104, v105, v23
	v_fma_f32 v15, -v22, v104, v15
	v_div_fmas_f32 v15, v15, v23, v104
	v_div_fixup_f32 v14, v15, v14, 1.0
	v_pk_mul_f32 v[20:21], v[14:15], v[20:21] op_sel_hi:[0,1]
	v_pk_mul_f32 v[14:15], v[14:15], v[16:17] op_sel_hi:[0,1]
	v_pk_mul_f32 v[22:23], v[8:9], v[14:15]
	v_pk_mul_f32 v[20:21], v[6:7], v[20:21]
	s_nop 1
	v_mov_b32_dpp v14, v20 quad_perm:[2,3,0,1] row_mask:0xf bank_mask:0xf
	v_mov_b32_dpp v15, v21 quad_perm:[2,3,0,1] row_mask:0xf bank_mask:0xf
	v_mov_b32_dpp v104, v22 quad_perm:[2,3,0,1] row_mask:0xf bank_mask:0xf
	v_mov_b32_dpp v105, v23 quad_perm:[2,3,0,1] row_mask:0xf bank_mask:0xf
	s_and_saveexec_b64 s[8:9], s[2:3]
	s_xor_b64 s[8:9], exec, s[8:9]
	s_cbranch_execz .LBB0_907
	s_and_saveexec_b64 s[20:21], s[4:5]
	s_cbranch_execz .LBB0_906
	v_pk_mul_f32 v[16:17], v[64:65], v[22:23]
	v_pk_mul_f32 v[20:21], v[12:13], v[20:21]
	s_waitcnt lgkmcnt(0)
	v_pk_fma_f32 v[22:23], v[68:69], v[104:105], v[16:17]
	v_pk_fma_f32 v[20:21], v[10:11], v[14:15], v[20:21]

; __device__ __forceinline__ void phase_qkpost(Frame& F, const Params& p, int j) {
;     ...
;             for (int c = 0; c < 9; ++c) {
;                 f32x4 v = x[c];
;                 float ss = (v.x * v.x + v.y * v.y) + (v.z * v.z + v.w * v.w);
;                 ss += __shfl_xor(ss, 1); ss += __shfl_xor(ss, 2); ss += __shfl_xor(ss, 4); ss += __shfl_xor(ss, 8);
;                 v = v * (1.0f / sqrtf(ss * (1.0f / 64.0f) + EPS)) * (c < 8 ? qg : kg);
;                 f32x4 pr; pr.x = __shfl_xor(v.x, 2); pr.y = __shfl_xor(v.y, 2); pr.z = __shfl_xor(v.z, 2); pr.w = __shfl_xor(v.w, 2);
;                 if (li < 2) v = v * cs - pr * sn; else if (li < 4) v = v * cs + pr * sn;
.LBB0_913:
	s_waitcnt vmcnt(31)
	v_and_b32_e32 v17, 0xffff0000, v19
	v_and_b32_e32 v16, 0xffff0000, v18
	v_lshlrev_b32_e32 v15, 16, v19
	v_lshlrev_b32_e32 v14, 16, v18
	v_pk_mul_f32 v[18:19], v[16:17], v[16:17]
	s_nop 0
	v_pk_fma_f32 v[18:19], v[14:15], v[14:15], v[18:19]
	s_nop 0
	v_add_f32_e32 v18, v18, v19
	s_waitcnt lgkmcnt(0)
	s_nop 1
	v_add_f32_dpp v18, v18, v18 quad_perm:[1,0,3,2] row_mask:0xf bank_mask:0xf
	s_nop 1
	v_add_f32_dpp v18, v18, v18 quad_perm:[2,3,0,1] row_mask:0xf bank_mask:0xf
	s_nop 1
	v_add_f32_dpp v18, v18, v18 row_half_mirror row_mask:0xf bank_mask:0xf
	s_nop 1
	v_add_f32_dpp v18, v18, v18 row_mirror row_mask:0xf bank_mask:0xf
	v_fmamk_f32 v18, v18, 0x3c800000, v204
	v_mul_f32_e32 v19, 0x4f800000, v18
	v_cmp_gt_f32_e32 vcc, s33, v18
	s_nop 1
	v_cndmask_b32_e32 v20, v18, v19, vcc
	v_sqrt_f32_e32 v21, v20
	v_mov_b32_e32 v18, v14
	v_mov_b32_e32 v19, v16
	v_add_u32_e32 v14, -1, v21
	v_add_u32_e32 v16, 1, v21
	v_fma_f32 v22, -v14, v21, v20
	v_fma_f32 v23, -v16, v21, v20
	v_cmp_ge_f32_e64 s[8:9], 0, v22
	s_nop 1
	v_cndmask_b32_e64 v14, v21, v14, s[8:9]
	v_cmp_lt_f32_e64 s[8:9], 0, v23
	s_nop 1
	v_cndmask_b32_e64 v14, v14, v16, s[8:9]
	v_mul_f32_e32 v16, 0x37800000, v14
	v_cndmask_b32_e32 v14, v14, v16, vcc
	v_cmp_class_f32_e32 vcc, v20, v205
	v_mov_b32_e32 v16, v15
	s_nop 0
	v_cndmask_b32_e32 v14, v14, v20, vcc
	v_div_scale_f32 v20, s[8:9], v14, v14, 1.0
	v_rcp_f32_e32 v21, v20
	v_div_scale_f32 v15, vcc, 1.0, v14, 1.0
	v_fma_f32 v22, -v20, v21, 1.0
	v_fmac_f32_e32 v21, v22, v21
	v_mul_f32_e32 v22, v15, v21
	v_fma_f32 v23, -v20, v22, v15
	v_fmac_f32_e32 v22, v23, v21
	v_fma_f32 v15, -v20, v22, v15
	v_div_fmas_f32 v15, v15, v21, v22
	v_div_fixup_f32 v14, v15, v14, 1.0
	v_pk_mul_f32 v[20:21], v[14:15], v[18:19] op_sel_hi:[0,1]
	v_pk_mul_f32 v[14:15], v[14:15], v[16:17] op_sel_hi:[0,1]
	v_pk_mul_f32 v[18:19], v[4:5], v[14:15]
	v_pk_mul_f32 v[16:17], v[2:3], v[20:21]
	s_nop 1
	v_mov_b32_dpp v20, v16 quad_perm:[2,3,0,1] row_mask:0xf bank_mask:0xf
	v_mov_b32_dpp v21, v17 quad_perm:[2,3,0,1] row_mask:0xf bank_mask:0xf
	v_mov_b32_dpp v102, v18 quad_perm:[2,3,0,1] row_mask:0xf bank_mask:0xf
	v_mov_b32_dpp v103, v19 quad_perm:[2,3,0,1] row_mask:0xf bank_mask:0xf
	s_and_saveexec_b64 s[8:9], s[2:3]
	s_xor_b64 s[8:9], exec, s[8:9]
	s_cbranch_execz .LBB0_917
	s_and_saveexec_b64 s[18:19], s[4:5]
	s_cbranch_execz .LBB0_916
	v_pk_mul_f32 v[14:15], v[64:65], v[18:19]
	v_pk_mul_f32 v[12:13], v[12:13], v[16:17]
	s_waitcnt lgkmcnt(0)
	v_pk_fma_f32 v[18:19], v[68:69], v[102:103], v[14:15]
	v_pk_fma_f32 v[16:17], v[10:11], v[20:21], v[12:13]

; __device__ __forceinline__ void phase_qkpost(Frame& F, const Params& p, int j) {
;     ...
;         for (int r = 0; r < 4; ++r) {
;             const int row = row0 + r, pos = kind ? PASTLEN : pos0 + r;
;             f32x4 x[10];
; #pragma unroll
;             for (int c = 0; c < 10; ++c) x[c] = (f32x4){__uint_as_float(xr[r][c].x << 16), __uint_as_float(xr[r][c].x & 0xffff0000u), __uint_as_float(xr[r][c].y << 16), __uint_as_float(xr[r][c].y & 0xffff0000u)};
;             f32x4 cs, sn;
; #pragma unroll
;             for (int e = 0; e < 4; ++e) { const float ang = (float)pos * inv[e]; const double tr = (double)ang * 0.15915494309189535; const float rv = (float)(tr - __builtin_rint(tr));
;                 cs[e] = __builtin_amdgcn_cosf(rv); sn[e] = __builtin_amdgcn_sinf(rv); }
; #pragma unroll
;             for (int c = 0; c < 9; ++c) {
;                 f32x4 v = x[c];
;                 float ss = (v.x * v.x + v.y * v.y) + (v.z * v.z + v.w * v.w);
;                 ss += __shfl_xor(ss, 1); ss += __shfl_xor(ss, 2); ss += __shfl_xor(ss, 4); ss += __shfl_xor(ss, 8);
;                 v = v * (1.0f / sqrtf(ss * (1.0f / 64.0f) + EPS)) * (c < 8 ? qg : kg);
;                 f32x4 pr; pr.x = __shfl_xor(v.x, 2); pr.y = __shfl_xor(v.y, 2); pr.z = __shfl_xor(v.z, 2); pr.w = __shfl_xor(v.w, 2);
;                 if (li < 2) v = v * cs - pr * sn; else if (li < 4) v = v * cs + pr * sn;
.LBB0_935:
	s_add_i32 s26, s82, 1
	v_cvt_f32_u32_e32 v14, s26
	v_cndmask_b32_e64 v22, v218, v14, s[12:13]
	v_mul_f32_e32 v14, v39, v22
	v_cvt_f64_f32_e32 v[14:15], v14
	v_mul_f64 v[16:17], v[14:15], s[66:67]
	v_rndne_f64_e32 v[16:17], v[16:17]
	v_fma_f64 v[14:15], v[14:15], s[66:67], -v[16:17]
	v_cvt_f32_f64_e32 v14, v[14:15]
	v_mul_f32_e32 v15, v120, v22
	v_cvt_f64_f32_e32 v[18:19], v15
	s_waitcnt lgkmcnt(2)
	v_mul_f64 v[20:21], v[18:19], s[66:67]
	v_rndne_f64_e32 v[20:21], v[20:21]
	v_fma_f64 v[18:19], v[18:19], s[66:67], -v[20:21]
	v_cvt_f32_f64_e32 v15, v[18:19]
	v_mul_f32_e32 v18, v121, v22
	v_cvt_f64_f32_e32 v[18:19], v18
	v_mul_f64 v[20:21], v[18:19], s[66:67]
	v_rndne_f64_e32 v[20:21], v[20:21]
	v_fma_f64 v[18:19], v[18:19], s[66:67], -v[20:21]
	v_cvt_f32_f64_e32 v18, v[18:19]
	v_cos_f32_e32 v100, v18
	s_waitcnt lgkmcnt(1)
	v_sin_f32_e32 v102, v18
	v_mul_f32_e32 v18, v122, v22
	v_cvt_f64_f32_e32 v[18:19], v18
	v_mul_f64 v[20:21], v[18:19], s[66:67]
	v_rndne_f64_e32 v[20:21], v[20:21]
	v_fma_f64 v[18:19], v[18:19], s[66:67], -v[20:21]
	v_cvt_f32_f64_e32 v18, v[18:19]
	s_waitcnt vmcnt(29)
	v_and_b32_e32 v21, 0xffff0000, v99
	v_and_b32_e32 v20, 0xffff0000, v98
	v_cos_f32_e32 v101, v18
	s_waitcnt lgkmcnt(0)
	v_sin_f32_e32 v103, v18
	v_lshlrev_b32_e32 v19, 16, v99
	v_lshlrev_b32_e32 v18, 16, v98
	v_pk_mul_f32 v[22:23], v[20:21], v[20:21]
	v_cos_f32_e32 v16, v14
	v_pk_fma_f32 v[22:23], v[18:19], v[18:19], v[22:23]
	v_sin_f32_e32 v14, v14
	v_add_f32_e32 v22, v22, v23
	s_nop 1
	v_mov_b32_dpp v23, v22 quad_perm:[1,0,3,2] row_mask:0xf bank_mask:0xf
	v_cos_f32_e32 v17, v15
	v_sin_f32_e32 v15, v15
	s_waitcnt lgkmcnt(0)
	v_add_f32_e32 v22, v22, v23
	s_nop 1
	v_mov_b32_dpp v23, v22 quad_perm:[2,3,0,1] row_mask:0xf bank_mask:0xf
	s_waitcnt lgkmcnt(0)
	v_add_f32_e32 v22, v22, v23
	s_nop 1
	v_mov_b32_dpp v23, v22 row_half_mirror row_mask:0xf bank_mask:0xf
	s_waitcnt lgkmcnt(0)
	v_add_f32_e32 v22, v22, v23
	s_nop 1
	v_mov_b32_dpp v23, v22 row_mirror row_mask:0xf bank_mask:0xf
	s_waitcnt lgkmcnt(0)
	v_add_f32_e32 v22, v22, v23
	v_fmamk_f32 v22, v22, 0x3c800000, v204
	v_cmp_gt_f32_e32 vcc, s33, v22
	v_mul_f32_e32 v23, 0x4f800000, v22
	s_nop 0
	v_cndmask_b32_e32 v22, v22, v23, vcc
	v_sqrt_f32_e32 v23, v22
	s_nop 0
	v_add_u32_e32 v65, -1, v23
	v_fma_f32 v98, -v65, v23, v22
	v_cmp_ge_f32_e64 s[8:9], 0, v98
	v_add_u32_e32 v98, 1, v23
	s_nop 0
	v_cndmask_b32_e64 v65, v23, v65, s[8:9]
	v_fma_f32 v23, -v98, v23, v22
	v_cmp_lt_f32_e64 s[8:9], 0, v23
	s_nop 1
	v_cndmask_b32_e64 v23, v65, v98, s[8:9]
	v_mul_f32_e32 v65, 0x37800000, v23
	v_cndmask_b32_e32 v23, v23, v65, vcc
	v_cmp_class_f32_e32 vcc, v22, v205
	s_nop 1
	v_cndmask_b32_e32 v22, v23, v22, vcc
	v_div_scale_f32 v23, s[8:9], v22, v22, 1.0
	v_rcp_f32_e32 v65, v23
	s_nop 0
	v_fma_f32 v98, -v23, v65, 1.0
	v_fmac_f32_e32 v65, v98, v65
	v_div_scale_f32 v98, vcc, 1.0, v22, 1.0
	v_mul_f32_e32 v99, v98, v65
	v_fma_f32 v104, -v23, v99, v98
	v_fmac_f32_e32 v99, v104, v65
	v_fma_f32 v23, -v23, v99, v98
	v_div_fmas_f32 v23, v23, v65, v99
	v_div_fixup_f32 v22, v23, v22, 1.0
	v_mov_b32_e32 v98, v18
	v_mov_b32_e32 v99, v20
	v_mov_b32_e32 v20, v19
	v_pk_mul_f32 v[104:105], v[22:23], v[98:99] op_sel_hi:[0,1]
	v_pk_mul_f32 v[18:19], v[22:23], v[20:21] op_sel_hi:[0,1]
	v_pk_mul_f32 v[98:99], v[8:9], v[18:19]
	v_pk_mul_f32 v[22:23], v[6:7], v[104:105]
	s_nop 1
	v_mov_b32_dpp v18, v22 quad_perm:[2,3,0,1] row_mask:0xf bank_mask:0xf
	v_mov_b32_dpp v19, v23 quad_perm:[2,3,0,1] row_mask:0xf bank_mask:0xf
	v_mov_b32_dpp v104, v98 quad_perm:[2,3,0,1] row_mask:0xf bank_mask:0xf
	v_mov_b32_dpp v105, v99 quad_perm:[2,3,0,1] row_mask:0xf bank_mask:0xf
	s_and_saveexec_b64 s[8:9], s[2:3]
	s_xor_b64 s[8:9], exec, s[8:9]
	s_cbranch_execz .LBB0_939
	s_and_saveexec_b64 s[28:29], s[4:5]
	s_cbranch_execz .LBB0_938
	v_pk_mul_f32 v[20:21], v[100:101], v[98:99]
	v_pk_mul_f32 v[22:23], v[16:17], v[22:23]
	s_waitcnt lgkmcnt(0)
	v_pk_fma_f32 v[98:99], v[102:103], v[104:105], v[20:21]
	v_pk_fma_f32 v[22:23], v[14:15], v[18:19], v[22:23]

; __device__ __forceinline__ void phase_qkpost(Frame& F, const Params& p, int j) {
;     ...
;             for (int c = 0; c < 9; ++c) {
;                 f32x4 v = x[c];
;                 float ss = (v.x * v.x + v.y * v.y) + (v.z * v.z + v.w * v.w);
;                 ss += __shfl_xor(ss, 1); ss += __shfl_xor(ss, 2); ss += __shfl_xor(ss, 4); ss += __shfl_xor(ss, 8);
;                 v = v * (1.0f / sqrtf(ss * (1.0f / 64.0f) + EPS)) * (c < 8 ? qg : kg);
;                 f32x4 pr; pr.x = __shfl_xor(v.x, 2); pr.y = __shfl_xor(v.y, 2); pr.z = __shfl_xor(v.z, 2); pr.w = __shfl_xor(v.w, 2);
;                 if (li < 2) v = v * cs - pr * sn; else if (li < 4) v = v * cs + pr * sn;
.LBB0_945:
	s_waitcnt vmcnt(28)
	v_and_b32_e32 v21, 0xffff0000, v97
	v_and_b32_e32 v20, 0xffff0000, v96
	v_lshlrev_b32_e32 v19, 16, v97
	v_lshlrev_b32_e32 v18, 16, v96
	v_pk_mul_f32 v[96:97], v[20:21], v[20:21]
	s_nop 0
	v_pk_fma_f32 v[96:97], v[18:19], v[18:19], v[96:97]
	s_nop 0
	v_add_f32_e32 v65, v96, v97
	s_nop 1
	v_mov_b32_dpp v96, v65 quad_perm:[1,0,3,2] row_mask:0xf bank_mask:0xf
	v_mov_b32_e32 v97, v20
	s_waitcnt lgkmcnt(0)
	v_add_f32_e32 v65, v65, v96
	s_nop 1
	v_mov_b32_dpp v96, v65 quad_perm:[2,3,0,1] row_mask:0xf bank_mask:0xf
	s_waitcnt lgkmcnt(0)
	v_add_f32_e32 v65, v65, v96
	s_nop 1
	v_mov_b32_dpp v96, v65 row_half_mirror row_mask:0xf bank_mask:0xf
	s_waitcnt lgkmcnt(0)
	v_add_f32_e32 v65, v65, v96
	s_nop 1
	v_mov_b32_dpp v96, v65 row_mirror row_mask:0xf bank_mask:0xf
	s_waitcnt lgkmcnt(0)
	v_add_f32_e32 v65, v65, v96
	v_fmamk_f32 v65, v65, 0x3c800000, v204
	v_mul_f32_e32 v96, 0x4f800000, v65
	v_cmp_gt_f32_e32 vcc, s33, v65
	s_nop 1
	v_cndmask_b32_e32 v65, v65, v96, vcc
	v_sqrt_f32_e32 v104, v65
	v_mov_b32_e32 v96, v18
	v_add_u32_e32 v18, -1, v104
	v_add_u32_e32 v20, 1, v104
	v_fma_f32 v105, -v18, v104, v65
	v_fma_f32 v106, -v20, v104, v65
	v_cmp_ge_f32_e64 s[8:9], 0, v105
	s_nop 1
	v_cndmask_b32_e64 v18, v104, v18, s[8:9]
	v_cmp_lt_f32_e64 s[8:9], 0, v106
	s_nop 1
	v_cndmask_b32_e64 v18, v18, v20, s[8:9]
	v_mul_f32_e32 v20, 0x37800000, v18
	v_cndmask_b32_e32 v18, v18, v20, vcc
	v_cmp_class_f32_e32 vcc, v65, v205
	v_mov_b32_e32 v20, v19
	s_nop 0
	v_cndmask_b32_e32 v18, v18, v65, vcc
	v_div_scale_f32 v65, s[8:9], v18, v18, 1.0
	v_rcp_f32_e32 v104, v65
	v_div_scale_f32 v19, vcc, 1.0, v18, 1.0
	v_fma_f32 v105, -v65, v104, 1.0
	v_fmac_f32_e32 v104, v105, v104
	v_mul_f32_e32 v105, v19, v104
	v_fma_f32 v106, -v65, v105, v19
	v_fmac_f32_e32 v105, v106, v104
	v_fma_f32 v19, -v65, v105, v19
	v_div_fmas_f32 v19, v19, v104, v105
	v_div_fixup_f32 v18, v19, v18, 1.0
	v_pk_mul_f32 v[96:97], v[18:19], v[96:97] op_sel_hi:[0,1]
	v_pk_mul_f32 v[18:19], v[18:19], v[20:21] op_sel_hi:[0,1]
	v_pk_mul_f32 v[104:105], v[8:9], v[18:19]
	v_pk_mul_f32 v[96:97], v[6:7], v[96:97]
	s_nop 1
	v_mov_b32_dpp v18, v96 quad_perm:[2,3,0,1] row_mask:0xf bank_mask:0xf
	v_mov_b32_dpp v19, v97 quad_perm:[2,3,0,1] row_mask:0xf bank_mask:0xf
	v_mov_b32_dpp v106, v104 quad_perm:[2,3,0,1] row_mask:0xf bank_mask:0xf
	v_mov_b32_dpp v107, v105 quad_perm:[2,3,0,1] row_mask:0xf bank_mask:0xf
	s_and_saveexec_b64 s[8:9], s[2:3]
	s_xor_b64 s[8:9], exec, s[8:9]
	s_cbranch_execz .LBB0_949
	s_and_saveexec_b64 s[24:25], s[4:5]
	s_cbranch_execz .LBB0_948
	v_pk_mul_f32 v[20:21], v[100:101], v[104:105]
	v_pk_mul_f32 v[96:97], v[16:17], v[96:97]
	s_waitcnt lgkmcnt(0)
	v_pk_fma_f32 v[104:105], v[102:103], v[106:107], v[20:21]
	v_pk_fma_f32 v[96:97], v[14:15], v[18:19], v[96:97]

; __device__ __forceinline__ void phase_qkpost(Frame& F, const Params& p, int j) {
;     ...
;             for (int c = 0; c < 9; ++c) {
;                 f32x4 v = x[c];
;                 float ss = (v.x * v.x + v.y * v.y) + (v.z * v.z + v.w * v.w);
;                 ss += __shfl_xor(ss, 1); ss += __shfl_xor(ss, 2); ss += __shfl_xor(ss, 4); ss += __shfl_xor(ss, 8);
;                 v = v * (1.0f / sqrtf(ss * (1.0f / 64.0f) + EPS)) * (c < 8 ? qg : kg);
;                 f32x4 pr; pr.x = __shfl_xor(v.x, 2); pr.y = __shfl_xor(v.y, 2); pr.z = __shfl_xor(v.z, 2); pr.w = __shfl_xor(v.w, 2);
;                 if (li < 2) v = v * cs - pr * sn; else if (li < 4) v = v * cs + pr * sn;
.LBB0_955:
	s_waitcnt vmcnt(27)
	v_and_b32_e32 v21, 0xffff0000, v95
	v_and_b32_e32 v20, 0xffff0000, v94
	v_lshlrev_b32_e32 v19, 16, v95
	v_lshlrev_b32_e32 v18, 16, v94
	v_pk_mul_f32 v[94:95], v[20:21], v[20:21]
	s_nop 0
	v_pk_fma_f32 v[94:95], v[18:19], v[18:19], v[94:95]
	s_nop 0
	v_add_f32_e32 v65, v94, v95
	s_nop 1
	v_mov_b32_dpp v94, v65 quad_perm:[1,0,3,2] row_mask:0xf bank_mask:0xf
	v_mov_b32_e32 v95, v20
	s_waitcnt lgkmcnt(0)
	v_add_f32_e32 v65, v65, v94
	s_nop 1
	v_mov_b32_dpp v94, v65 quad_perm:[2,3,0,1] row_mask:0xf bank_mask:0xf
	s_waitcnt lgkmcnt(0)
	v_add_f32_e32 v65, v65, v94
	s_nop 1
	v_mov_b32_dpp v94, v65 row_half_mirror row_mask:0xf bank_mask:0xf
	s_waitcnt lgkmcnt(0)
	v_add_f32_e32 v65, v65, v94
	s_nop 1
	v_mov_b32_dpp v94, v65 row_mirror row_mask:0xf bank_mask:0xf
	s_waitcnt lgkmcnt(0)
	v_add_f32_e32 v65, v65, v94
	v_fmamk_f32 v65, v65, 0x3c800000, v204
	v_mul_f32_e32 v94, 0x4f800000, v65
	v_cmp_gt_f32_e32 vcc, s33, v65
	s_nop 1
	v_cndmask_b32_e32 v65, v65, v94, vcc
	v_sqrt_f32_e32 v96, v65
	v_mov_b32_e32 v94, v18
	v_add_u32_e32 v18, -1, v96
	v_add_u32_e32 v20, 1, v96
	v_fma_f32 v97, -v18, v96, v65
	v_fma_f32 v104, -v20, v96, v65
	v_cmp_ge_f32_e64 s[8:9], 0, v97
	s_nop 1
	v_cndmask_b32_e64 v18, v96, v18, s[8:9]
	v_cmp_lt_f32_e64 s[8:9], 0, v104
	s_nop 1
	v_cndmask_b32_e64 v18, v18, v20, s[8:9]
	v_mul_f32_e32 v20, 0x37800000, v18
	v_cndmask_b32_e32 v18, v18, v20, vcc
	v_cmp_class_f32_e32 vcc, v65, v205
	v_mov_b32_e32 v20, v19
	s_nop 0
	v_cndmask_b32_e32 v18, v18, v65, vcc
	v_div_scale_f32 v65, s[8:9], v18, v18, 1.0
	v_rcp_f32_e32 v96, v65
	v_div_scale_f32 v19, vcc, 1.0, v18, 1.0
	v_fma_f32 v97, -v65, v96, 1.0
	v_fmac_f32_e32 v96, v97, v96
	v_mul_f32_e32 v97, v19, v96
	v_fma_f32 v104, -v65, v97, v19
	v_fmac_f32_e32 v97, v104, v96
	v_fma_f32 v19, -v65, v97, v19
	v_div_fmas_f32 v19, v19, v96, v97
	v_div_fixup_f32 v18, v19, v18, 1.0
	v_pk_mul_f32 v[94:95], v[18:19], v[94:95] op_sel_hi:[0,1]
	v_pk_mul_f32 v[18:19], v[18:19], v[20:21] op_sel_hi:[0,1]
	v_pk_mul_f32 v[96:97], v[8:9], v[18:19]
	v_pk_mul_f32 v[94:95], v[6:7], v[94:95]
	s_nop 1
	v_mov_b32_dpp v18, v94 quad_perm:[2,3,0,1] row_mask:0xf bank_mask:0xf
	v_mov_b32_dpp v19, v95 quad_perm:[2,3,0,1] row_mask:0xf bank_mask:0xf
	v_mov_b32_dpp v104, v96 quad_perm:[2,3,0,1] row_mask:0xf bank_mask:0xf
	v_mov_b32_dpp v105, v97 quad_perm:[2,3,0,1] row_mask:0xf bank_mask:0xf
	s_and_saveexec_b64 s[8:9], s[2:3]
	s_xor_b64 s[8:9], exec, s[8:9]
	s_cbranch_execz .LBB0_959
	s_and_saveexec_b64 s[24:25], s[4:5]
	s_cbranch_execz .LBB0_958
	v_pk_mul_f32 v[20:21], v[100:101], v[96:97]
	v_pk_mul_f32 v[94:95], v[16:17], v[94:95]
	s_waitcnt lgkmcnt(0)
	v_pk_fma_f32 v[96:97], v[102:103], v[104:105], v[20:21]
	v_pk_fma_f32 v[94:95], v[14:15], v[18:19], v[94:95]

; __device__ __forceinline__ void phase_qkpost(Frame& F, const Params& p, int j) {
;     ...
;             for (int c = 0; c < 9; ++c) {
;                 f32x4 v = x[c];
;                 float ss = (v.x * v.x + v.y * v.y) + (v.z * v.z + v.w * v.w);
;                 ss += __shfl_xor(ss, 1); ss += __shfl_xor(ss, 2); ss += __shfl_xor(ss, 4); ss += __shfl_xor(ss, 8);
;                 v = v * (1.0f / sqrtf(ss * (1.0f / 64.0f) + EPS)) * (c < 8 ? qg : kg);
;                 f32x4 pr; pr.x = __shfl_xor(v.x, 2); pr.y = __shfl_xor(v.y, 2); pr.z = __shfl_xor(v.z, 2); pr.w = __shfl_xor(v.w, 2);
;                 if (li < 2) v = v * cs - pr * sn; else if (li < 4) v = v * cs + pr * sn;
.LBB0_965:
	s_waitcnt vmcnt(26)
	v_and_b32_e32 v21, 0xffff0000, v93
	v_and_b32_e32 v20, 0xffff0000, v92
	v_lshlrev_b32_e32 v19, 16, v93
	v_lshlrev_b32_e32 v18, 16, v92
	v_pk_mul_f32 v[92:93], v[20:21], v[20:21]
	s_nop 0
	v_pk_fma_f32 v[92:93], v[18:19], v[18:19], v[92:93]
	s_nop 0
	v_add_f32_e32 v65, v92, v93
	s_nop 1
	v_mov_b32_dpp v92, v65 quad_perm:[1,0,3,2] row_mask:0xf bank_mask:0xf
	v_mov_b32_e32 v93, v20
	s_waitcnt lgkmcnt(0)
	v_add_f32_e32 v65, v65, v92
	s_nop 1
	v_mov_b32_dpp v92, v65 quad_perm:[2,3,0,1] row_mask:0xf bank_mask:0xf
	s_waitcnt lgkmcnt(0)
	v_add_f32_e32 v65, v65, v92
	s_nop 1
	v_mov_b32_dpp v92, v65 row_half_mirror row_mask:0xf bank_mask:0xf
	s_waitcnt lgkmcnt(0)
	v_add_f32_e32 v65, v65, v92
	s_nop 1
	v_mov_b32_dpp v92, v65 row_mirror row_mask:0xf bank_mask:0xf
	s_waitcnt lgkmcnt(0)
	v_add_f32_e32 v65, v65, v92
	v_fmamk_f32 v65, v65, 0x3c800000, v204
	v_mul_f32_e32 v92, 0x4f800000, v65
	v_cmp_gt_f32_e32 vcc, s33, v65
	s_nop 1
	v_cndmask_b32_e32 v65, v65, v92, vcc
	v_sqrt_f32_e32 v94, v65
	v_mov_b32_e32 v92, v18
	v_add_u32_e32 v18, -1, v94
	v_add_u32_e32 v20, 1, v94
	v_fma_f32 v95, -v18, v94, v65
	v_fma_f32 v96, -v20, v94, v65
	v_cmp_ge_f32_e64 s[8:9], 0, v95
	s_nop 1
	v_cndmask_b32_e64 v18, v94, v18, s[8:9]
	v_cmp_lt_f32_e64 s[8:9], 0, v96
	s_nop 1
	v_cndmask_b32_e64 v18, v18, v20, s[8:9]
	v_mul_f32_e32 v20, 0x37800000, v18
	v_cndmask_b32_e32 v18, v18, v20, vcc
	v_cmp_class_f32_e32 vcc, v65, v205
	v_mov_b32_e32 v20, v19
	s_nop 0
	v_cndmask_b32_e32 v18, v18, v65, vcc
	v_div_scale_f32 v65, s[8:9], v18, v18, 1.0
	v_rcp_f32_e32 v94, v65
	v_div_scale_f32 v19, vcc, 1.0, v18, 1.0
	v_fma_f32 v95, -v65, v94, 1.0
	v_fmac_f32_e32 v94, v95, v94
	v_mul_f32_e32 v95, v19, v94
	v_fma_f32 v96, -v65, v95, v19
	v_fmac_f32_e32 v95, v96, v94
	v_fma_f32 v19, -v65, v95, v19
	v_div_fmas_f32 v19, v19, v94, v95
	v_div_fixup_f32 v18, v19, v18, 1.0
	v_pk_mul_f32 v[92:93], v[18:19], v[92:93] op_sel_hi:[0,1]
	v_pk_mul_f32 v[18:19], v[18:19], v[20:21] op_sel_hi:[0,1]
	v_pk_mul_f32 v[94:95], v[8:9], v[18:19]
	v_pk_mul_f32 v[92:93], v[6:7], v[92:93]
	s_nop 1
	v_mov_b32_dpp v18, v92 quad_perm:[2,3,0,1] row_mask:0xf bank_mask:0xf
	v_mov_b32_dpp v19, v93 quad_perm:[2,3,0,1] row_mask:0xf bank_mask:0xf
	v_mov_b32_dpp v96, v94 quad_perm:[2,3,0,1] row_mask:0xf bank_mask:0xf
	v_mov_b32_dpp v97, v95 quad_perm:[2,3,0,1] row_mask:0xf bank_mask:0xf
	s_and_saveexec_b64 s[8:9], s[2:3]
	s_xor_b64 s[8:9], exec, s[8:9]
	s_cbranch_execz .LBB0_969
	s_and_saveexec_b64 s[24:25], s[4:5]
	s_cbranch_execz .LBB0_968
	v_pk_mul_f32 v[20:21], v[100:101], v[94:95]
	v_pk_mul_f32 v[92:93], v[16:17], v[92:93]
	s_waitcnt lgkmcnt(0)
	v_pk_fma_f32 v[94:95], v[102:103], v[96:97], v[20:21]
	v_pk_fma_f32 v[92:93], v[14:15], v[18:19], v[92:93]

; __device__ __forceinline__ void phase_qkpost(Frame& F, const Params& p, int j) {
;     ...
;             for (int c = 0; c < 9; ++c) {
;                 f32x4 v = x[c];
;                 float ss = (v.x * v.x + v.y * v.y) + (v.z * v.z + v.w * v.w);
;                 ss += __shfl_xor(ss, 1); ss += __shfl_xor(ss, 2); ss += __shfl_xor(ss, 4); ss += __shfl_xor(ss, 8);
;                 v = v * (1.0f / sqrtf(ss * (1.0f / 64.0f) + EPS)) * (c < 8 ? qg : kg);
;                 f32x4 pr; pr.x = __shfl_xor(v.x, 2); pr.y = __shfl_xor(v.y, 2); pr.z = __shfl_xor(v.z, 2); pr.w = __shfl_xor(v.w, 2);
;                 if (li < 2) v = v * cs - pr * sn; else if (li < 4) v = v * cs + pr * sn;
.LBB0_975:
	s_waitcnt vmcnt(25)
	v_and_b32_e32 v21, 0xffff0000, v91
	v_and_b32_e32 v20, 0xffff0000, v90
	v_lshlrev_b32_e32 v19, 16, v91
	v_lshlrev_b32_e32 v18, 16, v90
	v_pk_mul_f32 v[90:91], v[20:21], v[20:21]
	s_nop 0
	v_pk_fma_f32 v[90:91], v[18:19], v[18:19], v[90:91]
	s_nop 0
	v_add_f32_e32 v65, v90, v91
	s_nop 1
	v_mov_b32_dpp v90, v65 quad_perm:[1,0,3,2] row_mask:0xf bank_mask:0xf
	v_mov_b32_e32 v91, v20
	s_waitcnt lgkmcnt(0)
	v_add_f32_e32 v65, v65, v90
	s_nop 1
	v_mov_b32_dpp v90, v65 quad_perm:[2,3,0,1] row_mask:0xf bank_mask:0xf
	s_waitcnt lgkmcnt(0)
	v_add_f32_e32 v65, v65, v90
	s_nop 1
	v_mov_b32_dpp v90, v65 row_half_mirror row_mask:0xf bank_mask:0xf
	s_waitcnt lgkmcnt(0)
	v_add_f32_e32 v65, v65, v90
	s_nop 1
	v_mov_b32_dpp v90, v65 row_mirror row_mask:0xf bank_mask:0xf
	s_waitcnt lgkmcnt(0)
	v_add_f32_e32 v65, v65, v90
	v_fmamk_f32 v65, v65, 0x3c800000, v204
	v_mul_f32_e32 v90, 0x4f800000, v65
	v_cmp_gt_f32_e32 vcc, s33, v65
	s_nop 1
	v_cndmask_b32_e32 v65, v65, v90, vcc
	v_sqrt_f32_e32 v92, v65
	v_mov_b32_e32 v90, v18
	v_add_u32_e32 v18, -1, v92
	v_add_u32_e32 v20, 1, v92
	v_fma_f32 v93, -v18, v92, v65
	v_fma_f32 v94, -v20, v92, v65
	v_cmp_ge_f32_e64 s[8:9], 0, v93
	s_nop 1
	v_cndmask_b32_e64 v18, v92, v18, s[8:9]
	v_cmp_lt_f32_e64 s[8:9], 0, v94
	s_nop 1
	v_cndmask_b32_e64 v18, v18, v20, s[8:9]
	v_mul_f32_e32 v20, 0x37800000, v18
	v_cndmask_b32_e32 v18, v18, v20, vcc
	v_cmp_class_f32_e32 vcc, v65, v205
	v_mov_b32_e32 v20, v19
	s_nop 0
	v_cndmask_b32_e32 v18, v18, v65, vcc
	v_div_scale_f32 v65, s[8:9], v18, v18, 1.0
	v_rcp_f32_e32 v92, v65
	v_div_scale_f32 v19, vcc, 1.0, v18, 1.0
	v_fma_f32 v93, -v65, v92, 1.0
	v_fmac_f32_e32 v92, v93, v92
	v_mul_f32_e32 v93, v19, v92
	v_fma_f32 v94, -v65, v93, v19
	v_fmac_f32_e32 v93, v94, v92
	v_fma_f32 v19, -v65, v93, v19
	v_div_fmas_f32 v19, v19, v92, v93
	v_div_fixup_f32 v18, v19, v18, 1.0
	v_pk_mul_f32 v[90:91], v[18:19], v[90:91] op_sel_hi:[0,1]
	v_pk_mul_f32 v[18:19], v[18:19], v[20:21] op_sel_hi:[0,1]
	v_pk_mul_f32 v[92:93], v[8:9], v[18:19]
	v_pk_mul_f32 v[90:91], v[6:7], v[90:91]
	s_nop 1
	v_mov_b32_dpp v18, v90 quad_perm:[2,3,0,1] row_mask:0xf bank_mask:0xf
	v_mov_b32_dpp v19, v91 quad_perm:[2,3,0,1] row_mask:0xf bank_mask:0xf
	v_mov_b32_dpp v94, v92 quad_perm:[2,3,0,1] row_mask:0xf bank_mask:0xf
	v_mov_b32_dpp v95, v93 quad_perm:[2,3,0,1] row_mask:0xf bank_mask:0xf
	s_and_saveexec_b64 s[8:9], s[2:3]
	s_xor_b64 s[8:9], exec, s[8:9]
	s_cbranch_execz .LBB0_979
	s_and_saveexec_b64 s[24:25], s[4:5]
	s_cbranch_execz .LBB0_978
	v_pk_mul_f32 v[20:21], v[100:101], v[92:93]
	v_pk_mul_f32 v[90:91], v[16:17], v[90:91]
	s_waitcnt lgkmcnt(0)
	v_pk_fma_f32 v[92:93], v[102:103], v[94:95], v[20:21]
	v_pk_fma_f32 v[90:91], v[14:15], v[18:19], v[90:91]

; __device__ __forceinline__ void phase_qkpost(Frame& F, const Params& p, int j) {
;     ...
;             for (int c = 0; c < 9; ++c) {
;                 f32x4 v = x[c];
;                 float ss = (v.x * v.x + v.y * v.y) + (v.z * v.z + v.w * v.w);
;                 ss += __shfl_xor(ss, 1); ss += __shfl_xor(ss, 2); ss += __shfl_xor(ss, 4); ss += __shfl_xor(ss, 8);
;                 v = v * (1.0f / sqrtf(ss * (1.0f / 64.0f) + EPS)) * (c < 8 ? qg : kg);
;                 f32x4 pr; pr.x = __shfl_xor(v.x, 2); pr.y = __shfl_xor(v.y, 2); pr.z = __shfl_xor(v.z, 2); pr.w = __shfl_xor(v.w, 2);
;                 if (li < 2) v = v * cs - pr * sn; else if (li < 4) v = v * cs + pr * sn;
.LBB0_985:
	s_waitcnt vmcnt(24)
	v_and_b32_e32 v21, 0xffff0000, v89
	v_and_b32_e32 v20, 0xffff0000, v88
	v_lshlrev_b32_e32 v19, 16, v89
	v_lshlrev_b32_e32 v18, 16, v88
	v_pk_mul_f32 v[88:89], v[20:21], v[20:21]
	s_nop 0
	v_pk_fma_f32 v[88:89], v[18:19], v[18:19], v[88:89]
	s_nop 0
	v_add_f32_e32 v65, v88, v89
	s_nop 1
	v_mov_b32_dpp v88, v65 quad_perm:[1,0,3,2] row_mask:0xf bank_mask:0xf
	v_mov_b32_e32 v89, v20
	s_waitcnt lgkmcnt(0)
	v_add_f32_e32 v65, v65, v88
	s_nop 1
	v_mov_b32_dpp v88, v65 quad_perm:[2,3,0,1] row_mask:0xf bank_mask:0xf
	s_waitcnt lgkmcnt(0)
	v_add_f32_e32 v65, v65, v88
	s_nop 1
	v_mov_b32_dpp v88, v65 row_half_mirror row_mask:0xf bank_mask:0xf
	s_waitcnt lgkmcnt(0)
	v_add_f32_e32 v65, v65, v88
	s_nop 1
	v_mov_b32_dpp v88, v65 row_mirror row_mask:0xf bank_mask:0xf
	s_waitcnt lgkmcnt(0)
	v_add_f32_e32 v65, v65, v88
	v_fmamk_f32 v65, v65, 0x3c800000, v204
	v_mul_f32_e32 v88, 0x4f800000, v65
	v_cmp_gt_f32_e32 vcc, s33, v65
	s_nop 1
	v_cndmask_b32_e32 v65, v65, v88, vcc
	v_sqrt_f32_e32 v90, v65
	v_mov_b32_e32 v88, v18
	v_add_u32_e32 v18, -1, v90
	v_add_u32_e32 v20, 1, v90
	v_fma_f32 v91, -v18, v90, v65
	v_fma_f32 v92, -v20, v90, v65
	v_cmp_ge_f32_e64 s[8:9], 0, v91
	s_nop 1
	v_cndmask_b32_e64 v18, v90, v18, s[8:9]
	v_cmp_lt_f32_e64 s[8:9], 0, v92
	s_nop 1
	v_cndmask_b32_e64 v18, v18, v20, s[8:9]
	v_mul_f32_e32 v20, 0x37800000, v18
	v_cndmask_b32_e32 v18, v18, v20, vcc
	v_cmp_class_f32_e32 vcc, v65, v205
	v_mov_b32_e32 v20, v19
	s_nop 0
	v_cndmask_b32_e32 v18, v18, v65, vcc
	v_div_scale_f32 v65, s[8:9], v18, v18, 1.0
	v_rcp_f32_e32 v90, v65
	v_div_scale_f32 v19, vcc, 1.0, v18, 1.0
	v_fma_f32 v91, -v65, v90, 1.0
	v_fmac_f32_e32 v90, v91, v90
	v_mul_f32_e32 v91, v19, v90
	v_fma_f32 v92, -v65, v91, v19
	v_fmac_f32_e32 v91, v92, v90
	v_fma_f32 v19, -v65, v91, v19
	v_div_fmas_f32 v19, v19, v90, v91
	v_div_fixup_f32 v18, v19, v18, 1.0
	v_pk_mul_f32 v[88:89], v[18:19], v[88:89] op_sel_hi:[0,1]
	v_pk_mul_f32 v[18:19], v[18:19], v[20:21] op_sel_hi:[0,1]
	v_pk_mul_f32 v[90:91], v[8:9], v[18:19]
	v_pk_mul_f32 v[88:89], v[6:7], v[88:89]
	s_nop 1
	v_mov_b32_dpp v18, v88 quad_perm:[2,3,0,1] row_mask:0xf bank_mask:0xf
	v_mov_b32_dpp v19, v89 quad_perm:[2,3,0,1] row_mask:0xf bank_mask:0xf
	v_mov_b32_dpp v92, v90 quad_perm:[2,3,0,1] row_mask:0xf bank_mask:0xf
	v_mov_b32_dpp v93, v91 quad_perm:[2,3,0,1] row_mask:0xf bank_mask:0xf
	s_and_saveexec_b64 s[8:9], s[2:3]
	s_xor_b64 s[8:9], exec, s[8:9]
	s_cbranch_execz .LBB0_989
	s_and_saveexec_b64 s[24:25], s[4:5]
	s_cbranch_execz .LBB0_988
	v_pk_mul_f32 v[20:21], v[100:101], v[90:91]
	v_pk_mul_f32 v[88:89], v[16:17], v[88:89]
	s_waitcnt lgkmcnt(0)
	v_pk_fma_f32 v[90:91], v[102:103], v[92:93], v[20:21]
	v_pk_fma_f32 v[88:89], v[14:15], v[18:19], v[88:89]

; __device__ __forceinline__ void phase_qkpost(Frame& F, const Params& p, int j) {
;     ...
;             for (int c = 0; c < 9; ++c) {
;                 f32x4 v = x[c];
;                 float ss = (v.x * v.x + v.y * v.y) + (v.z * v.z + v.w * v.w);
;                 ss += __shfl_xor(ss, 1); ss += __shfl_xor(ss, 2); ss += __shfl_xor(ss, 4); ss += __shfl_xor(ss, 8);
;                 v = v * (1.0f / sqrtf(ss * (1.0f / 64.0f) + EPS)) * (c < 8 ? qg : kg);
;                 f32x4 pr; pr.x = __shfl_xor(v.x, 2); pr.y = __shfl_xor(v.y, 2); pr.z = __shfl_xor(v.z, 2); pr.w = __shfl_xor(v.w, 2);
;                 if (li < 2) v = v * cs - pr * sn; else if (li < 4) v = v * cs + pr * sn;
.LBB0_995:
	s_waitcnt vmcnt(23)
	v_and_b32_e32 v21, 0xffff0000, v87
	v_and_b32_e32 v20, 0xffff0000, v86
	v_lshlrev_b32_e32 v19, 16, v87
	v_lshlrev_b32_e32 v18, 16, v86
	v_pk_mul_f32 v[86:87], v[20:21], v[20:21]
	s_nop 0
	v_pk_fma_f32 v[86:87], v[18:19], v[18:19], v[86:87]
	s_nop 0
	v_add_f32_e32 v65, v86, v87
	s_nop 1
	v_mov_b32_dpp v86, v65 quad_perm:[1,0,3,2] row_mask:0xf bank_mask:0xf
	v_mov_b32_e32 v87, v20
	s_waitcnt lgkmcnt(0)
	v_add_f32_e32 v65, v65, v86
	s_nop 1
	v_mov_b32_dpp v86, v65 quad_perm:[2,3,0,1] row_mask:0xf bank_mask:0xf
	s_waitcnt lgkmcnt(0)
	v_add_f32_e32 v65, v65, v86
	s_nop 1
	v_mov_b32_dpp v86, v65 row_half_mirror row_mask:0xf bank_mask:0xf
	s_waitcnt lgkmcnt(0)
	v_add_f32_e32 v65, v65, v86
	s_nop 1
	v_mov_b32_dpp v86, v65 row_mirror row_mask:0xf bank_mask:0xf
	s_waitcnt lgkmcnt(0)
	v_add_f32_e32 v65, v65, v86
	v_fmamk_f32 v65, v65, 0x3c800000, v204
	v_mul_f32_e32 v86, 0x4f800000, v65
	v_cmp_gt_f32_e32 vcc, s33, v65
	s_nop 1
	v_cndmask_b32_e32 v65, v65, v86, vcc
	v_sqrt_f32_e32 v88, v65
	v_mov_b32_e32 v86, v18
	v_add_u32_e32 v18, -1, v88
	v_add_u32_e32 v20, 1, v88
	v_fma_f32 v89, -v18, v88, v65
	v_fma_f32 v90, -v20, v88, v65
	v_cmp_ge_f32_e64 s[8:9], 0, v89
	s_nop 1
	v_cndmask_b32_e64 v18, v88, v18, s[8:9]
	v_cmp_lt_f32_e64 s[8:9], 0, v90
	s_nop 1
	v_cndmask_b32_e64 v18, v18, v20, s[8:9]
	v_mul_f32_e32 v20, 0x37800000, v18
	v_cndmask_b32_e32 v18, v18, v20, vcc
	v_cmp_class_f32_e32 vcc, v65, v205
	v_mov_b32_e32 v20, v19
	s_nop 0
	v_cndmask_b32_e32 v18, v18, v65, vcc
	v_div_scale_f32 v65, s[8:9], v18, v18, 1.0
	v_rcp_f32_e32 v88, v65
	v_div_scale_f32 v19, vcc, 1.0, v18, 1.0
	v_fma_f32 v89, -v65, v88, 1.0
	v_fmac_f32_e32 v88, v89, v88
	v_mul_f32_e32 v89, v19, v88
	v_fma_f32 v90, -v65, v89, v19
	v_fmac_f32_e32 v89, v90, v88
	v_fma_f32 v19, -v65, v89, v19
	v_div_fmas_f32 v19, v19, v88, v89
	v_div_fixup_f32 v18, v19, v18, 1.0
	v_pk_mul_f32 v[86:87], v[18:19], v[86:87] op_sel_hi:[0,1]
	v_pk_mul_f32 v[18:19], v[18:19], v[20:21] op_sel_hi:[0,1]
	v_pk_mul_f32 v[88:89], v[8:9], v[18:19]
	v_pk_mul_f32 v[86:87], v[6:7], v[86:87]
	s_nop 1
	v_mov_b32_dpp v18, v86 quad_perm:[2,3,0,1] row_mask:0xf bank_mask:0xf
	v_mov_b32_dpp v19, v87 quad_perm:[2,3,0,1] row_mask:0xf bank_mask:0xf
	v_mov_b32_dpp v90, v88 quad_perm:[2,3,0,1] row_mask:0xf bank_mask:0xf
	v_mov_b32_dpp v91, v89 quad_perm:[2,3,0,1] row_mask:0xf bank_mask:0xf
	s_and_saveexec_b64 s[8:9], s[2:3]
	s_xor_b64 s[8:9], exec, s[8:9]
	s_cbranch_execz .LBB0_999
	s_and_saveexec_b64 s[24:25], s[4:5]
	s_cbranch_execz .LBB0_998
	v_pk_mul_f32 v[20:21], v[100:101], v[88:89]
	v_pk_mul_f32 v[86:87], v[16:17], v[86:87]
	s_waitcnt lgkmcnt(0)
	v_pk_fma_f32 v[88:89], v[102:103], v[90:91], v[20:21]
	v_pk_fma_f32 v[86:87], v[14:15], v[18:19], v[86:87]

; __device__ __forceinline__ void phase_qkpost(Frame& F, const Params& p, int j) {
;     ...
;             for (int c = 0; c < 9; ++c) {
;                 f32x4 v = x[c];
;                 float ss = (v.x * v.x + v.y * v.y) + (v.z * v.z + v.w * v.w);
;                 ss += __shfl_xor(ss, 1); ss += __shfl_xor(ss, 2); ss += __shfl_xor(ss, 4); ss += __shfl_xor(ss, 8);
;                 v = v * (1.0f / sqrtf(ss * (1.0f / 64.0f) + EPS)) * (c < 8 ? qg : kg);
;                 f32x4 pr; pr.x = __shfl_xor(v.x, 2); pr.y = __shfl_xor(v.y, 2); pr.z = __shfl_xor(v.z, 2); pr.w = __shfl_xor(v.w, 2);
;                 if (li < 2) v = v * cs - pr * sn; else if (li < 4) v = v * cs + pr * sn;
.LBB0_1005:
	s_waitcnt vmcnt(22)
	v_and_b32_e32 v21, 0xffff0000, v27
	v_and_b32_e32 v20, 0xffff0000, v26
	v_lshlrev_b32_e32 v19, 16, v27
	v_lshlrev_b32_e32 v18, 16, v26
	v_pk_mul_f32 v[26:27], v[20:21], v[20:21]
	s_nop 0
	v_pk_fma_f32 v[26:27], v[18:19], v[18:19], v[26:27]
	s_nop 0
	v_add_f32_e32 v26, v26, v27
	s_waitcnt lgkmcnt(0)
	s_nop 1
	v_add_f32_dpp v26, v26, v26 quad_perm:[1,0,3,2] row_mask:0xf bank_mask:0xf
	s_nop 1
	v_add_f32_dpp v26, v26, v26 quad_perm:[2,3,0,1] row_mask:0xf bank_mask:0xf
	s_nop 1
	v_add_f32_dpp v26, v26, v26 row_half_mirror row_mask:0xf bank_mask:0xf
	s_nop 1
	v_add_f32_dpp v26, v26, v26 row_mirror row_mask:0xf bank_mask:0xf
	v_fmamk_f32 v26, v26, 0x3c800000, v204
	v_mul_f32_e32 v27, 0x4f800000, v26
	v_cmp_gt_f32_e32 vcc, s33, v26
	s_nop 1
	v_cndmask_b32_e32 v65, v26, v27, vcc
	v_sqrt_f32_e32 v86, v65
	v_mov_b32_e32 v26, v18
	v_mov_b32_e32 v27, v20
	v_add_u32_e32 v18, -1, v86
	v_add_u32_e32 v20, 1, v86
	v_fma_f32 v87, -v18, v86, v65
	v_fma_f32 v88, -v20, v86, v65
	v_cmp_ge_f32_e64 s[8:9], 0, v87
	s_nop 1
	v_cndmask_b32_e64 v18, v86, v18, s[8:9]
	v_cmp_lt_f32_e64 s[8:9], 0, v88
	s_nop 1
	v_cndmask_b32_e64 v18, v18, v20, s[8:9]
	v_mul_f32_e32 v20, 0x37800000, v18
	v_cndmask_b32_e32 v18, v18, v20, vcc
	v_cmp_class_f32_e32 vcc, v65, v205
	v_mov_b32_e32 v20, v19
	s_nop 0
	v_cndmask_b32_e32 v18, v18, v65, vcc
	v_div_scale_f32 v65, s[8:9], v18, v18, 1.0
	v_rcp_f32_e32 v86, v65
	v_div_scale_f32 v19, vcc, 1.0, v18, 1.0
	v_fma_f32 v87, -v65, v86, 1.0
	v_fmac_f32_e32 v86, v87, v86
	v_mul_f32_e32 v87, v19, v86
	v_fma_f32 v88, -v65, v87, v19
	v_fmac_f32_e32 v87, v88, v86
	v_fma_f32 v19, -v65, v87, v19
	v_div_fmas_f32 v19, v19, v86, v87
	v_div_fixup_f32 v18, v19, v18, 1.0
	v_pk_mul_f32 v[26:27], v[18:19], v[26:27] op_sel_hi:[0,1]
	v_pk_mul_f32 v[18:19], v[18:19], v[20:21] op_sel_hi:[0,1]
	v_pk_mul_f32 v[86:87], v[8:9], v[18:19]
	v_pk_mul_f32 v[26:27], v[6:7], v[26:27]
	s_nop 1
	v_mov_b32_dpp v18, v26 quad_perm:[2,3,0,1] row_mask:0xf bank_mask:0xf
	v_mov_b32_dpp v19, v27 quad_perm:[2,3,0,1] row_mask:0xf bank_mask:0xf
	v_mov_b32_dpp v88, v86 quad_perm:[2,3,0,1] row_mask:0xf bank_mask:0xf
	v_mov_b32_dpp v89, v87 quad_perm:[2,3,0,1] row_mask:0xf bank_mask:0xf
	s_and_saveexec_b64 s[8:9], s[2:3]
	s_xor_b64 s[8:9], exec, s[8:9]
	s_cbranch_execz .LBB0_1009
	s_and_saveexec_b64 s[24:25], s[4:5]
	s_cbranch_execz .LBB0_1008
	v_pk_mul_f32 v[20:21], v[100:101], v[86:87]
	v_pk_mul_f32 v[26:27], v[16:17], v[26:27]
	s_waitcnt lgkmcnt(0)
	v_pk_fma_f32 v[86:87], v[102:103], v[88:89], v[20:21]
	v_pk_fma_f32 v[26:27], v[14:15], v[18:19], v[26:27]

; __device__ __forceinline__ void phase_qkpost(Frame& F, const Params& p, int j) {
;     ...
;             for (int c = 0; c < 9; ++c) {
;                 f32x4 v = x[c];
;                 float ss = (v.x * v.x + v.y * v.y) + (v.z * v.z + v.w * v.w);
;                 ss += __shfl_xor(ss, 1); ss += __shfl_xor(ss, 2); ss += __shfl_xor(ss, 4); ss += __shfl_xor(ss, 8);
;                 v = v * (1.0f / sqrtf(ss * (1.0f / 64.0f) + EPS)) * (c < 8 ? qg : kg);
;                 f32x4 pr; pr.x = __shfl_xor(v.x, 2); pr.y = __shfl_xor(v.y, 2); pr.z = __shfl_xor(v.z, 2); pr.w = __shfl_xor(v.w, 2);
;                 if (li < 2) v = v * cs - pr * sn; else if (li < 4) v = v * cs + pr * sn;
.LBB0_1015:
	s_waitcnt vmcnt(21)
	v_and_b32_e32 v21, 0xffff0000, v25
	v_and_b32_e32 v20, 0xffff0000, v24
	v_lshlrev_b32_e32 v19, 16, v25
	v_lshlrev_b32_e32 v18, 16, v24
	v_pk_mul_f32 v[22:23], v[20:21], v[20:21]
	s_nop 0
	v_pk_fma_f32 v[22:23], v[18:19], v[18:19], v[22:23]
	s_nop 0
	v_add_f32_e32 v22, v22, v23
	s_waitcnt lgkmcnt(0)
	s_nop 1
	v_add_f32_dpp v22, v22, v22 quad_perm:[1,0,3,2] row_mask:0xf bank_mask:0xf
	s_nop 1
	v_add_f32_dpp v22, v22, v22 quad_perm:[2,3,0,1] row_mask:0xf bank_mask:0xf
	s_nop 1
	v_add_f32_dpp v22, v22, v22 row_half_mirror row_mask:0xf bank_mask:0xf
	s_nop 1
	v_add_f32_dpp v22, v22, v22 row_mirror row_mask:0xf bank_mask:0xf
	v_fmamk_f32 v22, v22, 0x3c800000, v204
	v_mul_f32_e32 v23, 0x4f800000, v22
	v_cmp_gt_f32_e32 vcc, s33, v22
	s_nop 1
	v_cndmask_b32_e32 v24, v22, v23, vcc
	v_sqrt_f32_e32 v25, v24
	v_mov_b32_e32 v22, v18
	v_mov_b32_e32 v23, v20
	v_add_u32_e32 v18, -1, v25
	v_add_u32_e32 v20, 1, v25
	v_fma_f32 v26, -v18, v25, v24
	v_fma_f32 v27, -v20, v25, v24
	v_cmp_ge_f32_e64 s[8:9], 0, v26
	s_nop 1
	v_cndmask_b32_e64 v18, v25, v18, s[8:9]
	v_cmp_lt_f32_e64 s[8:9], 0, v27
	s_nop 1
	v_cndmask_b32_e64 v18, v18, v20, s[8:9]
	v_mul_f32_e32 v20, 0x37800000, v18
	v_cndmask_b32_e32 v18, v18, v20, vcc
	v_cmp_class_f32_e32 vcc, v24, v205
	v_mov_b32_e32 v20, v19
	s_nop 0
	v_cndmask_b32_e32 v18, v18, v24, vcc
	v_div_scale_f32 v24, s[8:9], v18, v18, 1.0
	v_rcp_f32_e32 v25, v24
	v_div_scale_f32 v19, vcc, 1.0, v18, 1.0
	v_fma_f32 v26, -v24, v25, 1.0
	v_fmac_f32_e32 v25, v26, v25
	v_mul_f32_e32 v26, v19, v25
	v_fma_f32 v27, -v24, v26, v19
	v_fmac_f32_e32 v26, v27, v25
	v_fma_f32 v19, -v24, v26, v19
	v_div_fmas_f32 v19, v19, v25, v26
	v_div_fixup_f32 v18, v19, v18, 1.0
	v_pk_mul_f32 v[24:25], v[18:19], v[22:23] op_sel_hi:[0,1]
	v_pk_mul_f32 v[18:19], v[18:19], v[20:21] op_sel_hi:[0,1]
	v_pk_mul_f32 v[22:23], v[4:5], v[18:19]
	v_pk_mul_f32 v[20:21], v[2:3], v[24:25]
	s_nop 1
	v_mov_b32_dpp v24, v20 quad_perm:[2,3,0,1] row_mask:0xf bank_mask:0xf
	v_mov_b32_dpp v25, v21 quad_perm:[2,3,0,1] row_mask:0xf bank_mask:0xf
	v_mov_b32_dpp v86, v22 quad_perm:[2,3,0,1] row_mask:0xf bank_mask:0xf
	v_mov_b32_dpp v87, v23 quad_perm:[2,3,0,1] row_mask:0xf bank_mask:0xf
	s_and_saveexec_b64 s[8:9], s[2:3]
	s_xor_b64 s[8:9], exec, s[8:9]
	s_cbranch_execz .LBB0_1019
	s_and_saveexec_b64 s[24:25], s[4:5]
	s_cbranch_execz .LBB0_1018
	v_pk_mul_f32 v[18:19], v[100:101], v[22:23]
	v_pk_mul_f32 v[16:17], v[16:17], v[20:21]
	s_waitcnt lgkmcnt(0)
	v_pk_fma_f32 v[22:23], v[102:103], v[86:87], v[18:19]
	v_pk_fma_f32 v[20:21], v[14:15], v[24:25], v[16:17]

; __device__ __forceinline__ void phase_qkpost(Frame& F, const Params& p, int j) {
;     ...
;         for (int r = 0; r < 4; ++r) {
;             const int row = row0 + r, pos = kind ? PASTLEN : pos0 + r;
;             f32x4 x[10];
; #pragma unroll
;             for (int c = 0; c < 10; ++c) x[c] = (f32x4){__uint_as_float(xr[r][c].x << 16), __uint_as_float(xr[r][c].x & 0xffff0000u), __uint_as_float(xr[r][c].y << 16), __uint_as_float(xr[r][c].y & 0xffff0000u)};
;             f32x4 cs, sn;
; #pragma unroll
;             for (int e = 0; e < 4; ++e) { const float ang = (float)pos * inv[e]; const double tr = (double)ang * 0.15915494309189535; const float rv = (float)(tr - __builtin_rint(tr));
;                 cs[e] = __builtin_amdgcn_cosf(rv); sn[e] = __builtin_amdgcn_sinf(rv); }
; #pragma unroll
;             for (int c = 0; c < 9; ++c) {
;                 f32x4 v = x[c];
;                 float ss = (v.x * v.x + v.y * v.y) + (v.z * v.z + v.w * v.w);
;                 ss += __shfl_xor(ss, 1); ss += __shfl_xor(ss, 2); ss += __shfl_xor(ss, 4); ss += __shfl_xor(ss, 8);
;                 v = v * (1.0f / sqrtf(ss * (1.0f / 64.0f) + EPS)) * (c < 8 ? qg : kg);
;                 f32x4 pr; pr.x = __shfl_xor(v.x, 2); pr.y = __shfl_xor(v.y, 2); pr.z = __shfl_xor(v.z, 2); pr.w = __shfl_xor(v.w, 2);
;                 if (li < 2) v = v * cs - pr * sn; else if (li < 4) v = v * cs + pr * sn;
.LBB0_1036:
	s_add_i32 s24, s82, 2
	v_cvt_f32_u32_e32 v18, s24
	v_cndmask_b32_e64 v26, v218, v18, s[12:13]
	v_mul_f32_e32 v18, v39, v26
	v_cvt_f64_f32_e32 v[18:19], v18
	v_mul_f64 v[20:21], v[18:19], s[66:67]
	v_rndne_f64_e32 v[20:21], v[20:21]
	v_fma_f64 v[18:19], v[18:19], s[66:67], -v[20:21]
	v_cvt_f32_f64_e32 v18, v[18:19]
	v_mul_f32_e32 v19, v120, v26
	v_cvt_f64_f32_e32 v[22:23], v19
	s_waitcnt lgkmcnt(2)
	v_mul_f64 v[24:25], v[22:23], s[66:67]
	v_rndne_f64_e32 v[24:25], v[24:25]
	v_fma_f64 v[22:23], v[22:23], s[66:67], -v[24:25]
	v_cvt_f32_f64_e32 v19, v[22:23]
	v_mul_f32_e32 v22, v121, v26
	v_cvt_f64_f32_e32 v[22:23], v22
	v_mul_f64 v[24:25], v[22:23], s[66:67]
	v_rndne_f64_e32 v[24:25], v[24:25]
	v_fma_f64 v[22:23], v[22:23], s[66:67], -v[24:25]
	v_cvt_f32_f64_e32 v22, v[22:23]
	v_cos_f32_e32 v84, v22
	s_waitcnt lgkmcnt(1)
	v_sin_f32_e32 v86, v22
	v_mul_f32_e32 v22, v122, v26
	v_cvt_f64_f32_e32 v[22:23], v22
	v_mul_f64 v[24:25], v[22:23], s[66:67]
	v_rndne_f64_e32 v[24:25], v[24:25]
	v_fma_f64 v[22:23], v[22:23], s[66:67], -v[24:25]
	v_cvt_f32_f64_e32 v22, v[22:23]
	s_waitcnt vmcnt(19)
	v_and_b32_e32 v25, 0xffff0000, v83
	v_and_b32_e32 v24, 0xffff0000, v82
	v_cos_f32_e32 v85, v22
	s_waitcnt lgkmcnt(0)
	v_sin_f32_e32 v87, v22
	v_lshlrev_b32_e32 v23, 16, v83
	v_lshlrev_b32_e32 v22, 16, v82
	v_pk_mul_f32 v[26:27], v[24:25], v[24:25]
	v_cos_f32_e32 v20, v18
	v_pk_fma_f32 v[26:27], v[22:23], v[22:23], v[26:27]
	v_sin_f32_e32 v18, v18
	v_add_f32_e32 v26, v26, v27
	s_nop 1
	v_mov_b32_dpp v27, v26 quad_perm:[1,0,3,2] row_mask:0xf bank_mask:0xf
	v_cos_f32_e32 v21, v19
	v_sin_f32_e32 v19, v19
	s_waitcnt lgkmcnt(0)
	v_add_f32_e32 v26, v26, v27
	s_nop 1
	v_mov_b32_dpp v27, v26 quad_perm:[2,3,0,1] row_mask:0xf bank_mask:0xf
	s_waitcnt lgkmcnt(0)
	v_add_f32_e32 v26, v26, v27
	s_nop 1
	v_mov_b32_dpp v27, v26 row_half_mirror row_mask:0xf bank_mask:0xf
	s_waitcnt lgkmcnt(0)
	v_add_f32_e32 v26, v26, v27
	s_nop 1
	v_mov_b32_dpp v27, v26 row_mirror row_mask:0xf bank_mask:0xf
	s_waitcnt lgkmcnt(0)
	v_add_f32_e32 v26, v26, v27
	v_fmamk_f32 v26, v26, 0x3c800000, v204
	v_cmp_gt_f32_e32 vcc, s33, v26
	v_mul_f32_e32 v27, 0x4f800000, v26
	s_nop 0
	v_cndmask_b32_e32 v26, v26, v27, vcc
	v_sqrt_f32_e32 v27, v26
	s_nop 0
	v_add_u32_e32 v65, -1, v27
	v_fma_f32 v82, -v65, v27, v26
	v_cmp_ge_f32_e64 s[8:9], 0, v82
	v_add_u32_e32 v82, 1, v27
	s_nop 0
	v_cndmask_b32_e64 v65, v27, v65, s[8:9]
	v_fma_f32 v27, -v82, v27, v26
	v_cmp_lt_f32_e64 s[8:9], 0, v27
	s_nop 1
	v_cndmask_b32_e64 v27, v65, v82, s[8:9]
	v_mul_f32_e32 v65, 0x37800000, v27
	v_cndmask_b32_e32 v27, v27, v65, vcc
	v_cmp_class_f32_e32 vcc, v26, v205
	s_nop 1
	v_cndmask_b32_e32 v26, v27, v26, vcc
	v_div_scale_f32 v27, s[8:9], v26, v26, 1.0
	v_rcp_f32_e32 v65, v27
	s_nop 0
	v_fma_f32 v82, -v27, v65, 1.0
	v_fmac_f32_e32 v65, v82, v65
	v_div_scale_f32 v82, vcc, 1.0, v26, 1.0
	v_mul_f32_e32 v83, v82, v65
	v_fma_f32 v88, -v27, v83, v82
	v_fmac_f32_e32 v83, v88, v65
	v_fma_f32 v27, -v27, v83, v82
	v_div_fmas_f32 v27, v27, v65, v83
	v_div_fixup_f32 v26, v27, v26, 1.0
	v_mov_b32_e32 v82, v22
	v_mov_b32_e32 v83, v24
	v_mov_b32_e32 v24, v23
	v_pk_mul_f32 v[88:89], v[26:27], v[82:83] op_sel_hi:[0,1]
	v_pk_mul_f32 v[22:23], v[26:27], v[24:25] op_sel_hi:[0,1]
	v_pk_mul_f32 v[82:83], v[8:9], v[22:23]
	v_pk_mul_f32 v[26:27], v[6:7], v[88:89]
	s_nop 1
	v_mov_b32_dpp v22, v26 quad_perm:[2,3,0,1] row_mask:0xf bank_mask:0xf
	v_mov_b32_dpp v23, v27 quad_perm:[2,3,0,1] row_mask:0xf bank_mask:0xf
	v_mov_b32_dpp v88, v82 quad_perm:[2,3,0,1] row_mask:0xf bank_mask:0xf
	v_mov_b32_dpp v89, v83 quad_perm:[2,3,0,1] row_mask:0xf bank_mask:0xf
	s_and_saveexec_b64 s[8:9], s[2:3]
	s_xor_b64 s[8:9], exec, s[8:9]
	s_cbranch_execz .LBB0_1040
	s_and_saveexec_b64 s[26:27], s[4:5]
	s_cbranch_execz .LBB0_1039
	v_pk_mul_f32 v[24:25], v[84:85], v[82:83]
	v_pk_mul_f32 v[26:27], v[20:21], v[26:27]
	s_waitcnt lgkmcnt(0)
	v_pk_fma_f32 v[82:83], v[86:87], v[88:89], v[24:25]
	v_pk_fma_f32 v[26:27], v[18:19], v[22:23], v[26:27]

; __device__ __forceinline__ void phase_qkpost(Frame& F, const Params& p, int j) {
;     ...
;             for (int c = 0; c < 9; ++c) {
;                 f32x4 v = x[c];
;                 float ss = (v.x * v.x + v.y * v.y) + (v.z * v.z + v.w * v.w);
;                 ss += __shfl_xor(ss, 1); ss += __shfl_xor(ss, 2); ss += __shfl_xor(ss, 4); ss += __shfl_xor(ss, 8);
;                 v = v * (1.0f / sqrtf(ss * (1.0f / 64.0f) + EPS)) * (c < 8 ? qg : kg);
;                 f32x4 pr; pr.x = __shfl_xor(v.x, 2); pr.y = __shfl_xor(v.y, 2); pr.z = __shfl_xor(v.z, 2); pr.w = __shfl_xor(v.w, 2);
;                 if (li < 2) v = v * cs - pr * sn; else if (li < 4) v = v * cs + pr * sn;
.LBB0_1046:
	s_waitcnt vmcnt(18)
	v_and_b32_e32 v25, 0xffff0000, v81
	v_and_b32_e32 v24, 0xffff0000, v80
	v_lshlrev_b32_e32 v23, 16, v81
	v_lshlrev_b32_e32 v22, 16, v80
	v_pk_mul_f32 v[80:81], v[24:25], v[24:25]
	s_nop 0
	v_pk_fma_f32 v[80:81], v[22:23], v[22:23], v[80:81]
	s_nop 0
	v_add_f32_e32 v65, v80, v81
	s_nop 1
	v_mov_b32_dpp v80, v65 quad_perm:[1,0,3,2] row_mask:0xf bank_mask:0xf
	v_mov_b32_e32 v81, v24
	s_waitcnt lgkmcnt(0)
	v_add_f32_e32 v65, v65, v80
	s_nop 1
	v_mov_b32_dpp v80, v65 quad_perm:[2,3,0,1] row_mask:0xf bank_mask:0xf
	s_waitcnt lgkmcnt(0)
	v_add_f32_e32 v65, v65, v80
	s_nop 1
	v_mov_b32_dpp v80, v65 row_half_mirror row_mask:0xf bank_mask:0xf
	s_waitcnt lgkmcnt(0)
	v_add_f32_e32 v65, v65, v80
	s_nop 1
	v_mov_b32_dpp v80, v65 row_mirror row_mask:0xf bank_mask:0xf
	s_waitcnt lgkmcnt(0)
	v_add_f32_e32 v65, v65, v80
	v_fmamk_f32 v65, v65, 0x3c800000, v204
	v_mul_f32_e32 v80, 0x4f800000, v65
	v_cmp_gt_f32_e32 vcc, s33, v65
	s_nop 1
	v_cndmask_b32_e32 v65, v65, v80, vcc
	v_sqrt_f32_e32 v88, v65
	v_mov_b32_e32 v80, v22
	v_add_u32_e32 v22, -1, v88
	v_add_u32_e32 v24, 1, v88
	v_fma_f32 v89, -v22, v88, v65
	v_fma_f32 v90, -v24, v88, v65
	v_cmp_ge_f32_e64 s[8:9], 0, v89
	s_nop 1
	v_cndmask_b32_e64 v22, v88, v22, s[8:9]
	v_cmp_lt_f32_e64 s[8:9], 0, v90
	s_nop 1
	v_cndmask_b32_e64 v22, v22, v24, s[8:9]
	v_mul_f32_e32 v24, 0x37800000, v22
	v_cndmask_b32_e32 v22, v22, v24, vcc
	v_cmp_class_f32_e32 vcc, v65, v205
	v_mov_b32_e32 v24, v23
	s_nop 0
	v_cndmask_b32_e32 v22, v22, v65, vcc
	v_div_scale_f32 v65, s[8:9], v22, v22, 1.0
	v_rcp_f32_e32 v88, v65
	v_div_scale_f32 v23, vcc, 1.0, v22, 1.0
	v_fma_f32 v89, -v65, v88, 1.0
	v_fmac_f32_e32 v88, v89, v88
	v_mul_f32_e32 v89, v23, v88
	v_fma_f32 v90, -v65, v89, v23
	v_fmac_f32_e32 v89, v90, v88
	v_fma_f32 v23, -v65, v89, v23
	v_div_fmas_f32 v23, v23, v88, v89
	v_div_fixup_f32 v22, v23, v22, 1.0
	v_pk_mul_f32 v[80:81], v[22:23], v[80:81] op_sel_hi:[0,1]
	v_pk_mul_f32 v[22:23], v[22:23], v[24:25] op_sel_hi:[0,1]
	v_pk_mul_f32 v[88:89], v[8:9], v[22:23]
	v_pk_mul_f32 v[80:81], v[6:7], v[80:81]
	s_nop 1
	v_mov_b32_dpp v22, v80 quad_perm:[2,3,0,1] row_mask:0xf bank_mask:0xf
	v_mov_b32_dpp v23, v81 quad_perm:[2,3,0,1] row_mask:0xf bank_mask:0xf
	v_mov_b32_dpp v90, v88 quad_perm:[2,3,0,1] row_mask:0xf bank_mask:0xf
	v_mov_b32_dpp v91, v89 quad_perm:[2,3,0,1] row_mask:0xf bank_mask:0xf
	s_and_saveexec_b64 s[8:9], s[2:3]
	s_xor_b64 s[8:9], exec, s[8:9]
	s_cbranch_execz .LBB0_1050
	s_and_saveexec_b64 s[22:23], s[4:5]
	s_cbranch_execz .LBB0_1049
	v_pk_mul_f32 v[24:25], v[84:85], v[88:89]
	v_pk_mul_f32 v[80:81], v[20:21], v[80:81]
	s_waitcnt lgkmcnt(0)
	v_pk_fma_f32 v[88:89], v[86:87], v[90:91], v[24:25]
	v_pk_fma_f32 v[80:81], v[18:19], v[22:23], v[80:81]

; __device__ __forceinline__ void phase_qkpost(Frame& F, const Params& p, int j) {
;     ...
;             for (int c = 0; c < 9; ++c) {
;                 f32x4 v = x[c];
;                 float ss = (v.x * v.x + v.y * v.y) + (v.z * v.z + v.w * v.w);
;                 ss += __shfl_xor(ss, 1); ss += __shfl_xor(ss, 2); ss += __shfl_xor(ss, 4); ss += __shfl_xor(ss, 8);
;                 v = v * (1.0f / sqrtf(ss * (1.0f / 64.0f) + EPS)) * (c < 8 ? qg : kg);
;                 f32x4 pr; pr.x = __shfl_xor(v.x, 2); pr.y = __shfl_xor(v.y, 2); pr.z = __shfl_xor(v.z, 2); pr.w = __shfl_xor(v.w, 2);
;                 if (li < 2) v = v * cs - pr * sn; else if (li < 4) v = v * cs + pr * sn;
.LBB0_1056:
	s_waitcnt vmcnt(17)
	v_and_b32_e32 v25, 0xffff0000, v79
	v_and_b32_e32 v24, 0xffff0000, v78
	v_lshlrev_b32_e32 v23, 16, v79
	v_lshlrev_b32_e32 v22, 16, v78
	v_pk_mul_f32 v[78:79], v[24:25], v[24:25]
	s_nop 0
	v_pk_fma_f32 v[78:79], v[22:23], v[22:23], v[78:79]
	s_nop 0
	v_add_f32_e32 v65, v78, v79
	s_nop 1
	v_mov_b32_dpp v78, v65 quad_perm:[1,0,3,2] row_mask:0xf bank_mask:0xf
	v_mov_b32_e32 v79, v24
	s_waitcnt lgkmcnt(0)
	v_add_f32_e32 v65, v65, v78
	s_nop 1
	v_mov_b32_dpp v78, v65 quad_perm:[2,3,0,1] row_mask:0xf bank_mask:0xf
	s_waitcnt lgkmcnt(0)
	v_add_f32_e32 v65, v65, v78
	s_nop 1
	v_mov_b32_dpp v78, v65 row_half_mirror row_mask:0xf bank_mask:0xf
	s_waitcnt lgkmcnt(0)
	v_add_f32_e32 v65, v65, v78
	s_nop 1
	v_mov_b32_dpp v78, v65 row_mirror row_mask:0xf bank_mask:0xf
	s_waitcnt lgkmcnt(0)
	v_add_f32_e32 v65, v65, v78
	v_fmamk_f32 v65, v65, 0x3c800000, v204
	v_mul_f32_e32 v78, 0x4f800000, v65
	v_cmp_gt_f32_e32 vcc, s33, v65
	s_nop 1
	v_cndmask_b32_e32 v65, v65, v78, vcc
	v_sqrt_f32_e32 v80, v65
	v_mov_b32_e32 v78, v22
	v_add_u32_e32 v22, -1, v80
	v_add_u32_e32 v24, 1, v80
	v_fma_f32 v81, -v22, v80, v65
	v_fma_f32 v88, -v24, v80, v65
	v_cmp_ge_f32_e64 s[8:9], 0, v81
	s_nop 1
	v_cndmask_b32_e64 v22, v80, v22, s[8:9]
	v_cmp_lt_f32_e64 s[8:9], 0, v88
	s_nop 1
	v_cndmask_b32_e64 v22, v22, v24, s[8:9]
	v_mul_f32_e32 v24, 0x37800000, v22
	v_cndmask_b32_e32 v22, v22, v24, vcc
	v_cmp_class_f32_e32 vcc, v65, v205
	v_mov_b32_e32 v24, v23
	s_nop 0
	v_cndmask_b32_e32 v22, v22, v65, vcc
	v_div_scale_f32 v65, s[8:9], v22, v22, 1.0
	v_rcp_f32_e32 v80, v65
	v_div_scale_f32 v23, vcc, 1.0, v22, 1.0
	v_fma_f32 v81, -v65, v80, 1.0
	v_fmac_f32_e32 v80, v81, v80
	v_mul_f32_e32 v81, v23, v80
	v_fma_f32 v88, -v65, v81, v23
	v_fmac_f32_e32 v81, v88, v80
	v_fma_f32 v23, -v65, v81, v23
	v_div_fmas_f32 v23, v23, v80, v81
	v_div_fixup_f32 v22, v23, v22, 1.0
	v_pk_mul_f32 v[78:79], v[22:23], v[78:79] op_sel_hi:[0,1]
	v_pk_mul_f32 v[22:23], v[22:23], v[24:25] op_sel_hi:[0,1]
	v_pk_mul_f32 v[80:81], v[8:9], v[22:23]
	v_pk_mul_f32 v[78:79], v[6:7], v[78:79]
	s_nop 1
	v_mov_b32_dpp v22, v78 quad_perm:[2,3,0,1] row_mask:0xf bank_mask:0xf
	v_mov_b32_dpp v23, v79 quad_perm:[2,3,0,1] row_mask:0xf bank_mask:0xf
	v_mov_b32_dpp v88, v80 quad_perm:[2,3,0,1] row_mask:0xf bank_mask:0xf
	v_mov_b32_dpp v89, v81 quad_perm:[2,3,0,1] row_mask:0xf bank_mask:0xf
	s_and_saveexec_b64 s[8:9], s[2:3]
	s_xor_b64 s[8:9], exec, s[8:9]
	s_cbranch_execz .LBB0_1060
	s_and_saveexec_b64 s[22:23], s[4:5]
	s_cbranch_execz .LBB0_1059
	v_pk_mul_f32 v[24:25], v[84:85], v[80:81]
	v_pk_mul_f32 v[78:79], v[20:21], v[78:79]
	s_waitcnt lgkmcnt(0)
	v_pk_fma_f32 v[80:81], v[86:87], v[88:89], v[24:25]
	v_pk_fma_f32 v[78:79], v[18:19], v[22:23], v[78:79]

; __device__ __forceinline__ void phase_qkpost(Frame& F, const Params& p, int j) {
;     ...
;             for (int c = 0; c < 9; ++c) {
;                 f32x4 v = x[c];
;                 float ss = (v.x * v.x + v.y * v.y) + (v.z * v.z + v.w * v.w);
;                 ss += __shfl_xor(ss, 1); ss += __shfl_xor(ss, 2); ss += __shfl_xor(ss, 4); ss += __shfl_xor(ss, 8);
;                 v = v * (1.0f / sqrtf(ss * (1.0f / 64.0f) + EPS)) * (c < 8 ? qg : kg);
;                 f32x4 pr; pr.x = __shfl_xor(v.x, 2); pr.y = __shfl_xor(v.y, 2); pr.z = __shfl_xor(v.z, 2); pr.w = __shfl_xor(v.w, 2);
;                 if (li < 2) v = v * cs - pr * sn; else if (li < 4) v = v * cs + pr * sn;
.LBB0_1066:
	s_waitcnt vmcnt(16)
	v_and_b32_e32 v25, 0xffff0000, v77
	v_and_b32_e32 v24, 0xffff0000, v76
	v_lshlrev_b32_e32 v23, 16, v77
	v_lshlrev_b32_e32 v22, 16, v76
	v_pk_mul_f32 v[76:77], v[24:25], v[24:25]
	s_nop 0
	v_pk_fma_f32 v[76:77], v[22:23], v[22:23], v[76:77]
	s_nop 0
	v_add_f32_e32 v65, v76, v77
	s_nop 1
	v_mov_b32_dpp v76, v65 quad_perm:[1,0,3,2] row_mask:0xf bank_mask:0xf
	v_mov_b32_e32 v77, v24
	s_waitcnt lgkmcnt(0)
	v_add_f32_e32 v65, v65, v76
	s_nop 1
	v_mov_b32_dpp v76, v65 quad_perm:[2,3,0,1] row_mask:0xf bank_mask:0xf
	s_waitcnt lgkmcnt(0)
	v_add_f32_e32 v65, v65, v76
	s_nop 1
	v_mov_b32_dpp v76, v65 row_half_mirror row_mask:0xf bank_mask:0xf
	s_waitcnt lgkmcnt(0)
	v_add_f32_e32 v65, v65, v76
	s_nop 1
	v_mov_b32_dpp v76, v65 row_mirror row_mask:0xf bank_mask:0xf
	s_waitcnt lgkmcnt(0)
	v_add_f32_e32 v65, v65, v76
	v_fmamk_f32 v65, v65, 0x3c800000, v204
	v_mul_f32_e32 v76, 0x4f800000, v65
	v_cmp_gt_f32_e32 vcc, s33, v65
	s_nop 1
	v_cndmask_b32_e32 v65, v65, v76, vcc
	v_sqrt_f32_e32 v78, v65
	v_mov_b32_e32 v76, v22
	v_add_u32_e32 v22, -1, v78
	v_add_u32_e32 v24, 1, v78
	v_fma_f32 v79, -v22, v78, v65
	v_fma_f32 v80, -v24, v78, v65
	v_cmp_ge_f32_e64 s[8:9], 0, v79
	s_nop 1
	v_cndmask_b32_e64 v22, v78, v22, s[8:9]
	v_cmp_lt_f32_e64 s[8:9], 0, v80
	s_nop 1
	v_cndmask_b32_e64 v22, v22, v24, s[8:9]
	v_mul_f32_e32 v24, 0x37800000, v22
	v_cndmask_b32_e32 v22, v22, v24, vcc
	v_cmp_class_f32_e32 vcc, v65, v205
	v_mov_b32_e32 v24, v23
	s_nop 0
	v_cndmask_b32_e32 v22, v22, v65, vcc
	v_div_scale_f32 v65, s[8:9], v22, v22, 1.0
	v_rcp_f32_e32 v78, v65
	v_div_scale_f32 v23, vcc, 1.0, v22, 1.0
	v_fma_f32 v79, -v65, v78, 1.0
	v_fmac_f32_e32 v78, v79, v78
	v_mul_f32_e32 v79, v23, v78
	v_fma_f32 v80, -v65, v79, v23
	v_fmac_f32_e32 v79, v80, v78
	v_fma_f32 v23, -v65, v79, v23
	v_div_fmas_f32 v23, v23, v78, v79
	v_div_fixup_f32 v22, v23, v22, 1.0
	v_pk_mul_f32 v[76:77], v[22:23], v[76:77] op_sel_hi:[0,1]
	v_pk_mul_f32 v[22:23], v[22:23], v[24:25] op_sel_hi:[0,1]
	v_pk_mul_f32 v[78:79], v[8:9], v[22:23]
	v_pk_mul_f32 v[76:77], v[6:7], v[76:77]
	s_nop 1
	v_mov_b32_dpp v22, v76 quad_perm:[2,3,0,1] row_mask:0xf bank_mask:0xf
	v_mov_b32_dpp v23, v77 quad_perm:[2,3,0,1] row_mask:0xf bank_mask:0xf
	v_mov_b32_dpp v80, v78 quad_perm:[2,3,0,1] row_mask:0xf bank_mask:0xf
	v_mov_b32_dpp v81, v79 quad_perm:[2,3,0,1] row_mask:0xf bank_mask:0xf
	s_and_saveexec_b64 s[8:9], s[2:3]
	s_xor_b64 s[8:9], exec, s[8:9]
	s_cbranch_execz .LBB0_1070
	s_and_saveexec_b64 s[22:23], s[4:5]
	s_cbranch_execz .LBB0_1069
	v_pk_mul_f32 v[24:25], v[84:85], v[78:79]
	v_pk_mul_f32 v[76:77], v[20:21], v[76:77]
	s_waitcnt lgkmcnt(0)
	v_pk_fma_f32 v[78:79], v[86:87], v[80:81], v[24:25]
	v_pk_fma_f32 v[76:77], v[18:19], v[22:23], v[76:77]

; __device__ __forceinline__ void phase_qkpost(Frame& F, const Params& p, int j) {
;     ...
;             for (int c = 0; c < 9; ++c) {
;                 f32x4 v = x[c];
;                 float ss = (v.x * v.x + v.y * v.y) + (v.z * v.z + v.w * v.w);
;                 ss += __shfl_xor(ss, 1); ss += __shfl_xor(ss, 2); ss += __shfl_xor(ss, 4); ss += __shfl_xor(ss, 8);
;                 v = v * (1.0f / sqrtf(ss * (1.0f / 64.0f) + EPS)) * (c < 8 ? qg : kg);
;                 f32x4 pr; pr.x = __shfl_xor(v.x, 2); pr.y = __shfl_xor(v.y, 2); pr.z = __shfl_xor(v.z, 2); pr.w = __shfl_xor(v.w, 2);
;                 if (li < 2) v = v * cs - pr * sn; else if (li < 4) v = v * cs + pr * sn;
.LBB0_1076:
	s_waitcnt vmcnt(15)
	v_and_b32_e32 v25, 0xffff0000, v75
	v_and_b32_e32 v24, 0xffff0000, v74
	v_lshlrev_b32_e32 v23, 16, v75
	v_lshlrev_b32_e32 v22, 16, v74
	v_pk_mul_f32 v[74:75], v[24:25], v[24:25]
	s_nop 0
	v_pk_fma_f32 v[74:75], v[22:23], v[22:23], v[74:75]
	s_nop 0
	v_add_f32_e32 v65, v74, v75
	s_nop 1
	v_mov_b32_dpp v74, v65 quad_perm:[1,0,3,2] row_mask:0xf bank_mask:0xf
	v_mov_b32_e32 v75, v24
	s_waitcnt lgkmcnt(0)
	v_add_f32_e32 v65, v65, v74
	s_nop 1
	v_mov_b32_dpp v74, v65 quad_perm:[2,3,0,1] row_mask:0xf bank_mask:0xf
	s_waitcnt lgkmcnt(0)
	v_add_f32_e32 v65, v65, v74
	s_nop 1
	v_mov_b32_dpp v74, v65 row_half_mirror row_mask:0xf bank_mask:0xf
	s_waitcnt lgkmcnt(0)
	v_add_f32_e32 v65, v65, v74
	s_nop 1
	v_mov_b32_dpp v74, v65 row_mirror row_mask:0xf bank_mask:0xf
	s_waitcnt lgkmcnt(0)
	v_add_f32_e32 v65, v65, v74
	v_fmamk_f32 v65, v65, 0x3c800000, v204
	v_mul_f32_e32 v74, 0x4f800000, v65
	v_cmp_gt_f32_e32 vcc, s33, v65
	s_nop 1
	v_cndmask_b32_e32 v65, v65, v74, vcc
	v_sqrt_f32_e32 v76, v65
	v_mov_b32_e32 v74, v22
	v_add_u32_e32 v22, -1, v76
	v_add_u32_e32 v24, 1, v76
	v_fma_f32 v77, -v22, v76, v65
	v_fma_f32 v78, -v24, v76, v65
	v_cmp_ge_f32_e64 s[8:9], 0, v77
	s_nop 1
	v_cndmask_b32_e64 v22, v76, v22, s[8:9]
	v_cmp_lt_f32_e64 s[8:9], 0, v78
	s_nop 1
	v_cndmask_b32_e64 v22, v22, v24, s[8:9]
	v_mul_f32_e32 v24, 0x37800000, v22
	v_cndmask_b32_e32 v22, v22, v24, vcc
	v_cmp_class_f32_e32 vcc, v65, v205
	v_mov_b32_e32 v24, v23
	s_nop 0
	v_cndmask_b32_e32 v22, v22, v65, vcc
	v_div_scale_f32 v65, s[8:9], v22, v22, 1.0
	v_rcp_f32_e32 v76, v65
	v_div_scale_f32 v23, vcc, 1.0, v22, 1.0
	v_fma_f32 v77, -v65, v76, 1.0
	v_fmac_f32_e32 v76, v77, v76
	v_mul_f32_e32 v77, v23, v76
	v_fma_f32 v78, -v65, v77, v23
	v_fmac_f32_e32 v77, v78, v76
	v_fma_f32 v23, -v65, v77, v23
	v_div_fmas_f32 v23, v23, v76, v77
	v_div_fixup_f32 v22, v23, v22, 1.0
	v_pk_mul_f32 v[74:75], v[22:23], v[74:75] op_sel_hi:[0,1]
	v_pk_mul_f32 v[22:23], v[22:23], v[24:25] op_sel_hi:[0,1]
	v_pk_mul_f32 v[76:77], v[8:9], v[22:23]
	v_pk_mul_f32 v[74:75], v[6:7], v[74:75]
	s_nop 1
	v_mov_b32_dpp v22, v74 quad_perm:[2,3,0,1] row_mask:0xf bank_mask:0xf
	v_mov_b32_dpp v23, v75 quad_perm:[2,3,0,1] row_mask:0xf bank_mask:0xf
	v_mov_b32_dpp v78, v76 quad_perm:[2,3,0,1] row_mask:0xf bank_mask:0xf
	v_mov_b32_dpp v79, v77 quad_perm:[2,3,0,1] row_mask:0xf bank_mask:0xf
	s_and_saveexec_b64 s[8:9], s[2:3]
	s_xor_b64 s[8:9], exec, s[8:9]
	s_cbranch_execz .LBB0_1080
	s_and_saveexec_b64 s[22:23], s[4:5]
	s_cbranch_execz .LBB0_1079
	v_pk_mul_f32 v[24:25], v[84:85], v[76:77]
	v_pk_mul_f32 v[74:75], v[20:21], v[74:75]
	s_waitcnt lgkmcnt(0)
	v_pk_fma_f32 v[76:77], v[86:87], v[78:79], v[24:25]
	v_pk_fma_f32 v[74:75], v[18:19], v[22:23], v[74:75]

; __device__ __forceinline__ void phase_qkpost(Frame& F, const Params& p, int j) {
;     ...
;             for (int c = 0; c < 9; ++c) {
;                 f32x4 v = x[c];
;                 float ss = (v.x * v.x + v.y * v.y) + (v.z * v.z + v.w * v.w);
;                 ss += __shfl_xor(ss, 1); ss += __shfl_xor(ss, 2); ss += __shfl_xor(ss, 4); ss += __shfl_xor(ss, 8);
;                 v = v * (1.0f / sqrtf(ss * (1.0f / 64.0f) + EPS)) * (c < 8 ? qg : kg);
;                 f32x4 pr; pr.x = __shfl_xor(v.x, 2); pr.y = __shfl_xor(v.y, 2); pr.z = __shfl_xor(v.z, 2); pr.w = __shfl_xor(v.w, 2);
;                 if (li < 2) v = v * cs - pr * sn; else if (li < 4) v = v * cs + pr * sn;
.LBB0_1086:
	s_waitcnt vmcnt(14)
	v_and_b32_e32 v25, 0xffff0000, v73
	v_and_b32_e32 v24, 0xffff0000, v72
	v_lshlrev_b32_e32 v23, 16, v73
	v_lshlrev_b32_e32 v22, 16, v72
	v_pk_mul_f32 v[72:73], v[24:25], v[24:25]
	s_nop 0
	v_pk_fma_f32 v[72:73], v[22:23], v[22:23], v[72:73]
	s_nop 0
	v_add_f32_e32 v65, v72, v73
	s_nop 1
	v_mov_b32_dpp v72, v65 quad_perm:[1,0,3,2] row_mask:0xf bank_mask:0xf
	v_mov_b32_e32 v73, v24
	s_waitcnt lgkmcnt(0)
	v_add_f32_e32 v65, v65, v72
	s_nop 1
	v_mov_b32_dpp v72, v65 quad_perm:[2,3,0,1] row_mask:0xf bank_mask:0xf
	s_waitcnt lgkmcnt(0)
	v_add_f32_e32 v65, v65, v72
	s_nop 1
	v_mov_b32_dpp v72, v65 row_half_mirror row_mask:0xf bank_mask:0xf
	s_waitcnt lgkmcnt(0)
	v_add_f32_e32 v65, v65, v72
	s_nop 1
	v_mov_b32_dpp v72, v65 row_mirror row_mask:0xf bank_mask:0xf
	s_waitcnt lgkmcnt(0)
	v_add_f32_e32 v65, v65, v72
	v_fmamk_f32 v65, v65, 0x3c800000, v204
	v_mul_f32_e32 v72, 0x4f800000, v65
	v_cmp_gt_f32_e32 vcc, s33, v65
	s_nop 1
	v_cndmask_b32_e32 v65, v65, v72, vcc
	v_sqrt_f32_e32 v74, v65
	v_mov_b32_e32 v72, v22
	v_add_u32_e32 v22, -1, v74
	v_add_u32_e32 v24, 1, v74
	v_fma_f32 v75, -v22, v74, v65
	v_fma_f32 v76, -v24, v74, v65
	v_cmp_ge_f32_e64 s[8:9], 0, v75
	s_nop 1
	v_cndmask_b32_e64 v22, v74, v22, s[8:9]
	v_cmp_lt_f32_e64 s[8:9], 0, v76
	s_nop 1
	v_cndmask_b32_e64 v22, v22, v24, s[8:9]
	v_mul_f32_e32 v24, 0x37800000, v22
	v_cndmask_b32_e32 v22, v22, v24, vcc
	v_cmp_class_f32_e32 vcc, v65, v205
	v_mov_b32_e32 v24, v23
	s_nop 0
	v_cndmask_b32_e32 v22, v22, v65, vcc
	v_div_scale_f32 v65, s[8:9], v22, v22, 1.0
	v_rcp_f32_e32 v74, v65
	v_div_scale_f32 v23, vcc, 1.0, v22, 1.0
	v_fma_f32 v75, -v65, v74, 1.0
	v_fmac_f32_e32 v74, v75, v74
	v_mul_f32_e32 v75, v23, v74
	v_fma_f32 v76, -v65, v75, v23
	v_fmac_f32_e32 v75, v76, v74
	v_fma_f32 v23, -v65, v75, v23
	v_div_fmas_f32 v23, v23, v74, v75
	v_div_fixup_f32 v22, v23, v22, 1.0
	v_pk_mul_f32 v[72:73], v[22:23], v[72:73] op_sel_hi:[0,1]
	v_pk_mul_f32 v[22:23], v[22:23], v[24:25] op_sel_hi:[0,1]
	v_pk_mul_f32 v[74:75], v[8:9], v[22:23]
	v_pk_mul_f32 v[72:73], v[6:7], v[72:73]
	s_nop 1
	v_mov_b32_dpp v22, v72 quad_perm:[2,3,0,1] row_mask:0xf bank_mask:0xf
	v_mov_b32_dpp v23, v73 quad_perm:[2,3,0,1] row_mask:0xf bank_mask:0xf
	v_mov_b32_dpp v76, v74 quad_perm:[2,3,0,1] row_mask:0xf bank_mask:0xf
	v_mov_b32_dpp v77, v75 quad_perm:[2,3,0,1] row_mask:0xf bank_mask:0xf
	s_and_saveexec_b64 s[8:9], s[2:3]
	s_xor_b64 s[8:9], exec, s[8:9]
	s_cbranch_execz .LBB0_1090
	s_and_saveexec_b64 s[22:23], s[4:5]
	s_cbranch_execz .LBB0_1089
	v_pk_mul_f32 v[24:25], v[84:85], v[74:75]
	v_pk_mul_f32 v[72:73], v[20:21], v[72:73]
	s_waitcnt lgkmcnt(0)
	v_pk_fma_f32 v[74:75], v[86:87], v[76:77], v[24:25]
	v_pk_fma_f32 v[72:73], v[18:19], v[22:23], v[72:73]

; __device__ __forceinline__ void phase_qkpost(Frame& F, const Params& p, int j) {
;     ...
;             for (int c = 0; c < 9; ++c) {
;                 f32x4 v = x[c];
;                 float ss = (v.x * v.x + v.y * v.y) + (v.z * v.z + v.w * v.w);
;                 ss += __shfl_xor(ss, 1); ss += __shfl_xor(ss, 2); ss += __shfl_xor(ss, 4); ss += __shfl_xor(ss, 8);
;                 v = v * (1.0f / sqrtf(ss * (1.0f / 64.0f) + EPS)) * (c < 8 ? qg : kg);
;                 f32x4 pr; pr.x = __shfl_xor(v.x, 2); pr.y = __shfl_xor(v.y, 2); pr.z = __shfl_xor(v.z, 2); pr.w = __shfl_xor(v.w, 2);
;                 if (li < 2) v = v * cs - pr * sn; else if (li < 4) v = v * cs + pr * sn;
.LBB0_1096:
	s_waitcnt vmcnt(13)
	v_and_b32_e32 v25, 0xffff0000, v71
	v_and_b32_e32 v24, 0xffff0000, v70
	v_lshlrev_b32_e32 v23, 16, v71
	v_lshlrev_b32_e32 v22, 16, v70
	v_pk_mul_f32 v[70:71], v[24:25], v[24:25]
	s_nop 0
	v_pk_fma_f32 v[70:71], v[22:23], v[22:23], v[70:71]
	s_nop 0
	v_add_f32_e32 v65, v70, v71
	s_nop 1
	v_mov_b32_dpp v70, v65 quad_perm:[1,0,3,2] row_mask:0xf bank_mask:0xf
	v_mov_b32_e32 v71, v24
	s_waitcnt lgkmcnt(0)
	v_add_f32_e32 v65, v65, v70
	s_nop 1
	v_mov_b32_dpp v70, v65 quad_perm:[2,3,0,1] row_mask:0xf bank_mask:0xf
	s_waitcnt lgkmcnt(0)
	v_add_f32_e32 v65, v65, v70
	s_nop 1
	v_mov_b32_dpp v70, v65 row_half_mirror row_mask:0xf bank_mask:0xf
	s_waitcnt lgkmcnt(0)
	v_add_f32_e32 v65, v65, v70
	s_nop 1
	v_mov_b32_dpp v70, v65 row_mirror row_mask:0xf bank_mask:0xf
	s_waitcnt lgkmcnt(0)
	v_add_f32_e32 v65, v65, v70
	v_fmamk_f32 v65, v65, 0x3c800000, v204
	v_mul_f32_e32 v70, 0x4f800000, v65
	v_cmp_gt_f32_e32 vcc, s33, v65
	s_nop 1
	v_cndmask_b32_e32 v65, v65, v70, vcc
	v_sqrt_f32_e32 v72, v65
	v_mov_b32_e32 v70, v22
	v_add_u32_e32 v22, -1, v72
	v_add_u32_e32 v24, 1, v72
	v_fma_f32 v73, -v22, v72, v65
	v_fma_f32 v74, -v24, v72, v65
	v_cmp_ge_f32_e64 s[8:9], 0, v73
	s_nop 1
	v_cndmask_b32_e64 v22, v72, v22, s[8:9]
	v_cmp_lt_f32_e64 s[8:9], 0, v74
	s_nop 1
	v_cndmask_b32_e64 v22, v22, v24, s[8:9]
	v_mul_f32_e32 v24, 0x37800000, v22
	v_cndmask_b32_e32 v22, v22, v24, vcc
	v_cmp_class_f32_e32 vcc, v65, v205
	v_mov_b32_e32 v24, v23
	s_nop 0
	v_cndmask_b32_e32 v22, v22, v65, vcc
	v_div_scale_f32 v65, s[8:9], v22, v22, 1.0
	v_rcp_f32_e32 v72, v65
	v_div_scale_f32 v23, vcc, 1.0, v22, 1.0
	v_fma_f32 v73, -v65, v72, 1.0
	v_fmac_f32_e32 v72, v73, v72
	v_mul_f32_e32 v73, v23, v72
	v_fma_f32 v74, -v65, v73, v23
	v_fmac_f32_e32 v73, v74, v72
	v_fma_f32 v23, -v65, v73, v23
	v_div_fmas_f32 v23, v23, v72, v73
	v_div_fixup_f32 v22, v23, v22, 1.0
	v_pk_mul_f32 v[70:71], v[22:23], v[70:71] op_sel_hi:[0,1]
	v_pk_mul_f32 v[22:23], v[22:23], v[24:25] op_sel_hi:[0,1]
	v_pk_mul_f32 v[72:73], v[8:9], v[22:23]
	v_pk_mul_f32 v[70:71], v[6:7], v[70:71]
	s_nop 1
	v_mov_b32_dpp v22, v70 quad_perm:[2,3,0,1] row_mask:0xf bank_mask:0xf
	v_mov_b32_dpp v23, v71 quad_perm:[2,3,0,1] row_mask:0xf bank_mask:0xf
	v_mov_b32_dpp v74, v72 quad_perm:[2,3,0,1] row_mask:0xf bank_mask:0xf
	v_mov_b32_dpp v75, v73 quad_perm:[2,3,0,1] row_mask:0xf bank_mask:0xf
	s_and_saveexec_b64 s[8:9], s[2:3]
	s_xor_b64 s[8:9], exec, s[8:9]
	s_cbranch_execz .LBB0_1100
	s_and_saveexec_b64 s[22:23], s[4:5]
	s_cbranch_execz .LBB0_1099
	v_pk_mul_f32 v[24:25], v[84:85], v[72:73]
	v_pk_mul_f32 v[70:71], v[20:21], v[70:71]
	s_waitcnt lgkmcnt(0)
	v_pk_fma_f32 v[72:73], v[86:87], v[74:75], v[24:25]
	v_pk_fma_f32 v[70:71], v[18:19], v[22:23], v[70:71]

; __device__ __forceinline__ void phase_qkpost(Frame& F, const Params& p, int j) {
;     ...
;             for (int c = 0; c < 9; ++c) {
;                 f32x4 v = x[c];
;                 float ss = (v.x * v.x + v.y * v.y) + (v.z * v.z + v.w * v.w);
;                 ss += __shfl_xor(ss, 1); ss += __shfl_xor(ss, 2); ss += __shfl_xor(ss, 4); ss += __shfl_xor(ss, 8);
;                 v = v * (1.0f / sqrtf(ss * (1.0f / 64.0f) + EPS)) * (c < 8 ? qg : kg);
;                 f32x4 pr; pr.x = __shfl_xor(v.x, 2); pr.y = __shfl_xor(v.y, 2); pr.z = __shfl_xor(v.z, 2); pr.w = __shfl_xor(v.w, 2);
;                 if (li < 2) v = v * cs - pr * sn; else if (li < 4) v = v * cs + pr * sn;
.LBB0_1106:
	s_waitcnt vmcnt(12)
	v_and_b32_e32 v25, 0xffff0000, v31
	v_and_b32_e32 v24, 0xffff0000, v30
	v_lshlrev_b32_e32 v23, 16, v31
	v_lshlrev_b32_e32 v22, 16, v30
	v_pk_mul_f32 v[30:31], v[24:25], v[24:25]
	s_nop 0
	v_pk_fma_f32 v[30:31], v[22:23], v[22:23], v[30:31]
	s_nop 0
	v_add_f32_e32 v30, v30, v31
	s_waitcnt lgkmcnt(0)
	s_nop 1
	v_add_f32_dpp v30, v30, v30 quad_perm:[1,0,3,2] row_mask:0xf bank_mask:0xf
	s_nop 1
	v_add_f32_dpp v30, v30, v30 quad_perm:[2,3,0,1] row_mask:0xf bank_mask:0xf
	s_nop 1
	v_add_f32_dpp v30, v30, v30 row_half_mirror row_mask:0xf bank_mask:0xf
	s_nop 1
	v_add_f32_dpp v30, v30, v30 row_mirror row_mask:0xf bank_mask:0xf
	v_fmamk_f32 v30, v30, 0x3c800000, v204
	v_mul_f32_e32 v31, 0x4f800000, v30
	v_cmp_gt_f32_e32 vcc, s33, v30
	s_nop 1
	v_cndmask_b32_e32 v65, v30, v31, vcc
	v_sqrt_f32_e32 v70, v65
	v_mov_b32_e32 v30, v22
	v_mov_b32_e32 v31, v24
	v_add_u32_e32 v22, -1, v70
	v_add_u32_e32 v24, 1, v70
	v_fma_f32 v71, -v22, v70, v65
	v_fma_f32 v72, -v24, v70, v65
	v_cmp_ge_f32_e64 s[8:9], 0, v71
	s_nop 1
	v_cndmask_b32_e64 v22, v70, v22, s[8:9]
	v_cmp_lt_f32_e64 s[8:9], 0, v72
	s_nop 1
	v_cndmask_b32_e64 v22, v22, v24, s[8:9]
	v_mul_f32_e32 v24, 0x37800000, v22
	v_cndmask_b32_e32 v22, v22, v24, vcc
	v_cmp_class_f32_e32 vcc, v65, v205
	v_mov_b32_e32 v24, v23
	s_nop 0
	v_cndmask_b32_e32 v22, v22, v65, vcc
	v_div_scale_f32 v65, s[8:9], v22, v22, 1.0
	v_rcp_f32_e32 v70, v65
	v_div_scale_f32 v23, vcc, 1.0, v22, 1.0
	v_fma_f32 v71, -v65, v70, 1.0
	v_fmac_f32_e32 v70, v71, v70
	v_mul_f32_e32 v71, v23, v70
	v_fma_f32 v72, -v65, v71, v23
	v_fmac_f32_e32 v71, v72, v70
	v_fma_f32 v23, -v65, v71, v23
	v_div_fmas_f32 v23, v23, v70, v71
	v_div_fixup_f32 v22, v23, v22, 1.0
	v_pk_mul_f32 v[30:31], v[22:23], v[30:31] op_sel_hi:[0,1]
	v_pk_mul_f32 v[22:23], v[22:23], v[24:25] op_sel_hi:[0,1]
	v_pk_mul_f32 v[70:71], v[8:9], v[22:23]
	v_pk_mul_f32 v[30:31], v[6:7], v[30:31]
	s_nop 1
	v_mov_b32_dpp v22, v30 quad_perm:[2,3,0,1] row_mask:0xf bank_mask:0xf
	v_mov_b32_dpp v23, v31 quad_perm:[2,3,0,1] row_mask:0xf bank_mask:0xf
	v_mov_b32_dpp v72, v70 quad_perm:[2,3,0,1] row_mask:0xf bank_mask:0xf
	v_mov_b32_dpp v73, v71 quad_perm:[2,3,0,1] row_mask:0xf bank_mask:0xf
	s_and_saveexec_b64 s[8:9], s[2:3]
	s_xor_b64 s[8:9], exec, s[8:9]
	s_cbranch_execz .LBB0_1110
	s_and_saveexec_b64 s[22:23], s[4:5]
	s_cbranch_execz .LBB0_1109
	v_pk_mul_f32 v[24:25], v[84:85], v[70:71]
	v_pk_mul_f32 v[30:31], v[20:21], v[30:31]
	s_waitcnt lgkmcnt(0)
	v_pk_fma_f32 v[70:71], v[86:87], v[72:73], v[24:25]
	v_pk_fma_f32 v[30:31], v[18:19], v[22:23], v[30:31]

; __device__ __forceinline__ void phase_qkpost(Frame& F, const Params& p, int j) {
;     ...
;             for (int c = 0; c < 9; ++c) {
;                 f32x4 v = x[c];
;                 float ss = (v.x * v.x + v.y * v.y) + (v.z * v.z + v.w * v.w);
;                 ss += __shfl_xor(ss, 1); ss += __shfl_xor(ss, 2); ss += __shfl_xor(ss, 4); ss += __shfl_xor(ss, 8);
;                 v = v * (1.0f / sqrtf(ss * (1.0f / 64.0f) + EPS)) * (c < 8 ? qg : kg);
;                 f32x4 pr; pr.x = __shfl_xor(v.x, 2); pr.y = __shfl_xor(v.y, 2); pr.z = __shfl_xor(v.z, 2); pr.w = __shfl_xor(v.w, 2);
;                 if (li < 2) v = v * cs - pr * sn; else if (li < 4) v = v * cs + pr * sn;
.LBB0_1116:
	s_waitcnt vmcnt(11)
	v_and_b32_e32 v25, 0xffff0000, v29
	v_and_b32_e32 v24, 0xffff0000, v28
	v_lshlrev_b32_e32 v23, 16, v29
	v_lshlrev_b32_e32 v22, 16, v28
	v_pk_mul_f32 v[26:27], v[24:25], v[24:25]
	s_nop 0
	v_pk_fma_f32 v[26:27], v[22:23], v[22:23], v[26:27]
	s_nop 0
	v_add_f32_e32 v26, v26, v27
	s_waitcnt lgkmcnt(0)
	s_nop 1
	v_add_f32_dpp v26, v26, v26 quad_perm:[1,0,3,2] row_mask:0xf bank_mask:0xf
	s_nop 1
	v_add_f32_dpp v26, v26, v26 quad_perm:[2,3,0,1] row_mask:0xf bank_mask:0xf
	s_nop 1
	v_add_f32_dpp v26, v26, v26 row_half_mirror row_mask:0xf bank_mask:0xf
	s_nop 1
	v_add_f32_dpp v26, v26, v26 row_mirror row_mask:0xf bank_mask:0xf
	v_fmamk_f32 v26, v26, 0x3c800000, v204
	v_mul_f32_e32 v27, 0x4f800000, v26
	v_cmp_gt_f32_e32 vcc, s33, v26
	s_nop 1
	v_cndmask_b32_e32 v28, v26, v27, vcc
	v_sqrt_f32_e32 v29, v28
	v_mov_b32_e32 v26, v22
	v_mov_b32_e32 v27, v24
	v_add_u32_e32 v22, -1, v29
	v_add_u32_e32 v24, 1, v29
	v_fma_f32 v30, -v22, v29, v28
	v_fma_f32 v31, -v24, v29, v28
	v_cmp_ge_f32_e64 s[8:9], 0, v30
	s_nop 1
	v_cndmask_b32_e64 v22, v29, v22, s[8:9]
	v_cmp_lt_f32_e64 s[8:9], 0, v31
	s_nop 1
	v_cndmask_b32_e64 v22, v22, v24, s[8:9]
	v_mul_f32_e32 v24, 0x37800000, v22
	v_cndmask_b32_e32 v22, v22, v24, vcc
	v_cmp_class_f32_e32 vcc, v28, v205
	v_mov_b32_e32 v24, v23
	s_nop 0
	v_cndmask_b32_e32 v22, v22, v28, vcc
	v_div_scale_f32 v28, s[8:9], v22, v22, 1.0
	v_rcp_f32_e32 v29, v28
	v_div_scale_f32 v23, vcc, 1.0, v22, 1.0
	v_fma_f32 v30, -v28, v29, 1.0
	v_fmac_f32_e32 v29, v30, v29
	v_mul_f32_e32 v30, v23, v29
	v_fma_f32 v31, -v28, v30, v23
	v_fmac_f32_e32 v30, v31, v29
	v_fma_f32 v23, -v28, v30, v23
	v_div_fmas_f32 v23, v23, v29, v30
	v_div_fixup_f32 v22, v23, v22, 1.0
	v_pk_mul_f32 v[28:29], v[22:23], v[26:27] op_sel_hi:[0,1]
	v_pk_mul_f32 v[22:23], v[22:23], v[24:25] op_sel_hi:[0,1]
	v_pk_mul_f32 v[26:27], v[4:5], v[22:23]
	v_pk_mul_f32 v[24:25], v[2:3], v[28:29]
	s_nop 1
	v_mov_b32_dpp v28, v24 quad_perm:[2,3,0,1] row_mask:0xf bank_mask:0xf
	v_mov_b32_dpp v29, v25 quad_perm:[2,3,0,1] row_mask:0xf bank_mask:0xf
	v_mov_b32_dpp v70, v26 quad_perm:[2,3,0,1] row_mask:0xf bank_mask:0xf
	v_mov_b32_dpp v71, v27 quad_perm:[2,3,0,1] row_mask:0xf bank_mask:0xf
	s_and_saveexec_b64 s[8:9], s[2:3]
	s_xor_b64 s[8:9], exec, s[8:9]
	s_cbranch_execz .LBB0_1120
	s_and_saveexec_b64 s[22:23], s[4:5]
	s_cbranch_execz .LBB0_1119
	v_pk_mul_f32 v[22:23], v[84:85], v[26:27]
	v_pk_mul_f32 v[20:21], v[20:21], v[24:25]
	s_waitcnt lgkmcnt(0)
	v_pk_fma_f32 v[26:27], v[86:87], v[70:71], v[22:23]
	v_pk_fma_f32 v[24:25], v[18:19], v[28:29], v[20:21]

; __device__ __forceinline__ void phase_qkpost(Frame& F, const Params& p, int j) {
;     ...
;             const int row = row0 + r, pos = kind ? PASTLEN : pos0 + r;
;             f32x4 x[10];
; #pragma unroll
;             for (int c = 0; c < 10; ++c) x[c] = (f32x4){__uint_as_float(xr[r][c].x << 16), __uint_as_float(xr[r][c].x & 0xffff0000u), __uint_as_float(xr[r][c].y << 16), __uint_as_float(xr[r][c].y & 0xffff0000u)};
;             f32x4 cs, sn;
; #pragma unroll
;             for (int e = 0; e < 4; ++e) { const float ang = (float)pos * inv[e]; const double tr = (double)ang * 0.15915494309189535; const float rv = (float)(tr - __builtin_rint(tr));
;                 cs[e] = __builtin_amdgcn_cosf(rv); sn[e] = __builtin_amdgcn_sinf(rv); }
; #pragma unroll
;             for (int c = 0; c < 9; ++c) {
;                 f32x4 v = x[c];
;                 float ss = (v.x * v.x + v.y * v.y) + (v.z * v.z + v.w * v.w);
;                 ss += __shfl_xor(ss, 1); ss += __shfl_xor(ss, 2); ss += __shfl_xor(ss, 4); ss += __shfl_xor(ss, 8);
;                 v = v * (1.0f / sqrtf(ss * (1.0f / 64.0f) + EPS)) * (c < 8 ? qg : kg);
;                 f32x4 pr; pr.x = __shfl_xor(v.x, 2); pr.y = __shfl_xor(v.y, 2); pr.z = __shfl_xor(v.z, 2); pr.w = __shfl_xor(v.w, 2);
;                 if (li < 2) v = v * cs - pr * sn; else if (li < 4) v = v * cs + pr * sn;
.LBB0_1137:
	s_add_i32 s22, s82, 3
	v_cvt_f32_u32_e32 v22, s22
	v_cndmask_b32_e64 v30, v218, v22, s[12:13]
	v_mul_f32_e32 v22, v39, v30
	v_cvt_f64_f32_e32 v[22:23], v22
	v_mul_f64 v[24:25], v[22:23], s[66:67]
	v_rndne_f64_e32 v[24:25], v[24:25]
	v_fma_f64 v[22:23], v[22:23], s[66:67], -v[24:25]
	v_cvt_f32_f64_e32 v22, v[22:23]
	v_mul_f32_e32 v23, v120, v30
	v_cvt_f64_f32_e32 v[26:27], v23
	s_waitcnt lgkmcnt(2)
	v_mul_f64 v[28:29], v[26:27], s[66:67]
	v_rndne_f64_e32 v[28:29], v[28:29]
	v_fma_f64 v[26:27], v[26:27], s[66:67], -v[28:29]
	v_cvt_f32_f64_e32 v23, v[26:27]
	v_mul_f32_e32 v26, v121, v30
	v_cvt_f64_f32_e32 v[26:27], v26
	v_mul_f64 v[28:29], v[26:27], s[66:67]
	v_rndne_f64_e32 v[28:29], v[28:29]
	v_fma_f64 v[26:27], v[26:27], s[66:67], -v[28:29]
	v_cvt_f32_f64_e32 v26, v[26:27]
	v_cos_f32_e32 v66, v26
	s_waitcnt lgkmcnt(1)
	v_sin_f32_e32 v70, v26
	v_mul_f32_e32 v26, v122, v30
	v_cvt_f64_f32_e32 v[26:27], v26
	v_mul_f64 v[28:29], v[26:27], s[66:67]
	v_rndne_f64_e32 v[28:29], v[28:29]
	v_fma_f64 v[26:27], v[26:27], s[66:67], -v[28:29]
	v_cvt_f32_f64_e32 v26, v[26:27]
	s_waitcnt vmcnt(9)
	v_and_b32_e32 v29, 0xffff0000, v63
	v_and_b32_e32 v28, 0xffff0000, v62
	v_cos_f32_e32 v67, v26
	s_waitcnt lgkmcnt(0)
	v_sin_f32_e32 v71, v26
	v_lshlrev_b32_e32 v27, 16, v63
	v_lshlrev_b32_e32 v26, 16, v62
	v_pk_mul_f32 v[30:31], v[28:29], v[28:29]
	v_cos_f32_e32 v24, v22
	v_pk_fma_f32 v[30:31], v[26:27], v[26:27], v[30:31]
	v_sin_f32_e32 v22, v22
	v_add_f32_e32 v30, v30, v31
	s_nop 1
	v_mov_b32_dpp v31, v30 quad_perm:[1,0,3,2] row_mask:0xf bank_mask:0xf
	v_cos_f32_e32 v25, v23
	v_sin_f32_e32 v23, v23
	s_waitcnt lgkmcnt(0)
	v_add_f32_e32 v30, v30, v31
	s_nop 1
	v_mov_b32_dpp v31, v30 quad_perm:[2,3,0,1] row_mask:0xf bank_mask:0xf
	s_waitcnt lgkmcnt(0)
	v_add_f32_e32 v30, v30, v31
	s_nop 1
	v_mov_b32_dpp v31, v30 row_half_mirror row_mask:0xf bank_mask:0xf
	s_waitcnt lgkmcnt(0)
	v_add_f32_e32 v30, v30, v31
	s_nop 1
	v_mov_b32_dpp v31, v30 row_mirror row_mask:0xf bank_mask:0xf
	s_waitcnt lgkmcnt(0)
	v_add_f32_e32 v30, v30, v31
	v_fmamk_f32 v30, v30, 0x3c800000, v204
	v_cmp_gt_f32_e32 vcc, s33, v30
	v_mul_f32_e32 v31, 0x4f800000, v30
	s_nop 0
	v_cndmask_b32_e32 v30, v30, v31, vcc
	v_sqrt_f32_e32 v31, v30
	s_nop 0
	v_add_u32_e32 v62, -1, v31
	v_fma_f32 v63, -v62, v31, v30
	v_cmp_ge_f32_e64 s[8:9], 0, v63
	v_add_u32_e32 v63, 1, v31
	s_nop 0
	v_cndmask_b32_e64 v62, v31, v62, s[8:9]
	v_fma_f32 v31, -v63, v31, v30
	v_cmp_lt_f32_e64 s[8:9], 0, v31
	s_nop 1
	v_cndmask_b32_e64 v31, v62, v63, s[8:9]
	v_mul_f32_e32 v62, 0x37800000, v31
	v_cndmask_b32_e32 v31, v31, v62, vcc
	v_cmp_class_f32_e32 vcc, v30, v205
	s_nop 1
	v_cndmask_b32_e32 v30, v31, v30, vcc
	v_div_scale_f32 v31, s[8:9], v30, v30, 1.0
	v_rcp_f32_e32 v62, v31
	s_nop 0
	v_fma_f32 v63, -v31, v62, 1.0
	v_fmac_f32_e32 v62, v63, v62
	v_div_scale_f32 v63, vcc, 1.0, v30, 1.0
	v_mul_f32_e32 v65, v63, v62
	v_fma_f32 v72, -v31, v65, v63
	v_fmac_f32_e32 v65, v72, v62
	v_fma_f32 v31, -v31, v65, v63
	v_div_fmas_f32 v31, v31, v62, v65
	v_div_fixup_f32 v30, v31, v30, 1.0
	v_mov_b32_e32 v62, v26
	v_mov_b32_e32 v63, v28
	v_mov_b32_e32 v28, v27
	v_pk_mul_f32 v[72:73], v[30:31], v[62:63] op_sel_hi:[0,1]
	v_pk_mul_f32 v[26:27], v[30:31], v[28:29] op_sel_hi:[0,1]
	v_pk_mul_f32 v[62:63], v[8:9], v[26:27]
	v_pk_mul_f32 v[30:31], v[6:7], v[72:73]
	s_nop 1
	v_mov_b32_dpp v26, v30 quad_perm:[2,3,0,1] row_mask:0xf bank_mask:0xf
	v_mov_b32_dpp v27, v31 quad_perm:[2,3,0,1] row_mask:0xf bank_mask:0xf
	v_mov_b32_dpp v72, v62 quad_perm:[2,3,0,1] row_mask:0xf bank_mask:0xf
	v_mov_b32_dpp v73, v63 quad_perm:[2,3,0,1] row_mask:0xf bank_mask:0xf
	s_and_saveexec_b64 s[8:9], s[2:3]
	s_xor_b64 s[8:9], exec, s[8:9]
	s_cbranch_execz .LBB0_1141
	s_and_saveexec_b64 s[24:25], s[4:5]
	s_cbranch_execz .LBB0_1140
	v_pk_mul_f32 v[28:29], v[66:67], v[62:63]
	v_pk_mul_f32 v[30:31], v[24:25], v[30:31]
	s_waitcnt lgkmcnt(0)
	v_pk_fma_f32 v[62:63], v[70:71], v[72:73], v[28:29]
	v_pk_fma_f32 v[30:31], v[22:23], v[26:27], v[30:31]

; __device__ __forceinline__ void phase_qkpost(Frame& F, const Params& p, int j) {
;     ...
;                 f32x4 v = x[c];
;                 float ss = (v.x * v.x + v.y * v.y) + (v.z * v.z + v.w * v.w);
;                 ss += __shfl_xor(ss, 1); ss += __shfl_xor(ss, 2); ss += __shfl_xor(ss, 4); ss += __shfl_xor(ss, 8);
;                 v = v * (1.0f / sqrtf(ss * (1.0f / 64.0f) + EPS)) * (c < 8 ? qg : kg);
;                 f32x4 pr; pr.x = __shfl_xor(v.x, 2); pr.y = __shfl_xor(v.y, 2); pr.z = __shfl_xor(v.z, 2); pr.w = __shfl_xor(v.w, 2);
;                 if (li < 2) v = v * cs - pr * sn; else if (li < 4) v = v * cs + pr * sn;
.LBB0_1147:
	s_waitcnt vmcnt(8)
	v_and_b32_e32 v29, 0xffff0000, v61
	v_and_b32_e32 v28, 0xffff0000, v60
	v_lshlrev_b32_e32 v27, 16, v61
	v_lshlrev_b32_e32 v26, 16, v60
	v_pk_mul_f32 v[60:61], v[28:29], v[28:29]
	s_nop 0
	v_pk_fma_f32 v[60:61], v[26:27], v[26:27], v[60:61]
	s_nop 0
	v_add_f32_e32 v60, v60, v61
	s_waitcnt lgkmcnt(0)
	s_nop 1
	v_add_f32_dpp v60, v60, v60 quad_perm:[1,0,3,2] row_mask:0xf bank_mask:0xf
	s_nop 1
	v_add_f32_dpp v60, v60, v60 quad_perm:[2,3,0,1] row_mask:0xf bank_mask:0xf
	s_nop 1
	v_add_f32_dpp v60, v60, v60 row_half_mirror row_mask:0xf bank_mask:0xf
	s_nop 1
	v_add_f32_dpp v60, v60, v60 row_mirror row_mask:0xf bank_mask:0xf
	v_fmamk_f32 v60, v60, 0x3c800000, v204
	v_mul_f32_e32 v61, 0x4f800000, v60
	v_cmp_gt_f32_e32 vcc, s33, v60
	s_nop 1
	v_cndmask_b32_e32 v65, v60, v61, vcc
	v_sqrt_f32_e32 v72, v65
	v_mov_b32_e32 v60, v26
	v_mov_b32_e32 v61, v28
	v_add_u32_e32 v26, -1, v72
	v_add_u32_e32 v28, 1, v72
	v_fma_f32 v73, -v26, v72, v65
	v_fma_f32 v74, -v28, v72, v65
	v_cmp_ge_f32_e64 s[8:9], 0, v73
	s_nop 1
	v_cndmask_b32_e64 v26, v72, v26, s[8:9]
	v_cmp_lt_f32_e64 s[8:9], 0, v74
	s_nop 1
	v_cndmask_b32_e64 v26, v26, v28, s[8:9]
	v_mul_f32_e32 v28, 0x37800000, v26
	v_cndmask_b32_e32 v26, v26, v28, vcc
	v_cmp_class_f32_e32 vcc, v65, v205
	v_mov_b32_e32 v28, v27
	s_nop 0
	v_cndmask_b32_e32 v26, v26, v65, vcc
	v_div_scale_f32 v65, s[8:9], v26, v26, 1.0
	v_rcp_f32_e32 v72, v65
	v_div_scale_f32 v27, vcc, 1.0, v26, 1.0
	v_fma_f32 v73, -v65, v72, 1.0
	v_fmac_f32_e32 v72, v73, v72
	v_mul_f32_e32 v73, v27, v72
	v_fma_f32 v74, -v65, v73, v27
	v_fmac_f32_e32 v73, v74, v72
	v_fma_f32 v27, -v65, v73, v27
	v_div_fmas_f32 v27, v27, v72, v73
	v_div_fixup_f32 v26, v27, v26, 1.0
	v_pk_mul_f32 v[60:61], v[26:27], v[60:61] op_sel_hi:[0,1]
	v_pk_mul_f32 v[26:27], v[26:27], v[28:29] op_sel_hi:[0,1]
	v_pk_mul_f32 v[72:73], v[8:9], v[26:27]
	v_pk_mul_f32 v[60:61], v[6:7], v[60:61]
	s_nop 1
	v_mov_b32_dpp v26, v60 quad_perm:[2,3,0,1] row_mask:0xf bank_mask:0xf
	v_mov_b32_dpp v27, v61 quad_perm:[2,3,0,1] row_mask:0xf bank_mask:0xf
	v_mov_b32_dpp v74, v72 quad_perm:[2,3,0,1] row_mask:0xf bank_mask:0xf
	v_mov_b32_dpp v75, v73 quad_perm:[2,3,0,1] row_mask:0xf bank_mask:0xf
	s_and_saveexec_b64 s[8:9], s[2:3]
	s_xor_b64 s[8:9], exec, s[8:9]
	s_cbranch_execz .LBB0_1151
	s_and_saveexec_b64 s[16:17], s[4:5]
	s_cbranch_execz .LBB0_1150
	v_pk_mul_f32 v[28:29], v[66:67], v[72:73]
	v_pk_mul_f32 v[60:61], v[24:25], v[60:61]
	s_waitcnt lgkmcnt(0)
	v_pk_fma_f32 v[72:73], v[70:71], v[74:75], v[28:29]
	v_pk_fma_f32 v[60:61], v[22:23], v[26:27], v[60:61]

; __device__ __forceinline__ void phase_qkpost(Frame& F, const Params& p, int j) {
;     ...
;                 f32x4 v = x[c];
;                 float ss = (v.x * v.x + v.y * v.y) + (v.z * v.z + v.w * v.w);
;                 ss += __shfl_xor(ss, 1); ss += __shfl_xor(ss, 2); ss += __shfl_xor(ss, 4); ss += __shfl_xor(ss, 8);
;                 v = v * (1.0f / sqrtf(ss * (1.0f / 64.0f) + EPS)) * (c < 8 ? qg : kg);
;                 f32x4 pr; pr.x = __shfl_xor(v.x, 2); pr.y = __shfl_xor(v.y, 2); pr.z = __shfl_xor(v.z, 2); pr.w = __shfl_xor(v.w, 2);
;                 if (li < 2) v = v * cs - pr * sn; else if (li < 4) v = v * cs + pr * sn;
.LBB0_1157:
	s_waitcnt vmcnt(7)
	v_and_b32_e32 v29, 0xffff0000, v59
	v_and_b32_e32 v28, 0xffff0000, v58
	v_lshlrev_b32_e32 v27, 16, v59
	v_lshlrev_b32_e32 v26, 16, v58
	v_pk_mul_f32 v[58:59], v[28:29], v[28:29]
	s_nop 0
	v_pk_fma_f32 v[58:59], v[26:27], v[26:27], v[58:59]
	s_nop 0
	v_add_f32_e32 v58, v58, v59
	s_waitcnt lgkmcnt(0)
	s_nop 1
	v_add_f32_dpp v58, v58, v58 quad_perm:[1,0,3,2] row_mask:0xf bank_mask:0xf
	s_nop 1
	v_add_f32_dpp v58, v58, v58 quad_perm:[2,3,0,1] row_mask:0xf bank_mask:0xf
	s_nop 1
	v_add_f32_dpp v58, v58, v58 row_half_mirror row_mask:0xf bank_mask:0xf
	s_nop 1
	v_add_f32_dpp v58, v58, v58 row_mirror row_mask:0xf bank_mask:0xf
	v_fmamk_f32 v58, v58, 0x3c800000, v204
	v_mul_f32_e32 v59, 0x4f800000, v58
	v_cmp_gt_f32_e32 vcc, s33, v58
	s_nop 1
	v_cndmask_b32_e32 v60, v58, v59, vcc
	v_sqrt_f32_e32 v61, v60
	v_mov_b32_e32 v58, v26
	v_mov_b32_e32 v59, v28
	v_add_u32_e32 v26, -1, v61
	v_add_u32_e32 v28, 1, v61
	v_fma_f32 v65, -v26, v61, v60
	v_fma_f32 v72, -v28, v61, v60
	v_cmp_ge_f32_e64 s[8:9], 0, v65
	s_nop 1
	v_cndmask_b32_e64 v26, v61, v26, s[8:9]
	v_cmp_lt_f32_e64 s[8:9], 0, v72
	s_nop 1
	v_cndmask_b32_e64 v26, v26, v28, s[8:9]
	v_mul_f32_e32 v28, 0x37800000, v26
	v_cndmask_b32_e32 v26, v26, v28, vcc
	v_cmp_class_f32_e32 vcc, v60, v205
	v_mov_b32_e32 v28, v27
	s_nop 0
	v_cndmask_b32_e32 v26, v26, v60, vcc
	v_div_scale_f32 v60, s[8:9], v26, v26, 1.0
	v_rcp_f32_e32 v61, v60
	v_div_scale_f32 v27, vcc, 1.0, v26, 1.0
	v_fma_f32 v65, -v60, v61, 1.0
	v_fmac_f32_e32 v61, v65, v61
	v_mul_f32_e32 v65, v27, v61
	v_fma_f32 v72, -v60, v65, v27
	v_fmac_f32_e32 v65, v72, v61
	v_fma_f32 v27, -v60, v65, v27
	v_div_fmas_f32 v27, v27, v61, v65
	v_div_fixup_f32 v26, v27, v26, 1.0
	v_pk_mul_f32 v[58:59], v[26:27], v[58:59] op_sel_hi:[0,1]
	v_pk_mul_f32 v[26:27], v[26:27], v[28:29] op_sel_hi:[0,1]
	v_pk_mul_f32 v[60:61], v[8:9], v[26:27]
	v_pk_mul_f32 v[58:59], v[6:7], v[58:59]
	s_nop 1
	v_mov_b32_dpp v26, v58 quad_perm:[2,3,0,1] row_mask:0xf bank_mask:0xf
	v_mov_b32_dpp v27, v59 quad_perm:[2,3,0,1] row_mask:0xf bank_mask:0xf
	v_mov_b32_dpp v72, v60 quad_perm:[2,3,0,1] row_mask:0xf bank_mask:0xf
	v_mov_b32_dpp v73, v61 quad_perm:[2,3,0,1] row_mask:0xf bank_mask:0xf
	s_and_saveexec_b64 s[8:9], s[2:3]
	s_xor_b64 s[8:9], exec, s[8:9]
	s_cbranch_execz .LBB0_1161
	s_and_saveexec_b64 s[16:17], s[4:5]
	s_cbranch_execz .LBB0_1160
	v_pk_mul_f32 v[28:29], v[66:67], v[60:61]
	v_pk_mul_f32 v[58:59], v[24:25], v[58:59]
	s_waitcnt lgkmcnt(0)
	v_pk_fma_f32 v[60:61], v[70:71], v[72:73], v[28:29]
	v_pk_fma_f32 v[58:59], v[22:23], v[26:27], v[58:59]

; __device__ __forceinline__ void phase_qkpost(Frame& F, const Params& p, int j) {
;     ...
;                 f32x4 v = x[c];
;                 float ss = (v.x * v.x + v.y * v.y) + (v.z * v.z + v.w * v.w);
;                 ss += __shfl_xor(ss, 1); ss += __shfl_xor(ss, 2); ss += __shfl_xor(ss, 4); ss += __shfl_xor(ss, 8);
;                 v = v * (1.0f / sqrtf(ss * (1.0f / 64.0f) + EPS)) * (c < 8 ? qg : kg);
;                 f32x4 pr; pr.x = __shfl_xor(v.x, 2); pr.y = __shfl_xor(v.y, 2); pr.z = __shfl_xor(v.z, 2); pr.w = __shfl_xor(v.w, 2);
;                 if (li < 2) v = v * cs - pr * sn; else if (li < 4) v = v * cs + pr * sn;
.LBB0_1167:
	s_waitcnt vmcnt(6)
	v_and_b32_e32 v29, 0xffff0000, v57
	v_and_b32_e32 v28, 0xffff0000, v56
	v_lshlrev_b32_e32 v27, 16, v57
	v_lshlrev_b32_e32 v26, 16, v56
	v_pk_mul_f32 v[56:57], v[28:29], v[28:29]
	s_nop 0
	v_pk_fma_f32 v[56:57], v[26:27], v[26:27], v[56:57]
	s_nop 0
	v_add_f32_e32 v56, v56, v57
	s_waitcnt lgkmcnt(0)
	s_nop 1
	v_add_f32_dpp v56, v56, v56 quad_perm:[1,0,3,2] row_mask:0xf bank_mask:0xf
	s_nop 1
	v_add_f32_dpp v56, v56, v56 quad_perm:[2,3,0,1] row_mask:0xf bank_mask:0xf
	s_nop 1
	v_add_f32_dpp v56, v56, v56 row_half_mirror row_mask:0xf bank_mask:0xf
	s_nop 1
	v_add_f32_dpp v56, v56, v56 row_mirror row_mask:0xf bank_mask:0xf
	v_fmamk_f32 v56, v56, 0x3c800000, v204
	v_mul_f32_e32 v57, 0x4f800000, v56
	v_cmp_gt_f32_e32 vcc, s33, v56
	s_nop 1
	v_cndmask_b32_e32 v58, v56, v57, vcc
	v_sqrt_f32_e32 v59, v58
	v_mov_b32_e32 v56, v26
	v_mov_b32_e32 v57, v28
	v_add_u32_e32 v26, -1, v59
	v_add_u32_e32 v28, 1, v59
	v_fma_f32 v60, -v26, v59, v58
	v_fma_f32 v61, -v28, v59, v58
	v_cmp_ge_f32_e64 s[8:9], 0, v60
	s_nop 1
	v_cndmask_b32_e64 v26, v59, v26, s[8:9]
	v_cmp_lt_f32_e64 s[8:9], 0, v61
	s_nop 1
	v_cndmask_b32_e64 v26, v26, v28, s[8:9]
	v_mul_f32_e32 v28, 0x37800000, v26
	v_cndmask_b32_e32 v26, v26, v28, vcc
	v_cmp_class_f32_e32 vcc, v58, v205
	v_mov_b32_e32 v28, v27
	s_nop 0
	v_cndmask_b32_e32 v26, v26, v58, vcc
	v_div_scale_f32 v58, s[8:9], v26, v26, 1.0
	v_rcp_f32_e32 v59, v58
	v_div_scale_f32 v27, vcc, 1.0, v26, 1.0
	v_fma_f32 v60, -v58, v59, 1.0
	v_fmac_f32_e32 v59, v60, v59
	v_mul_f32_e32 v60, v27, v59
	v_fma_f32 v61, -v58, v60, v27
	v_fmac_f32_e32 v60, v61, v59
	v_fma_f32 v27, -v58, v60, v27
	v_div_fmas_f32 v27, v27, v59, v60
	v_div_fixup_f32 v26, v27, v26, 1.0
	v_pk_mul_f32 v[56:57], v[26:27], v[56:57] op_sel_hi:[0,1]
	v_pk_mul_f32 v[26:27], v[26:27], v[28:29] op_sel_hi:[0,1]
	v_pk_mul_f32 v[58:59], v[8:9], v[26:27]
	v_pk_mul_f32 v[56:57], v[6:7], v[56:57]
	s_nop 1
	v_mov_b32_dpp v26, v56 quad_perm:[2,3,0,1] row_mask:0xf bank_mask:0xf
	v_mov_b32_dpp v27, v57 quad_perm:[2,3,0,1] row_mask:0xf bank_mask:0xf
	v_mov_b32_dpp v60, v58 quad_perm:[2,3,0,1] row_mask:0xf bank_mask:0xf
	v_mov_b32_dpp v61, v59 quad_perm:[2,3,0,1] row_mask:0xf bank_mask:0xf
	s_and_saveexec_b64 s[8:9], s[2:3]
	s_xor_b64 s[8:9], exec, s[8:9]
	s_cbranch_execz .LBB0_1171
	s_and_saveexec_b64 s[16:17], s[4:5]
	s_cbranch_execz .LBB0_1170
	v_pk_mul_f32 v[28:29], v[66:67], v[58:59]
	v_pk_mul_f32 v[56:57], v[24:25], v[56:57]
	s_waitcnt lgkmcnt(0)
	v_pk_fma_f32 v[58:59], v[70:71], v[60:61], v[28:29]
	v_pk_fma_f32 v[56:57], v[22:23], v[26:27], v[56:57]

; __device__ __forceinline__ void phase_qkpost(Frame& F, const Params& p, int j) {
;     ...
;                 f32x4 v = x[c];
;                 float ss = (v.x * v.x + v.y * v.y) + (v.z * v.z + v.w * v.w);
;                 ss += __shfl_xor(ss, 1); ss += __shfl_xor(ss, 2); ss += __shfl_xor(ss, 4); ss += __shfl_xor(ss, 8);
;                 v = v * (1.0f / sqrtf(ss * (1.0f / 64.0f) + EPS)) * (c < 8 ? qg : kg);
;                 f32x4 pr; pr.x = __shfl_xor(v.x, 2); pr.y = __shfl_xor(v.y, 2); pr.z = __shfl_xor(v.z, 2); pr.w = __shfl_xor(v.w, 2);
;                 if (li < 2) v = v * cs - pr * sn; else if (li < 4) v = v * cs + pr * sn;
.LBB0_1177:
	s_waitcnt vmcnt(5)
	v_and_b32_e32 v29, 0xffff0000, v55
	v_and_b32_e32 v28, 0xffff0000, v54
	v_lshlrev_b32_e32 v27, 16, v55
	v_lshlrev_b32_e32 v26, 16, v54
	v_pk_mul_f32 v[54:55], v[28:29], v[28:29]
	s_nop 0
	v_pk_fma_f32 v[54:55], v[26:27], v[26:27], v[54:55]
	s_nop 0
	v_add_f32_e32 v54, v54, v55
	s_waitcnt lgkmcnt(0)
	s_nop 1
	v_add_f32_dpp v54, v54, v54 quad_perm:[1,0,3,2] row_mask:0xf bank_mask:0xf
	s_nop 1
	v_add_f32_dpp v54, v54, v54 quad_perm:[2,3,0,1] row_mask:0xf bank_mask:0xf
	s_nop 1
	v_add_f32_dpp v54, v54, v54 row_half_mirror row_mask:0xf bank_mask:0xf
	s_nop 1
	v_add_f32_dpp v54, v54, v54 row_mirror row_mask:0xf bank_mask:0xf
	v_fmamk_f32 v54, v54, 0x3c800000, v204
	v_mul_f32_e32 v55, 0x4f800000, v54
	v_cmp_gt_f32_e32 vcc, s33, v54
	s_nop 1
	v_cndmask_b32_e32 v56, v54, v55, vcc
	v_sqrt_f32_e32 v57, v56
	v_mov_b32_e32 v54, v26
	v_mov_b32_e32 v55, v28
	v_add_u32_e32 v26, -1, v57
	v_add_u32_e32 v28, 1, v57
	v_fma_f32 v58, -v26, v57, v56
	v_fma_f32 v59, -v28, v57, v56
	v_cmp_ge_f32_e64 s[8:9], 0, v58
	s_nop 1
	v_cndmask_b32_e64 v26, v57, v26, s[8:9]
	v_cmp_lt_f32_e64 s[8:9], 0, v59
	s_nop 1
	v_cndmask_b32_e64 v26, v26, v28, s[8:9]
	v_mul_f32_e32 v28, 0x37800000, v26
	v_cndmask_b32_e32 v26, v26, v28, vcc
	v_cmp_class_f32_e32 vcc, v56, v205
	v_mov_b32_e32 v28, v27
	s_nop 0
	v_cndmask_b32_e32 v26, v26, v56, vcc
	v_div_scale_f32 v56, s[8:9], v26, v26, 1.0
	v_rcp_f32_e32 v57, v56
	v_div_scale_f32 v27, vcc, 1.0, v26, 1.0
	v_fma_f32 v58, -v56, v57, 1.0
	v_fmac_f32_e32 v57, v58, v57
	v_mul_f32_e32 v58, v27, v57
	v_fma_f32 v59, -v56, v58, v27
	v_fmac_f32_e32 v58, v59, v57
	v_fma_f32 v27, -v56, v58, v27
	v_div_fmas_f32 v27, v27, v57, v58
	v_div_fixup_f32 v26, v27, v26, 1.0
	v_pk_mul_f32 v[54:55], v[26:27], v[54:55] op_sel_hi:[0,1]
	v_pk_mul_f32 v[26:27], v[26:27], v[28:29] op_sel_hi:[0,1]
	v_pk_mul_f32 v[56:57], v[8:9], v[26:27]
	v_pk_mul_f32 v[54:55], v[6:7], v[54:55]
	s_nop 1
	v_mov_b32_dpp v26, v54 quad_perm:[2,3,0,1] row_mask:0xf bank_mask:0xf
	v_mov_b32_dpp v27, v55 quad_perm:[2,3,0,1] row_mask:0xf bank_mask:0xf
	v_mov_b32_dpp v58, v56 quad_perm:[2,3,0,1] row_mask:0xf bank_mask:0xf
	v_mov_b32_dpp v59, v57 quad_perm:[2,3,0,1] row_mask:0xf bank_mask:0xf
	s_and_saveexec_b64 s[8:9], s[2:3]
	s_xor_b64 s[8:9], exec, s[8:9]
	s_cbranch_execz .LBB0_1181
	s_and_saveexec_b64 s[16:17], s[4:5]
	s_cbranch_execz .LBB0_1180
	v_pk_mul_f32 v[28:29], v[66:67], v[56:57]
	v_pk_mul_f32 v[54:55], v[24:25], v[54:55]
	s_waitcnt lgkmcnt(0)
	v_pk_fma_f32 v[56:57], v[70:71], v[58:59], v[28:29]
	v_pk_fma_f32 v[54:55], v[22:23], v[26:27], v[54:55]

; __device__ __forceinline__ void phase_qkpost(Frame& F, const Params& p, int j) {
;     ...
;                 f32x4 v = x[c];
;                 float ss = (v.x * v.x + v.y * v.y) + (v.z * v.z + v.w * v.w);
;                 ss += __shfl_xor(ss, 1); ss += __shfl_xor(ss, 2); ss += __shfl_xor(ss, 4); ss += __shfl_xor(ss, 8);
;                 v = v * (1.0f / sqrtf(ss * (1.0f / 64.0f) + EPS)) * (c < 8 ? qg : kg);
;                 f32x4 pr; pr.x = __shfl_xor(v.x, 2); pr.y = __shfl_xor(v.y, 2); pr.z = __shfl_xor(v.z, 2); pr.w = __shfl_xor(v.w, 2);
;                 if (li < 2) v = v * cs - pr * sn; else if (li < 4) v = v * cs + pr * sn;
.LBB0_1187:
	s_waitcnt vmcnt(4)
	v_and_b32_e32 v29, 0xffff0000, v53
	v_and_b32_e32 v28, 0xffff0000, v52
	v_lshlrev_b32_e32 v27, 16, v53
	v_lshlrev_b32_e32 v26, 16, v52
	v_pk_mul_f32 v[52:53], v[28:29], v[28:29]
	s_nop 0
	v_pk_fma_f32 v[52:53], v[26:27], v[26:27], v[52:53]
	s_nop 0
	v_add_f32_e32 v52, v52, v53
	s_waitcnt lgkmcnt(0)
	s_nop 1
	v_add_f32_dpp v52, v52, v52 quad_perm:[1,0,3,2] row_mask:0xf bank_mask:0xf
	s_nop 1
	v_add_f32_dpp v52, v52, v52 quad_perm:[2,3,0,1] row_mask:0xf bank_mask:0xf
	s_nop 1
	v_add_f32_dpp v52, v52, v52 row_half_mirror row_mask:0xf bank_mask:0xf
	s_nop 1
	v_add_f32_dpp v52, v52, v52 row_mirror row_mask:0xf bank_mask:0xf
	v_fmamk_f32 v52, v52, 0x3c800000, v204
	v_mul_f32_e32 v53, 0x4f800000, v52
	v_cmp_gt_f32_e32 vcc, s33, v52
	s_nop 1
	v_cndmask_b32_e32 v54, v52, v53, vcc
	v_sqrt_f32_e32 v55, v54
	v_mov_b32_e32 v52, v26
	v_mov_b32_e32 v53, v28
	v_add_u32_e32 v26, -1, v55
	v_add_u32_e32 v28, 1, v55
	v_fma_f32 v56, -v26, v55, v54
	v_fma_f32 v57, -v28, v55, v54
	v_cmp_ge_f32_e64 s[8:9], 0, v56
	s_nop 1
	v_cndmask_b32_e64 v26, v55, v26, s[8:9]
	v_cmp_lt_f32_e64 s[8:9], 0, v57
	s_nop 1
	v_cndmask_b32_e64 v26, v26, v28, s[8:9]
	v_mul_f32_e32 v28, 0x37800000, v26
	v_cndmask_b32_e32 v26, v26, v28, vcc
	v_cmp_class_f32_e32 vcc, v54, v205
	v_mov_b32_e32 v28, v27
	s_nop 0
	v_cndmask_b32_e32 v26, v26, v54, vcc
	v_div_scale_f32 v54, s[8:9], v26, v26, 1.0
	v_rcp_f32_e32 v55, v54
	v_div_scale_f32 v27, vcc, 1.0, v26, 1.0
	v_fma_f32 v56, -v54, v55, 1.0
	v_fmac_f32_e32 v55, v56, v55
	v_mul_f32_e32 v56, v27, v55
	v_fma_f32 v57, -v54, v56, v27
	v_fmac_f32_e32 v56, v57, v55
	v_fma_f32 v27, -v54, v56, v27
	v_div_fmas_f32 v27, v27, v55, v56
	v_div_fixup_f32 v26, v27, v26, 1.0
	v_pk_mul_f32 v[52:53], v[26:27], v[52:53] op_sel_hi:[0,1]
	v_pk_mul_f32 v[26:27], v[26:27], v[28:29] op_sel_hi:[0,1]
	v_pk_mul_f32 v[54:55], v[8:9], v[26:27]
	v_pk_mul_f32 v[52:53], v[6:7], v[52:53]
	s_nop 1
	v_mov_b32_dpp v26, v52 quad_perm:[2,3,0,1] row_mask:0xf bank_mask:0xf
	v_mov_b32_dpp v27, v53 quad_perm:[2,3,0,1] row_mask:0xf bank_mask:0xf
	v_mov_b32_dpp v56, v54 quad_perm:[2,3,0,1] row_mask:0xf bank_mask:0xf
	v_mov_b32_dpp v57, v55 quad_perm:[2,3,0,1] row_mask:0xf bank_mask:0xf
	s_and_saveexec_b64 s[8:9], s[2:3]
	s_xor_b64 s[8:9], exec, s[8:9]
	s_cbranch_execz .LBB0_1191
	s_and_saveexec_b64 s[16:17], s[4:5]
	s_cbranch_execz .LBB0_1190
	v_pk_mul_f32 v[28:29], v[66:67], v[54:55]
	v_pk_mul_f32 v[52:53], v[24:25], v[52:53]
	s_waitcnt lgkmcnt(0)
	v_pk_fma_f32 v[54:55], v[70:71], v[56:57], v[28:29]
	v_pk_fma_f32 v[52:53], v[22:23], v[26:27], v[52:53]

; __device__ __forceinline__ void phase_qkpost(Frame& F, const Params& p, int j) {
;     ...
;                 f32x4 v = x[c];
;                 float ss = (v.x * v.x + v.y * v.y) + (v.z * v.z + v.w * v.w);
;                 ss += __shfl_xor(ss, 1); ss += __shfl_xor(ss, 2); ss += __shfl_xor(ss, 4); ss += __shfl_xor(ss, 8);
;                 v = v * (1.0f / sqrtf(ss * (1.0f / 64.0f) + EPS)) * (c < 8 ? qg : kg);
;                 f32x4 pr; pr.x = __shfl_xor(v.x, 2); pr.y = __shfl_xor(v.y, 2); pr.z = __shfl_xor(v.z, 2); pr.w = __shfl_xor(v.w, 2);
;                 if (li < 2) v = v * cs - pr * sn; else if (li < 4) v = v * cs + pr * sn;
.LBB0_1197:
	s_waitcnt vmcnt(3)
	v_and_b32_e32 v29, 0xffff0000, v51
	v_and_b32_e32 v28, 0xffff0000, v50
	v_lshlrev_b32_e32 v27, 16, v51
	v_lshlrev_b32_e32 v26, 16, v50
	v_pk_mul_f32 v[50:51], v[28:29], v[28:29]
	s_nop 0
	v_pk_fma_f32 v[50:51], v[26:27], v[26:27], v[50:51]
	s_nop 0
	v_add_f32_e32 v50, v50, v51
	s_waitcnt lgkmcnt(0)
	s_nop 1
	v_add_f32_dpp v50, v50, v50 quad_perm:[1,0,3,2] row_mask:0xf bank_mask:0xf
	s_nop 1
	v_add_f32_dpp v50, v50, v50 quad_perm:[2,3,0,1] row_mask:0xf bank_mask:0xf
	s_nop 1
	v_add_f32_dpp v50, v50, v50 row_half_mirror row_mask:0xf bank_mask:0xf
	s_nop 1
	v_add_f32_dpp v50, v50, v50 row_mirror row_mask:0xf bank_mask:0xf
	v_fmamk_f32 v50, v50, 0x3c800000, v204
	v_mul_f32_e32 v51, 0x4f800000, v50
	v_cmp_gt_f32_e32 vcc, s33, v50
	s_nop 1
	v_cndmask_b32_e32 v52, v50, v51, vcc
	v_sqrt_f32_e32 v53, v52
	v_mov_b32_e32 v50, v26
	v_mov_b32_e32 v51, v28
	v_add_u32_e32 v26, -1, v53
	v_add_u32_e32 v28, 1, v53
	v_fma_f32 v54, -v26, v53, v52
	v_fma_f32 v55, -v28, v53, v52
	v_cmp_ge_f32_e64 s[8:9], 0, v54
	s_nop 1
	v_cndmask_b32_e64 v26, v53, v26, s[8:9]
	v_cmp_lt_f32_e64 s[8:9], 0, v55
	s_nop 1
	v_cndmask_b32_e64 v26, v26, v28, s[8:9]
	v_mul_f32_e32 v28, 0x37800000, v26
	v_cndmask_b32_e32 v26, v26, v28, vcc
	v_cmp_class_f32_e32 vcc, v52, v205
	v_mov_b32_e32 v28, v27
	s_nop 0
	v_cndmask_b32_e32 v26, v26, v52, vcc
	v_div_scale_f32 v52, s[8:9], v26, v26, 1.0
	v_rcp_f32_e32 v53, v52
	v_div_scale_f32 v27, vcc, 1.0, v26, 1.0
	v_fma_f32 v54, -v52, v53, 1.0
	v_fmac_f32_e32 v53, v54, v53
	v_mul_f32_e32 v54, v27, v53
	v_fma_f32 v55, -v52, v54, v27
	v_fmac_f32_e32 v54, v55, v53
	v_fma_f32 v27, -v52, v54, v27
	v_div_fmas_f32 v27, v27, v53, v54
	v_div_fixup_f32 v26, v27, v26, 1.0
	v_pk_mul_f32 v[50:51], v[26:27], v[50:51] op_sel_hi:[0,1]
	v_pk_mul_f32 v[26:27], v[26:27], v[28:29] op_sel_hi:[0,1]
	v_pk_mul_f32 v[52:53], v[8:9], v[26:27]
	v_pk_mul_f32 v[50:51], v[6:7], v[50:51]
	s_nop 1
	v_mov_b32_dpp v26, v50 quad_perm:[2,3,0,1] row_mask:0xf bank_mask:0xf
	v_mov_b32_dpp v27, v51 quad_perm:[2,3,0,1] row_mask:0xf bank_mask:0xf
	v_mov_b32_dpp v54, v52 quad_perm:[2,3,0,1] row_mask:0xf bank_mask:0xf
	v_mov_b32_dpp v55, v53 quad_perm:[2,3,0,1] row_mask:0xf bank_mask:0xf
	s_and_saveexec_b64 s[8:9], s[2:3]
	s_xor_b64 s[8:9], exec, s[8:9]
	s_cbranch_execz .LBB0_1201
	s_and_saveexec_b64 s[16:17], s[4:5]
	s_cbranch_execz .LBB0_1200
	v_pk_mul_f32 v[28:29], v[66:67], v[52:53]
	v_pk_mul_f32 v[50:51], v[24:25], v[50:51]
	s_waitcnt lgkmcnt(0)
	v_pk_fma_f32 v[52:53], v[70:71], v[54:55], v[28:29]
	v_pk_fma_f32 v[50:51], v[22:23], v[26:27], v[50:51]

; __device__ __forceinline__ void phase_qkpost(Frame& F, const Params& p, int j) {
;     ...
;                 f32x4 v = x[c];
;                 float ss = (v.x * v.x + v.y * v.y) + (v.z * v.z + v.w * v.w);
;                 ss += __shfl_xor(ss, 1); ss += __shfl_xor(ss, 2); ss += __shfl_xor(ss, 4); ss += __shfl_xor(ss, 8);
;                 v = v * (1.0f / sqrtf(ss * (1.0f / 64.0f) + EPS)) * (c < 8 ? qg : kg);
;                 f32x4 pr; pr.x = __shfl_xor(v.x, 2); pr.y = __shfl_xor(v.y, 2); pr.z = __shfl_xor(v.z, 2); pr.w = __shfl_xor(v.w, 2);
;                 if (li < 2) v = v * cs - pr * sn; else if (li < 4) v = v * cs + pr * sn;
.LBB0_1207:
	s_waitcnt vmcnt(2)
	v_and_b32_e32 v29, 0xffff0000, v35
	v_and_b32_e32 v28, 0xffff0000, v34
	v_lshlrev_b32_e32 v27, 16, v35
	v_lshlrev_b32_e32 v26, 16, v34
	v_pk_mul_f32 v[34:35], v[28:29], v[28:29]
	s_nop 0
	v_pk_fma_f32 v[34:35], v[26:27], v[26:27], v[34:35]
	s_nop 0
	v_add_f32_e32 v34, v34, v35
	s_waitcnt lgkmcnt(0)
	s_nop 1
	v_add_f32_dpp v34, v34, v34 quad_perm:[1,0,3,2] row_mask:0xf bank_mask:0xf
	s_nop 1
	v_add_f32_dpp v34, v34, v34 quad_perm:[2,3,0,1] row_mask:0xf bank_mask:0xf
	s_nop 1
	v_add_f32_dpp v34, v34, v34 row_half_mirror row_mask:0xf bank_mask:0xf
	s_nop 1
	v_add_f32_dpp v34, v34, v34 row_mirror row_mask:0xf bank_mask:0xf
	v_fmamk_f32 v34, v34, 0x3c800000, v204
	v_mul_f32_e32 v35, 0x4f800000, v34
	v_cmp_gt_f32_e32 vcc, s33, v34
	s_nop 1
	v_cndmask_b32_e32 v50, v34, v35, vcc
	v_sqrt_f32_e32 v51, v50
	v_mov_b32_e32 v34, v26
	v_mov_b32_e32 v35, v28
	v_add_u32_e32 v26, -1, v51
	v_add_u32_e32 v28, 1, v51
	v_fma_f32 v52, -v26, v51, v50
	v_fma_f32 v53, -v28, v51, v50
	v_cmp_ge_f32_e64 s[8:9], 0, v52
	s_nop 1
	v_cndmask_b32_e64 v26, v51, v26, s[8:9]
	v_cmp_lt_f32_e64 s[8:9], 0, v53
	s_nop 1
	v_cndmask_b32_e64 v26, v26, v28, s[8:9]
	v_mul_f32_e32 v28, 0x37800000, v26
	v_cndmask_b32_e32 v26, v26, v28, vcc
	v_cmp_class_f32_e32 vcc, v50, v205
	v_mov_b32_e32 v28, v27
	s_nop 0
	v_cndmask_b32_e32 v26, v26, v50, vcc
	v_div_scale_f32 v50, s[8:9], v26, v26, 1.0
	v_rcp_f32_e32 v51, v50
	v_div_scale_f32 v27, vcc, 1.0, v26, 1.0
	v_fma_f32 v52, -v50, v51, 1.0
	v_fmac_f32_e32 v51, v52, v51
	v_mul_f32_e32 v52, v27, v51
	v_fma_f32 v53, -v50, v52, v27
	v_fmac_f32_e32 v52, v53, v51
	v_fma_f32 v27, -v50, v52, v27
	v_div_fmas_f32 v27, v27, v51, v52
	v_div_fixup_f32 v26, v27, v26, 1.0
	v_pk_mul_f32 v[34:35], v[26:27], v[34:35] op_sel_hi:[0,1]
	v_pk_mul_f32 v[26:27], v[26:27], v[28:29] op_sel_hi:[0,1]
	v_pk_mul_f32 v[50:51], v[8:9], v[26:27]
	v_pk_mul_f32 v[34:35], v[6:7], v[34:35]
	s_nop 1
	v_mov_b32_dpp v26, v34 quad_perm:[2,3,0,1] row_mask:0xf bank_mask:0xf
	v_mov_b32_dpp v27, v35 quad_perm:[2,3,0,1] row_mask:0xf bank_mask:0xf
	v_mov_b32_dpp v52, v50 quad_perm:[2,3,0,1] row_mask:0xf bank_mask:0xf
	v_mov_b32_dpp v53, v51 quad_perm:[2,3,0,1] row_mask:0xf bank_mask:0xf
	s_and_saveexec_b64 s[8:9], s[2:3]
	s_xor_b64 s[8:9], exec, s[8:9]
	s_cbranch_execz .LBB0_1211
	s_and_saveexec_b64 s[16:17], s[4:5]
	s_cbranch_execz .LBB0_1210
	v_pk_mul_f32 v[28:29], v[66:67], v[50:51]
	v_pk_mul_f32 v[34:35], v[24:25], v[34:35]
	s_waitcnt lgkmcnt(0)
	v_pk_fma_f32 v[50:51], v[70:71], v[52:53], v[28:29]
	v_pk_fma_f32 v[34:35], v[22:23], v[26:27], v[34:35]

; __device__ __forceinline__ unsigned cvt_pk_bf16(float lo, float hi) { unsigned r; asm volatile("v_cvt_pk_bf16_f32 %0, %1, %2" : "=v"(r) : "v"(lo), "v"(hi)); return r; }
; __device__ __forceinline__ void phase_qkpost(Frame& F, const Params& p, int j) {
;     ...
;                 f32x4 v = x[c];
;                 float ss = (v.x * v.x + v.y * v.y) + (v.z * v.z + v.w * v.w);
;                 ss += __shfl_xor(ss, 1); ss += __shfl_xor(ss, 2); ss += __shfl_xor(ss, 4); ss += __shfl_xor(ss, 8);
;                 v = v * (1.0f / sqrtf(ss * (1.0f / 64.0f) + EPS)) * (c < 8 ? qg : kg);
;                 f32x4 pr; pr.x = __shfl_xor(v.x, 2); pr.y = __shfl_xor(v.y, 2); pr.z = __shfl_xor(v.z, 2); pr.w = __shfl_xor(v.w, 2);
;                 if (li < 2) v = v * cs - pr * sn; else if (li < 4) v = v * cs + pr * sn;
;     ...
;                     if (kind == 0) { u32x2 w; w.x = cvt_pk_bf16(v.x, v.y); w.y = cvt_pk_bf16(v.z, v.w); *((u32x2*)(F.KN + ((size_t)(b * 4 + hq) * LP + pos) * 64) + li) = w;
.LBB0_1217:
	s_waitcnt vmcnt(1)
	v_and_b32_e32 v29, 0xffff0000, v33
	v_and_b32_e32 v28, 0xffff0000, v32
	v_lshlrev_b32_e32 v27, 16, v33
	v_lshlrev_b32_e32 v26, 16, v32
	v_pk_mul_f32 v[30:31], v[28:29], v[28:29]
	s_nop 0
	v_pk_fma_f32 v[30:31], v[26:27], v[26:27], v[30:31]
	s_nop 0
	v_add_f32_e32 v30, v30, v31
	s_waitcnt lgkmcnt(0)
	s_nop 1
	v_add_f32_dpp v30, v30, v30 quad_perm:[1,0,3,2] row_mask:0xf bank_mask:0xf
	s_nop 1
	v_add_f32_dpp v30, v30, v30 quad_perm:[2,3,0,1] row_mask:0xf bank_mask:0xf
	s_nop 1
	v_add_f32_dpp v30, v30, v30 row_half_mirror row_mask:0xf bank_mask:0xf
	s_nop 1
	v_add_f32_dpp v30, v30, v30 row_mirror row_mask:0xf bank_mask:0xf
	v_fmamk_f32 v30, v30, 0x3c800000, v204
	v_mul_f32_e32 v31, 0x4f800000, v30
	v_cmp_gt_f32_e32 vcc, s33, v30
	s_nop 1
	v_cndmask_b32_e32 v32, v30, v31, vcc
	v_sqrt_f32_e32 v33, v32
	v_mov_b32_e32 v30, v26
	v_mov_b32_e32 v31, v28
	v_add_u32_e32 v26, -1, v33
	v_add_u32_e32 v28, 1, v33
	v_fma_f32 v34, -v26, v33, v32
	v_fma_f32 v35, -v28, v33, v32
	v_cmp_ge_f32_e64 s[8:9], 0, v34
	s_nop 1
	v_cndmask_b32_e64 v26, v33, v26, s[8:9]
	v_cmp_lt_f32_e64 s[8:9], 0, v35
	s_nop 1
	v_cndmask_b32_e64 v26, v26, v28, s[8:9]
	v_mul_f32_e32 v28, 0x37800000, v26
	v_cndmask_b32_e32 v26, v26, v28, vcc
	v_cmp_class_f32_e32 vcc, v32, v205
	v_mov_b32_e32 v28, v27
	s_nop 0
	v_cndmask_b32_e32 v26, v26, v32, vcc
	v_div_scale_f32 v32, s[8:9], v26, v26, 1.0
	v_rcp_f32_e32 v33, v32
	v_div_scale_f32 v27, vcc, 1.0, v26, 1.0
	v_fma_f32 v34, -v32, v33, 1.0
	v_fmac_f32_e32 v33, v34, v33
	v_mul_f32_e32 v34, v27, v33
	v_fma_f32 v35, -v32, v34, v27
	v_fmac_f32_e32 v34, v35, v33
	v_fma_f32 v27, -v32, v34, v27
	v_div_fmas_f32 v27, v27, v33, v34
	v_div_fixup_f32 v26, v27, v26, 1.0
	v_pk_mul_f32 v[32:33], v[26:27], v[30:31] op_sel_hi:[0,1]
	v_pk_mul_f32 v[26:27], v[26:27], v[28:29] op_sel_hi:[0,1]
	v_pk_mul_f32 v[30:31], v[4:5], v[26:27]
	v_pk_mul_f32 v[28:29], v[2:3], v[32:33]
	s_nop 1
	v_mov_b32_dpp v32, v28 quad_perm:[2,3,0,1] row_mask:0xf bank_mask:0xf
	v_mov_b32_dpp v33, v29 quad_perm:[2,3,0,1] row_mask:0xf bank_mask:0xf
	v_mov_b32_dpp v50, v30 quad_perm:[2,3,0,1] row_mask:0xf bank_mask:0xf
	v_mov_b32_dpp v51, v31 quad_perm:[2,3,0,1] row_mask:0xf bank_mask:0xf
	s_and_saveexec_b64 s[8:9], s[2:3]
	s_xor_b64 s[8:9], exec, s[8:9]
	s_cbranch_execz .LBB0_1221
	s_and_saveexec_b64 s[14:15], s[4:5]
	s_cbranch_execz .LBB0_1220
	v_pk_mul_f32 v[26:27], v[66:67], v[30:31]
	v_pk_mul_f32 v[24:25], v[24:25], v[28:29]
	s_waitcnt lgkmcnt(0)
	v_pk_fma_f32 v[30:31], v[70:71], v[50:51], v[26:27]
	v_pk_fma_f32 v[28:29], v[22:23], v[32:33], v[24:25]
